# v9 + slot-handoff trimming in all 17 GEMM K-loops: s_setprio 1 hoisted above the pre-MMA barrier (redundant lgkmcnt wait dropped), mid-segment prio flips removed, s_barrier issued before s_setprio 0 a
# speedup vs baseline: 1.0098x; 1.0098x over previous
.LBB0_402:
	ds_read_b128 v[130:133], v167
	ds_read_b128 v[134:137], v167 offset:1024
	ds_read_b128 v[138:141], v167 offset:2048
	ds_read_b128 v[178:181], v167 offset:3072
	ds_read_b128 v[182:185], v168
	ds_read_b128 v[188:191], v168 offset:1024
	ds_read_b128 v[192:195], v168 offset:2048
	ds_read_b128 v[196:199], v168 offset:3072
	s_add_u32 s41, s60, 0xfff00080
	s_addc_u32 s62, s61, -1
	s_cmp_eq_u32 s39, 60
	s_cselect_b32 s65, s43, s62
	s_cselect_b32 s64, s42, s41
	s_cselect_b32 s63, s45, s10
	s_cselect_b32 s62, s44, s9
	s_add_i32 m0, s47, 0xc000
	ds_read_b128 v[200:203], v169
	ds_read_b128 v[204:207], v169 offset:1024
	ds_read_b128 v[208:211], v169 offset:2048
	ds_read_b128 v[212:215], v169 offset:3072
	ds_read_b128 v[216:219], v169 offset:4096
	ds_read_b128 v[220:223], v169 offset:5120
	ds_read_b128 v[224:227], v169 offset:6144
	ds_read_b128 v[228:231], v169 offset:7168
	global_load_lds_dwordx4 v158, s[60:61]
	s_add_i32 m0, s47, 0xe000
	s_nop 0
	global_load_lds_dwordx4 v156, s[60:61]
	s_waitcnt vmcnt(8)
	s_waitcnt lgkmcnt(0)
	s_setprio 1
	s_barrier
	v_mfma_f32_16x16x32_bf16 v[126:129], v[130:133], v[200:203], v[126:129]
	v_mfma_f32_16x16x32_bf16 v[122:125], v[138:141], v[200:203], v[122:125]
	v_mfma_f32_16x16x32_bf16 v[110:113], v[130:133], v[208:211], v[110:113]
	v_mfma_f32_16x16x32_bf16 v[106:109], v[138:141], v[208:211], v[106:109]
	v_mfma_f32_16x16x32_bf16 v[94:97], v[130:133], v[216:219], v[94:97]
	v_mfma_f32_16x16x32_bf16 v[90:93], v[138:141], v[216:219], v[90:93]
	v_mfma_f32_16x16x32_bf16 v[78:81], v[130:133], v[224:227], v[78:81]
	v_mfma_f32_16x16x32_bf16 v[74:77], v[138:141], v[224:227], v[74:77]
	v_mfma_f32_16x16x32_bf16 v[126:129], v[134:137], v[204:207], v[126:129]
	v_mfma_f32_16x16x32_bf16 v[122:125], v[178:181], v[204:207], v[122:125]
	v_mfma_f32_16x16x32_bf16 v[110:113], v[134:137], v[212:215], v[110:113]
	v_mfma_f32_16x16x32_bf16 v[106:109], v[178:181], v[212:215], v[106:109]
	v_mfma_f32_16x16x32_bf16 v[94:97], v[134:137], v[220:223], v[94:97]
	v_mfma_f32_16x16x32_bf16 v[90:93], v[178:181], v[220:223], v[90:93]
	v_mfma_f32_16x16x32_bf16 v[78:81], v[134:137], v[228:231], v[78:81]
	v_mfma_f32_16x16x32_bf16 v[74:77], v[178:181], v[228:231], v[74:77]
	v_mfma_f32_16x16x32_bf16 v[118:121], v[182:185], v[200:203], v[118:121]
	v_mfma_f32_16x16x32_bf16 v[114:117], v[192:195], v[200:203], v[114:117]
	v_mfma_f32_16x16x32_bf16 v[102:105], v[182:185], v[208:211], v[102:105]
	v_mfma_f32_16x16x32_bf16 v[98:101], v[192:195], v[208:211], v[98:101]
	v_mfma_f32_16x16x32_bf16 v[86:89], v[182:185], v[216:219], v[86:89]
	v_mfma_f32_16x16x32_bf16 v[82:85], v[192:195], v[216:219], v[82:85]
	v_mfma_f32_16x16x32_bf16 v[70:73], v[182:185], v[224:227], v[70:73]
	v_mfma_f32_16x16x32_bf16 v[66:69], v[192:195], v[224:227], v[66:69]
	v_mfma_f32_16x16x32_bf16 v[118:121], v[188:191], v[204:207], v[118:121]
	v_mfma_f32_16x16x32_bf16 v[114:117], v[196:199], v[204:207], v[114:117]
	v_mfma_f32_16x16x32_bf16 v[102:105], v[188:191], v[212:215], v[102:105]
	v_mfma_f32_16x16x32_bf16 v[98:101], v[196:199], v[212:215], v[98:101]
	v_mfma_f32_16x16x32_bf16 v[86:89], v[188:191], v[220:223], v[86:89]
	v_mfma_f32_16x16x32_bf16 v[82:85], v[196:199], v[220:223], v[82:85]
	v_mfma_f32_16x16x32_bf16 v[70:73], v[188:191], v[228:231], v[70:73]
	v_mfma_f32_16x16x32_bf16 v[66:69], v[196:199], v[228:231], v[66:69]
	s_barrier
	s_setprio 0
	s_add_i32 s41, s83, s70
	v_lshl_add_u64 v[164:165], s[62:63], 0, v[144:145]
	s_mov_b32 m0, s41
	ds_read_b128 v[200:203], v169 offset:16384
	ds_read_b128 v[204:207], v169 offset:17408
	ds_read_b128 v[208:211], v169 offset:18432
	ds_read_b128 v[212:215], v169 offset:19456
	ds_read_b128 v[216:219], v169 offset:20480
	ds_read_b128 v[220:223], v169 offset:21504
	ds_read_b128 v[224:227], v169 offset:22528
	ds_read_b128 v[228:231], v169 offset:23552
	global_load_lds_dwordx4 v[164:165], off
	s_add_i32 m0, s41, 0x2000
	s_add_u32 vcc_lo, s62, 0x100000
	v_lshl_add_u64 v[232:233], s[62:63], 0, v[148:149]
	s_addc_u32 vcc_hi, s63, 0
	s_add_i32 s41, s84, s70
	global_load_lds_dwordx4 v[232:233], off
	s_mov_b32 m0, s41
	v_lshl_add_u64 v[236:237], s[64:65], 0, v[146:147]
	global_load_lds_dwordx4 v144, vcc
	s_add_i32 m0, s41, 0x2000
	s_nop 0
	global_load_lds_dwordx4 v148, vcc
	v_lshl_add_u64 v[234:235], s[64:65], 0, v[142:143]
	s_mov_b32 m0, s47
	s_nop 0
	global_load_lds_dwordx4 v[234:235], off
	s_mov_b32 m0, s71
	s_nop 0
	global_load_lds_dwordx4 v[236:237], off
	s_waitcnt vmcnt(8)
	s_waitcnt lgkmcnt(0)
	s_setprio 1
	s_barrier
	v_mfma_f32_16x16x32_bf16 v[62:65], v[130:133], v[200:203], v[62:65]
	v_mfma_f32_16x16x32_bf16 v[58:61], v[138:141], v[200:203], v[58:61]
	v_mfma_f32_16x16x32_bf16 v[46:49], v[130:133], v[208:211], v[46:49]
	v_mfma_f32_16x16x32_bf16 v[42:45], v[138:141], v[208:211], v[42:45]
	v_mfma_f32_16x16x32_bf16 v[30:33], v[130:133], v[216:219], v[30:33]
	v_mfma_f32_16x16x32_bf16 v[26:29], v[138:141], v[216:219], v[26:29]
	v_mfma_f32_16x16x32_bf16 v[14:17], v[130:133], v[224:227], v[14:17]
	v_mfma_f32_16x16x32_bf16 v[10:13], v[138:141], v[224:227], v[10:13]
	v_mfma_f32_16x16x32_bf16 v[62:65], v[134:137], v[204:207], v[62:65]
	v_mfma_f32_16x16x32_bf16 v[58:61], v[178:181], v[204:207], v[58:61]
	v_mfma_f32_16x16x32_bf16 v[46:49], v[134:137], v[212:215], v[46:49]
	v_mfma_f32_16x16x32_bf16 v[42:45], v[178:181], v[212:215], v[42:45]
	v_mfma_f32_16x16x32_bf16 v[30:33], v[134:137], v[220:223], v[30:33]
	v_mfma_f32_16x16x32_bf16 v[26:29], v[178:181], v[220:223], v[26:29]
	v_mfma_f32_16x16x32_bf16 v[14:17], v[134:137], v[228:231], v[14:17]
	v_mfma_f32_16x16x32_bf16 v[10:13], v[178:181], v[228:231], v[10:13]
	v_mfma_f32_16x16x32_bf16 v[54:57], v[182:185], v[200:203], v[54:57]
	v_mfma_f32_16x16x32_bf16 v[50:53], v[192:195], v[200:203], v[50:53]
	v_mfma_f32_16x16x32_bf16 v[38:41], v[182:185], v[208:211], v[38:41]
	v_mfma_f32_16x16x32_bf16 v[34:37], v[192:195], v[208:211], v[34:37]
	v_mfma_f32_16x16x32_bf16 v[22:25], v[182:185], v[216:219], v[22:25]
	v_mfma_f32_16x16x32_bf16 v[18:21], v[192:195], v[216:219], v[18:21]
	v_mfma_f32_16x16x32_bf16 v[6:9], v[182:185], v[224:227], v[6:9]
	v_mfma_f32_16x16x32_bf16 v[2:5], v[192:195], v[224:227], v[2:5]
	v_mfma_f32_16x16x32_bf16 v[54:57], v[188:191], v[204:207], v[54:57]
	v_mfma_f32_16x16x32_bf16 v[50:53], v[196:199], v[204:207], v[50:53]
	v_mfma_f32_16x16x32_bf16 v[38:41], v[188:191], v[212:215], v[38:41]
	v_mfma_f32_16x16x32_bf16 v[34:37], v[196:199], v[212:215], v[34:37]
	v_mfma_f32_16x16x32_bf16 v[22:25], v[188:191], v[220:223], v[22:25]
	v_mfma_f32_16x16x32_bf16 v[18:21], v[196:199], v[220:223], v[18:21]
	v_mfma_f32_16x16x32_bf16 v[6:9], v[188:191], v[228:231], v[6:9]
	v_mfma_f32_16x16x32_bf16 v[2:5], v[196:199], v[228:231], v[2:5]
	s_barrier
	s_setprio 0
	s_add_i32 s41, 0, 0x18000
	v_add_u32_e32 v150, s41, v153
	s_add_i32 s90, 0, 0x1c000
	ds_read_b128 v[130:133], v150
	ds_read_b128 v[134:137], v150 offset:1024
	ds_read_b128 v[138:141], v150 offset:2048
	ds_read_b128 v[178:181], v150 offset:3072
	v_add_u32_e32 v150, s90, v153
	ds_read_b128 v[182:185], v150
	ds_read_b128 v[188:191], v150 offset:1024
	ds_read_b128 v[192:195], v150 offset:2048
	ds_read_b128 v[196:199], v150 offset:3072
	s_add_u32 s64, s64, 0x100000
	s_addc_u32 s65, s65, 0
	s_mov_b32 m0, s72
	ds_read_b128 v[200:203], v169 offset:32768
	ds_read_b128 v[204:207], v169 offset:33792
	ds_read_b128 v[208:211], v169 offset:34816
	ds_read_b128 v[212:215], v169 offset:35840
	ds_read_b128 v[216:219], v169 offset:36864
	ds_read_b128 v[220:223], v169 offset:37888
	ds_read_b128 v[224:227], v169 offset:38912
	ds_read_b128 v[228:231], v169 offset:39936
	global_load_lds_dwordx4 v142, s[64:65]
	s_mov_b32 m0, s73
	s_nop 0
	global_load_lds_dwordx4 v146, s[64:65]
	s_waitcnt vmcnt(8)
	s_waitcnt lgkmcnt(0)
	s_setprio 1
	s_barrier
	v_mfma_f32_16x16x32_bf16 v[126:129], v[130:133], v[200:203], v[126:129]
	v_mfma_f32_16x16x32_bf16 v[122:125], v[138:141], v[200:203], v[122:125]
	v_mfma_f32_16x16x32_bf16 v[110:113], v[130:133], v[208:211], v[110:113]
	v_mfma_f32_16x16x32_bf16 v[106:109], v[138:141], v[208:211], v[106:109]
	v_mfma_f32_16x16x32_bf16 v[94:97], v[130:133], v[216:219], v[94:97]
	v_mfma_f32_16x16x32_bf16 v[90:93], v[138:141], v[216:219], v[90:93]
	v_mfma_f32_16x16x32_bf16 v[78:81], v[130:133], v[224:227], v[78:81]
	v_mfma_f32_16x16x32_bf16 v[74:77], v[138:141], v[224:227], v[74:77]
	v_mfma_f32_16x16x32_bf16 v[126:129], v[134:137], v[204:207], v[126:129]
	v_mfma_f32_16x16x32_bf16 v[122:125], v[178:181], v[204:207], v[122:125]
	v_mfma_f32_16x16x32_bf16 v[110:113], v[134:137], v[212:215], v[110:113]
	v_mfma_f32_16x16x32_bf16 v[106:109], v[178:181], v[212:215], v[106:109]
	v_mfma_f32_16x16x32_bf16 v[94:97], v[134:137], v[220:223], v[94:97]
	v_mfma_f32_16x16x32_bf16 v[90:93], v[178:181], v[220:223], v[90:93]
	v_mfma_f32_16x16x32_bf16 v[78:81], v[134:137], v[228:231], v[78:81]
	v_mfma_f32_16x16x32_bf16 v[74:77], v[178:181], v[228:231], v[74:77]
	v_mfma_f32_16x16x32_bf16 v[118:121], v[182:185], v[200:203], v[118:121]
	v_mfma_f32_16x16x32_bf16 v[114:117], v[192:195], v[200:203], v[114:117]
	v_mfma_f32_16x16x32_bf16 v[102:105], v[182:185], v[208:211], v[102:105]
	v_mfma_f32_16x16x32_bf16 v[98:101], v[192:195], v[208:211], v[98:101]
	v_mfma_f32_16x16x32_bf16 v[86:89], v[182:185], v[216:219], v[86:89]
	v_mfma_f32_16x16x32_bf16 v[82:85], v[192:195], v[216:219], v[82:85]
	v_mfma_f32_16x16x32_bf16 v[70:73], v[182:185], v[224:227], v[70:73]
	v_mfma_f32_16x16x32_bf16 v[66:69], v[192:195], v[224:227], v[66:69]
	v_mfma_f32_16x16x32_bf16 v[118:121], v[188:191], v[204:207], v[118:121]
	v_mfma_f32_16x16x32_bf16 v[114:117], v[196:199], v[204:207], v[114:117]
	v_mfma_f32_16x16x32_bf16 v[102:105], v[188:191], v[212:215], v[102:105]
	v_mfma_f32_16x16x32_bf16 v[98:101], v[196:199], v[212:215], v[98:101]
	v_mfma_f32_16x16x32_bf16 v[86:89], v[188:191], v[220:223], v[86:89]
	v_mfma_f32_16x16x32_bf16 v[82:85], v[196:199], v[220:223], v[82:85]
	v_mfma_f32_16x16x32_bf16 v[70:73], v[188:191], v[228:231], v[70:73]
	v_mfma_f32_16x16x32_bf16 v[66:69], v[196:199], v[228:231], v[66:69]
	s_barrier
	s_setprio 0
	s_add_i32 s41, s41, s70
	v_lshl_add_u64 v[164:165], v[164:165], 0, s[26:27]
	s_mov_b32 m0, s41
	ds_read_b128 v[200:203], v169 offset:49152
	ds_read_b128 v[204:207], v169 offset:50176
	ds_read_b128 v[208:211], v169 offset:51200
	ds_read_b128 v[212:215], v169 offset:52224
	ds_read_b128 v[216:219], v169 offset:53248
	ds_read_b128 v[220:223], v169 offset:54272
	ds_read_b128 v[224:227], v169 offset:55296
	ds_read_b128 v[228:231], v169 offset:56320
	global_load_lds_dwordx4 v[164:165], off
	s_add_i32 m0, s41, 0x2000
	s_add_u32 s62, s62, 0x100080
	v_lshl_add_u64 v[164:165], v[232:233], 0, s[26:27]
	s_addc_u32 s63, s63, 0
	s_add_i32 s41, s90, s70
	global_load_lds_dwordx4 v[164:165], off
	s_mov_b32 m0, s41
	s_nop 0
	global_load_lds_dwordx4 v144, s[62:63]
	s_add_i32 m0, s41, 0x2000
	s_nop 0
	global_load_lds_dwordx4 v148, s[62:63]
	v_lshl_add_u64 v[164:165], v[234:235], 0, s[26:27]
	s_mov_b32 m0, s77
	s_nop 0
	global_load_lds_dwordx4 v[164:165], off
	v_lshl_add_u64 v[164:165], v[236:237], 0, s[26:27]
	s_mov_b32 m0, s78
	s_nop 0
	global_load_lds_dwordx4 v[164:165], off
	s_waitcnt vmcnt(8)
	s_waitcnt lgkmcnt(0)
	s_setprio 1
	s_barrier
	v_mfma_f32_16x16x32_bf16 v[62:65], v[130:133], v[200:203], v[62:65]
	v_mfma_f32_16x16x32_bf16 v[58:61], v[138:141], v[200:203], v[58:61]
	v_mfma_f32_16x16x32_bf16 v[46:49], v[130:133], v[208:211], v[46:49]
	v_mfma_f32_16x16x32_bf16 v[42:45], v[138:141], v[208:211], v[42:45]
	v_mfma_f32_16x16x32_bf16 v[30:33], v[130:133], v[216:219], v[30:33]
	v_mfma_f32_16x16x32_bf16 v[26:29], v[138:141], v[216:219], v[26:29]
	v_mfma_f32_16x16x32_bf16 v[14:17], v[130:133], v[224:227], v[14:17]
	v_mfma_f32_16x16x32_bf16 v[10:13], v[138:141], v[224:227], v[10:13]
	v_mfma_f32_16x16x32_bf16 v[62:65], v[134:137], v[204:207], v[62:65]
	v_mfma_f32_16x16x32_bf16 v[58:61], v[178:181], v[204:207], v[58:61]
	v_mfma_f32_16x16x32_bf16 v[46:49], v[134:137], v[212:215], v[46:49]
	v_mfma_f32_16x16x32_bf16 v[42:45], v[178:181], v[212:215], v[42:45]
	v_mfma_f32_16x16x32_bf16 v[30:33], v[134:137], v[220:223], v[30:33]
	v_mfma_f32_16x16x32_bf16 v[26:29], v[178:181], v[220:223], v[26:29]
	v_mfma_f32_16x16x32_bf16 v[14:17], v[134:137], v[228:231], v[14:17]
	v_mfma_f32_16x16x32_bf16 v[10:13], v[178:181], v[228:231], v[10:13]
	v_mfma_f32_16x16x32_bf16 v[54:57], v[182:185], v[200:203], v[54:57]
	v_mfma_f32_16x16x32_bf16 v[50:53], v[192:195], v[200:203], v[50:53]
	v_mfma_f32_16x16x32_bf16 v[38:41], v[182:185], v[208:211], v[38:41]
	v_mfma_f32_16x16x32_bf16 v[34:37], v[192:195], v[208:211], v[34:37]
	v_mfma_f32_16x16x32_bf16 v[22:25], v[182:185], v[216:219], v[22:25]
	v_mfma_f32_16x16x32_bf16 v[18:21], v[192:195], v[216:219], v[18:21]
	v_mfma_f32_16x16x32_bf16 v[6:9], v[182:185], v[224:227], v[6:9]
	v_mfma_f32_16x16x32_bf16 v[2:5], v[192:195], v[224:227], v[2:5]
	v_mfma_f32_16x16x32_bf16 v[54:57], v[188:191], v[204:207], v[54:57]
	v_mfma_f32_16x16x32_bf16 v[50:53], v[196:199], v[204:207], v[50:53]
	v_mfma_f32_16x16x32_bf16 v[38:41], v[188:191], v[212:215], v[38:41]
	v_mfma_f32_16x16x32_bf16 v[34:37], v[196:199], v[212:215], v[34:37]
	v_mfma_f32_16x16x32_bf16 v[22:25], v[188:191], v[220:223], v[22:25]
	v_mfma_f32_16x16x32_bf16 v[18:21], v[196:199], v[220:223], v[18:21]
	v_mfma_f32_16x16x32_bf16 v[6:9], v[188:191], v[228:231], v[6:9]
	v_mfma_f32_16x16x32_bf16 v[2:5], v[196:199], v[228:231], v[2:5]
	s_barrier
	s_setprio 0
	s_add_i32 s39, s39, 2
	s_add_u32 s9, s9, 0x100
	s_addc_u32 s10, s10, 0
	s_add_u32 s60, s60, 0x100
	s_addc_u32 s61, s61, 0
	s_cmp_gt_u32 s39, 61
	s_cbranch_scc0 .LBB0_402
	s_and_b64 vcc, exec, s[28:29]
	s_cbranch_vccz .LBB0_405
	s_barrier

.LBB0_697:
	s_waitcnt lgkmcnt(0)
	ds_read_b128 v[2:5], v188
	ds_read_b128 v[6:9], v188 offset:1024
	s_waitcnt vmcnt(0)
	ds_read_b128 v[138:141], v188 offset:2048
	ds_read_b128 v[142:145], v188 offset:3072
	ds_read_b128 v[146:149], v189
	ds_read_b128 v[150:153], v189 offset:1024
	ds_read_b128 v[172:175], v189 offset:2048
	ds_read_b128 v[176:179], v189 offset:3072
	s_add_u32 s38, s36, 0xfff80080
	s_addc_u32 s39, s37, -1
	s_cmp_eq_u32 s72, 28
	s_cselect_b32 s41, s29, s39
	s_cselect_b32 s40, s68, s38
	s_cselect_b32 s39, s27, s71
	s_cselect_b32 s38, s69, s70
	s_add_i32 m0, s9, 0xc000
	ds_read_b128 v[192:195], v190
	ds_read_b128 v[196:199], v190 offset:1024
	ds_read_b128 v[200:203], v190 offset:2048
	ds_read_b128 v[204:207], v190 offset:3072
	ds_read_b128 v[208:211], v190 offset:4096
	ds_read_b128 v[212:215], v190 offset:5120
	ds_read_b128 v[216:219], v190 offset:6144
	ds_read_b128 v[220:223], v190 offset:7168
	global_load_lds_dwordx4 v166, s[36:37]
	s_add_i32 m0, s9, 0xe000
	s_nop 0
	global_load_lds_dwordx4 v164, s[36:37]
	s_waitcnt vmcnt(8)
	s_waitcnt lgkmcnt(0)
	s_setprio 1
	s_barrier
	v_mfma_i32_16x16x64_i8 v[134:137], v[2:5], v[192:195], v[134:137]
	v_mfma_i32_16x16x64_i8 v[130:133], v[138:141], v[192:195], v[130:133]
	v_mfma_i32_16x16x64_i8 v[118:121], v[2:5], v[200:203], v[118:121]
	v_mfma_i32_16x16x64_i8 v[114:117], v[138:141], v[200:203], v[114:117]
	v_mfma_i32_16x16x64_i8 v[102:105], v[2:5], v[208:211], v[102:105]
	v_mfma_i32_16x16x64_i8 v[98:101], v[138:141], v[208:211], v[98:101]
	v_mfma_i32_16x16x64_i8 v[86:89], v[2:5], v[216:219], v[86:89]
	v_mfma_i32_16x16x64_i8 v[82:85], v[138:141], v[216:219], v[82:85]
	v_mfma_i32_16x16x64_i8 v[134:137], v[6:9], v[196:199], v[134:137]
	v_mfma_i32_16x16x64_i8 v[130:133], v[142:145], v[196:199], v[130:133]
	v_mfma_i32_16x16x64_i8 v[118:121], v[6:9], v[204:207], v[118:121]
	v_mfma_i32_16x16x64_i8 v[114:117], v[142:145], v[204:207], v[114:117]
	v_mfma_i32_16x16x64_i8 v[102:105], v[6:9], v[212:215], v[102:105]
	v_mfma_i32_16x16x64_i8 v[98:101], v[142:145], v[212:215], v[98:101]
	v_mfma_i32_16x16x64_i8 v[86:89], v[6:9], v[220:223], v[86:89]
	v_mfma_i32_16x16x64_i8 v[82:85], v[142:145], v[220:223], v[82:85]
	v_mfma_i32_16x16x64_i8 v[126:129], v[146:149], v[192:195], v[126:129]
	v_mfma_i32_16x16x64_i8 v[122:125], v[172:175], v[192:195], v[122:125]
	v_mfma_i32_16x16x64_i8 v[110:113], v[146:149], v[200:203], v[110:113]
	v_mfma_i32_16x16x64_i8 v[106:109], v[172:175], v[200:203], v[106:109]
	v_mfma_i32_16x16x64_i8 v[94:97], v[146:149], v[208:211], v[94:97]
	v_mfma_i32_16x16x64_i8 v[90:93], v[172:175], v[208:211], v[90:93]
	v_mfma_i32_16x16x64_i8 v[78:81], v[146:149], v[216:219], v[78:81]
	v_mfma_i32_16x16x64_i8 v[74:77], v[172:175], v[216:219], v[74:77]
	v_mfma_i32_16x16x64_i8 v[126:129], v[150:153], v[196:199], v[126:129]
	v_mfma_i32_16x16x64_i8 v[122:125], v[176:179], v[196:199], v[122:125]
	v_mfma_i32_16x16x64_i8 v[110:113], v[150:153], v[204:207], v[110:113]
	v_mfma_i32_16x16x64_i8 v[106:109], v[176:179], v[204:207], v[106:109]
	v_mfma_i32_16x16x64_i8 v[94:97], v[150:153], v[212:215], v[94:97]
	v_mfma_i32_16x16x64_i8 v[90:93], v[176:179], v[212:215], v[90:93]
	v_mfma_i32_16x16x64_i8 v[78:81], v[150:153], v[220:223], v[78:81]
	v_mfma_i32_16x16x64_i8 v[74:77], v[176:179], v[220:223], v[74:77]
	s_barrier
	s_setprio 0
	s_add_i32 s73, s65, s44
	v_lshl_add_u64 v[180:181], s[38:39], 0, v[158:159]
	s_mov_b32 m0, s73
	ds_read_b128 v[192:195], v190 offset:16384
	ds_read_b128 v[196:199], v190 offset:17408
	ds_read_b128 v[200:203], v190 offset:18432
	ds_read_b128 v[204:207], v190 offset:19456
	ds_read_b128 v[208:211], v190 offset:20480
	ds_read_b128 v[212:215], v190 offset:21504
	ds_read_b128 v[216:219], v190 offset:22528
	ds_read_b128 v[220:223], v190 offset:23552
	global_load_lds_dwordx4 v[180:181], off
	s_add_i32 m0, s73, 0x2000
	s_add_u32 s76, s38, 0x80000
	v_lshl_add_u64 v[224:225], s[38:39], 0, v[154:155]
	s_addc_u32 s77, s39, 0
	s_add_i32 s73, s66, s44
	global_load_lds_dwordx4 v[224:225], off
	s_mov_b32 m0, s73
	v_lshl_add_u64 v[228:229], s[40:41], 0, v[156:157]
	global_load_lds_dwordx4 v158, s[76:77]
	s_add_i32 m0, s73, 0x2000
	s_nop 0
	global_load_lds_dwordx4 v154, s[76:77]
	v_lshl_add_u64 v[226:227], s[40:41], 0, v[160:161]
	s_mov_b32 m0, s9
	s_nop 0
	global_load_lds_dwordx4 v[226:227], off
	s_mov_b32 m0, s47
	s_nop 0
	global_load_lds_dwordx4 v[228:229], off
	s_waitcnt vmcnt(8)
	s_waitcnt lgkmcnt(0)
	s_setprio 1
	s_barrier
	v_mfma_i32_16x16x64_i8 v[70:73], v[2:5], v[192:195], v[70:73]
	v_mfma_i32_16x16x64_i8 v[66:69], v[138:141], v[192:195], v[66:69]
	v_mfma_i32_16x16x64_i8 v[54:57], v[2:5], v[200:203], v[54:57]
	v_mfma_i32_16x16x64_i8 v[50:53], v[138:141], v[200:203], v[50:53]
	v_mfma_i32_16x16x64_i8 v[38:41], v[2:5], v[208:211], v[38:41]
	v_mfma_i32_16x16x64_i8 v[34:37], v[138:141], v[208:211], v[34:37]
	v_mfma_i32_16x16x64_i8 v[2:5], v[2:5], v[216:219], v[22:25]
	v_mfma_i32_16x16x64_i8 v[70:73], v[6:9], v[196:199], v[70:73]
	v_mfma_i32_16x16x64_i8 v[66:69], v[142:145], v[196:199], v[66:69]
	v_mfma_i32_16x16x64_i8 v[54:57], v[6:9], v[204:207], v[54:57]
	v_mfma_i32_16x16x64_i8 v[50:53], v[142:145], v[204:207], v[50:53]
	v_mfma_i32_16x16x64_i8 v[38:41], v[6:9], v[212:215], v[38:41]
	v_mfma_i32_16x16x64_i8 v[34:37], v[142:145], v[212:215], v[34:37]
	v_mfma_i32_16x16x64_i8 v[2:5], v[6:9], v[220:223], v[2:5]
	v_mfma_i32_16x16x64_i8 v[6:9], v[138:141], v[216:219], v[18:21]
	v_mfma_i32_16x16x64_i8 v[6:9], v[142:145], v[220:223], v[6:9]
	v_mfma_i32_16x16x64_i8 v[18:21], v[146:149], v[192:195], v[62:65]
	v_mfma_i32_16x16x64_i8 v[62:65], v[150:153], v[196:199], v[18:21]
	v_mfma_i32_16x16x64_i8 v[18:21], v[172:175], v[192:195], v[58:61]
	v_mfma_i32_16x16x64_i8 v[58:61], v[176:179], v[196:199], v[18:21]
	v_mfma_i32_16x16x64_i8 v[18:21], v[146:149], v[200:203], v[46:49]
	v_mfma_i32_16x16x64_i8 v[46:49], v[150:153], v[204:207], v[18:21]
	v_mfma_i32_16x16x64_i8 v[18:21], v[172:175], v[200:203], v[42:45]
	v_mfma_i32_16x16x64_i8 v[42:45], v[176:179], v[204:207], v[18:21]
	v_mfma_i32_16x16x64_i8 v[18:21], v[146:149], v[208:211], v[30:33]
	v_mfma_i32_16x16x64_i8 v[30:33], v[150:153], v[212:215], v[18:21]
	v_mfma_i32_16x16x64_i8 v[18:21], v[172:175], v[208:211], v[26:29]
	v_mfma_i32_16x16x64_i8 v[14:17], v[146:149], v[216:219], v[14:17]
	v_mfma_i32_16x16x64_i8 v[10:13], v[172:175], v[216:219], v[10:13]
	v_mfma_i32_16x16x64_i8 v[26:29], v[176:179], v[212:215], v[18:21]
	v_mfma_i32_16x16x64_i8 v[14:17], v[150:153], v[220:223], v[14:17]
	v_mfma_i32_16x16x64_i8 v[10:13], v[176:179], v[220:223], v[10:13]
	s_barrier
	s_setprio 0
	s_add_i32 s73, 0, 0x18000
	s_add_i32 s75, 0, 0x1c000
	v_add_u32_e32 v142, s73, v182
	v_add_u32_e32 v162, s75, v182
	ds_read_b128 v[18:21], v142
	ds_read_b128 v[22:25], v142 offset:1024
	ds_read_b128 v[138:141], v142 offset:2048
	ds_read_b128 v[142:145], v142 offset:3072
	ds_read_b128 v[146:149], v162
	ds_read_b128 v[150:153], v162 offset:1024
	ds_read_b128 v[172:175], v162 offset:2048
	ds_read_b128 v[176:179], v162 offset:3072
	s_add_u32 s40, s40, 0x80000
	s_addc_u32 s41, s41, 0
	s_mov_b32 m0, s49
	ds_read_b128 v[192:195], v190 offset:32768
	ds_read_b128 v[196:199], v190 offset:33792
	ds_read_b128 v[200:203], v190 offset:34816
	ds_read_b128 v[204:207], v190 offset:35840
	ds_read_b128 v[208:211], v190 offset:36864
	ds_read_b128 v[212:215], v190 offset:37888
	ds_read_b128 v[216:219], v190 offset:38912
	ds_read_b128 v[220:223], v190 offset:39936
	global_load_lds_dwordx4 v160, s[40:41]
	s_mov_b32 m0, s60
	s_nop 0
	global_load_lds_dwordx4 v156, s[40:41]
	s_waitcnt vmcnt(8)
	s_waitcnt lgkmcnt(0)
	s_setprio 1
	s_barrier
	v_mfma_i32_16x16x64_i8 v[134:137], v[18:21], v[192:195], v[134:137]
	v_mfma_i32_16x16x64_i8 v[130:133], v[138:141], v[192:195], v[130:133]
	v_mfma_i32_16x16x64_i8 v[118:121], v[18:21], v[200:203], v[118:121]
	v_mfma_i32_16x16x64_i8 v[114:117], v[138:141], v[200:203], v[114:117]
	v_mfma_i32_16x16x64_i8 v[102:105], v[18:21], v[208:211], v[102:105]
	v_mfma_i32_16x16x64_i8 v[98:101], v[138:141], v[208:211], v[98:101]
	v_mfma_i32_16x16x64_i8 v[86:89], v[18:21], v[216:219], v[86:89]
	v_mfma_i32_16x16x64_i8 v[82:85], v[138:141], v[216:219], v[82:85]
	v_mfma_i32_16x16x64_i8 v[134:137], v[22:25], v[196:199], v[134:137]
	v_mfma_i32_16x16x64_i8 v[130:133], v[142:145], v[196:199], v[130:133]
	v_mfma_i32_16x16x64_i8 v[118:121], v[22:25], v[204:207], v[118:121]
	v_mfma_i32_16x16x64_i8 v[114:117], v[142:145], v[204:207], v[114:117]
	v_mfma_i32_16x16x64_i8 v[102:105], v[22:25], v[212:215], v[102:105]
	v_mfma_i32_16x16x64_i8 v[98:101], v[142:145], v[212:215], v[98:101]
	v_mfma_i32_16x16x64_i8 v[86:89], v[22:25], v[220:223], v[86:89]
	v_mfma_i32_16x16x64_i8 v[82:85], v[142:145], v[220:223], v[82:85]
	v_mfma_i32_16x16x64_i8 v[126:129], v[146:149], v[192:195], v[126:129]
	v_mfma_i32_16x16x64_i8 v[122:125], v[172:175], v[192:195], v[122:125]
	v_mfma_i32_16x16x64_i8 v[110:113], v[146:149], v[200:203], v[110:113]
	v_mfma_i32_16x16x64_i8 v[106:109], v[172:175], v[200:203], v[106:109]
	v_mfma_i32_16x16x64_i8 v[94:97], v[146:149], v[208:211], v[94:97]
	v_mfma_i32_16x16x64_i8 v[90:93], v[172:175], v[208:211], v[90:93]
	v_mfma_i32_16x16x64_i8 v[78:81], v[146:149], v[216:219], v[78:81]
	v_mfma_i32_16x16x64_i8 v[74:77], v[172:175], v[216:219], v[74:77]
	v_mfma_i32_16x16x64_i8 v[126:129], v[150:153], v[196:199], v[126:129]
	v_mfma_i32_16x16x64_i8 v[122:125], v[176:179], v[196:199], v[122:125]
	v_mfma_i32_16x16x64_i8 v[110:113], v[150:153], v[204:207], v[110:113]
	v_mfma_i32_16x16x64_i8 v[106:109], v[176:179], v[204:207], v[106:109]
	v_mfma_i32_16x16x64_i8 v[94:97], v[150:153], v[212:215], v[94:97]
	v_mfma_i32_16x16x64_i8 v[90:93], v[176:179], v[212:215], v[90:93]
	v_mfma_i32_16x16x64_i8 v[78:81], v[150:153], v[220:223], v[78:81]
	v_mfma_i32_16x16x64_i8 v[74:77], v[176:179], v[220:223], v[74:77]
	s_barrier
	s_setprio 0
	s_add_i32 s40, s73, s44
	v_lshl_add_u64 v[180:181], v[180:181], 0, s[20:21]
	s_mov_b32 m0, s40
	ds_read_b128 v[192:195], v190 offset:49152
	ds_read_b128 v[196:199], v190 offset:50176
	ds_read_b128 v[200:203], v190 offset:51200
	ds_read_b128 v[204:207], v190 offset:52224
	ds_read_b128 v[208:211], v190 offset:53248
	ds_read_b128 v[212:215], v190 offset:54272
	ds_read_b128 v[216:219], v190 offset:55296
	ds_read_b128 v[220:223], v190 offset:56320
	global_load_lds_dwordx4 v[180:181], off
	s_add_i32 m0, s40, 0x2000
	s_add_u32 s38, s38, 0x80080
	v_lshl_add_u64 v[180:181], v[224:225], 0, s[20:21]
	s_addc_u32 s39, s39, 0
	s_add_i32 s40, s75, s44
	global_load_lds_dwordx4 v[180:181], off
	s_mov_b32 m0, s40
	s_nop 0
	global_load_lds_dwordx4 v158, s[38:39]
	s_add_i32 m0, s40, 0x2000
	s_nop 0
	global_load_lds_dwordx4 v154, s[38:39]
	v_lshl_add_u64 v[180:181], v[226:227], 0, s[20:21]
	s_mov_b32 m0, s62
	s_nop 0
	global_load_lds_dwordx4 v[180:181], off
	v_lshl_add_u64 v[180:181], v[228:229], 0, s[20:21]
	s_mov_b32 m0, s63
	s_nop 0
	global_load_lds_dwordx4 v[180:181], off
	s_waitcnt vmcnt(8)
	s_waitcnt lgkmcnt(0)
	s_setprio 1
	s_barrier
	v_mfma_i32_16x16x64_i8 v[70:73], v[18:21], v[192:195], v[70:73]
	v_mfma_i32_16x16x64_i8 v[54:57], v[18:21], v[200:203], v[54:57]
	v_mfma_i32_16x16x64_i8 v[38:41], v[18:21], v[208:211], v[38:41]
	v_mfma_i32_16x16x64_i8 v[2:5], v[18:21], v[216:219], v[2:5]
	v_mfma_i32_16x16x64_i8 v[70:73], v[22:25], v[196:199], v[70:73]
	v_mfma_i32_16x16x64_i8 v[66:69], v[138:141], v[192:195], v[66:69]
	v_mfma_i32_16x16x64_i8 v[54:57], v[22:25], v[204:207], v[54:57]
	v_mfma_i32_16x16x64_i8 v[50:53], v[138:141], v[200:203], v[50:53]
	v_mfma_i32_16x16x64_i8 v[38:41], v[22:25], v[212:215], v[38:41]
	v_mfma_i32_16x16x64_i8 v[34:37], v[138:141], v[208:211], v[34:37]
	v_mfma_i32_16x16x64_i8 v[22:25], v[22:25], v[220:223], v[2:5]
	v_mfma_i32_16x16x64_i8 v[2:5], v[138:141], v[216:219], v[6:9]
	v_mfma_i32_16x16x64_i8 v[66:69], v[142:145], v[196:199], v[66:69]
	v_mfma_i32_16x16x64_i8 v[50:53], v[142:145], v[204:207], v[50:53]
	v_mfma_i32_16x16x64_i8 v[34:37], v[142:145], v[212:215], v[34:37]
	v_mfma_i32_16x16x64_i8 v[18:21], v[142:145], v[220:223], v[2:5]
	v_mfma_i32_16x16x64_i8 v[2:5], v[146:149], v[192:195], v[62:65]
	v_mfma_i32_16x16x64_i8 v[62:65], v[150:153], v[196:199], v[2:5]
	v_mfma_i32_16x16x64_i8 v[2:5], v[172:175], v[192:195], v[58:61]
	v_mfma_i32_16x16x64_i8 v[58:61], v[176:179], v[196:199], v[2:5]
	v_mfma_i32_16x16x64_i8 v[2:5], v[146:149], v[200:203], v[46:49]
	v_mfma_i32_16x16x64_i8 v[46:49], v[150:153], v[204:207], v[2:5]
	v_mfma_i32_16x16x64_i8 v[2:5], v[172:175], v[200:203], v[42:45]
	v_mfma_i32_16x16x64_i8 v[42:45], v[176:179], v[204:207], v[2:5]
	v_mfma_i32_16x16x64_i8 v[2:5], v[146:149], v[208:211], v[30:33]
	v_mfma_i32_16x16x64_i8 v[30:33], v[150:153], v[212:215], v[2:5]
	v_mfma_i32_16x16x64_i8 v[2:5], v[172:175], v[208:211], v[26:29]
	v_mfma_i32_16x16x64_i8 v[26:29], v[176:179], v[212:215], v[2:5]
	v_mfma_i32_16x16x64_i8 v[2:5], v[146:149], v[216:219], v[14:17]
	v_mfma_i32_16x16x64_i8 v[14:17], v[150:153], v[220:223], v[2:5]
	v_mfma_i32_16x16x64_i8 v[2:5], v[172:175], v[216:219], v[10:13]
	v_mfma_i32_16x16x64_i8 v[10:13], v[176:179], v[220:223], v[2:5]
	s_barrier
	s_setprio 0
	s_add_i32 s72, s72, 2
	s_add_u32 s70, s70, 0x100
	s_addc_u32 s71, s71, 0
	s_add_u32 s36, s36, 0x100
	s_addc_u32 s37, s37, 0
	s_cmp_gt_u32 s72, 29
	s_cbranch_scc0 .LBB0_697
	s_and_b64 vcc, exec, s[22:23]
	s_cbranch_vccz .LBB0_700
	s_barrier

.LBB0_790:
	ds_read_b128 v[164:167], v1
	ds_read_b128 v[168:171], v1 offset:1024
	ds_read_b128 v[172:175], v1 offset:2048
	ds_read_b128 v[176:179], v1 offset:3072
	ds_read_b128 v[180:183], v143
	ds_read_b128 v[188:191], v143 offset:1024
	ds_read_b128 v[192:195], v143 offset:2048
	ds_read_b128 v[196:199], v143 offset:3072
	s_add_u32 s26, s24, 0xfff00080
	s_addc_u32 s27, s25, -1
	s_cmp_eq_u32 s77, 12
	s_cselect_b32 s29, s21, s27
	s_cselect_b32 s28, s20, s26
	s_cselect_b32 s27, s9, s76
	s_cselect_b32 s26, s8, s75
	s_mov_b32 m0, s61
	ds_read_b128 v[200:203], v141
	ds_read_b128 v[204:207], v141 offset:1024
	ds_read_b128 v[208:211], v141 offset:2048
	ds_read_b128 v[212:215], v141 offset:3072
	ds_read_b128 v[216:219], v141 offset:4096
	ds_read_b128 v[220:223], v141 offset:5120
	ds_read_b128 v[224:227], v141 offset:6144
	ds_read_b128 v[228:231], v141 offset:7168
	global_load_lds_dwordx4 v158, s[24:25]
	s_mov_b32 m0, s62
	s_nop 0
	global_load_lds_dwordx4 v156, s[24:25]
	s_waitcnt vmcnt(8)
	s_waitcnt lgkmcnt(0)
	s_setprio 1
	s_barrier
	v_mfma_f32_16x16x32_bf16 v[126:129], v[164:167], v[200:203], v[126:129]
	v_mfma_f32_16x16x32_bf16 v[122:125], v[172:175], v[200:203], v[122:125]
	v_mfma_f32_16x16x32_bf16 v[118:121], v[164:167], v[208:211], v[118:121]
	v_mfma_f32_16x16x32_bf16 v[110:113], v[172:175], v[208:211], v[110:113]
	v_mfma_f32_16x16x32_bf16 v[102:105], v[164:167], v[216:219], v[102:105]
	v_mfma_f32_16x16x32_bf16 v[94:97], v[172:175], v[216:219], v[94:97]
	v_mfma_f32_16x16x32_bf16 v[86:89], v[164:167], v[224:227], v[86:89]
	v_mfma_f32_16x16x32_bf16 v[78:81], v[172:175], v[224:227], v[78:81]
	v_mfma_f32_16x16x32_bf16 v[126:129], v[168:171], v[204:207], v[126:129]
	v_mfma_f32_16x16x32_bf16 v[122:125], v[176:179], v[204:207], v[122:125]
	v_mfma_f32_16x16x32_bf16 v[118:121], v[168:171], v[212:215], v[118:121]
	v_mfma_f32_16x16x32_bf16 v[110:113], v[176:179], v[212:215], v[110:113]
	v_mfma_f32_16x16x32_bf16 v[102:105], v[168:171], v[220:223], v[102:105]
	v_mfma_f32_16x16x32_bf16 v[94:97], v[176:179], v[220:223], v[94:97]
	v_mfma_f32_16x16x32_bf16 v[86:89], v[168:171], v[228:231], v[86:89]
	v_mfma_f32_16x16x32_bf16 v[78:81], v[176:179], v[228:231], v[78:81]
	v_mfma_f32_16x16x32_bf16 v[114:117], v[180:183], v[200:203], v[114:117]
	v_mfma_f32_16x16x32_bf16 v[106:109], v[192:195], v[200:203], v[106:109]
	v_mfma_f32_16x16x32_bf16 v[98:101], v[180:183], v[208:211], v[98:101]
	v_mfma_f32_16x16x32_bf16 v[90:93], v[192:195], v[208:211], v[90:93]
	v_mfma_f32_16x16x32_bf16 v[82:85], v[180:183], v[216:219], v[82:85]
	v_mfma_f32_16x16x32_bf16 v[74:77], v[192:195], v[216:219], v[74:77]
	v_mfma_f32_16x16x32_bf16 v[70:73], v[180:183], v[224:227], v[70:73]
	v_mfma_f32_16x16x32_bf16 v[66:69], v[192:195], v[224:227], v[66:69]
	v_mfma_f32_16x16x32_bf16 v[114:117], v[188:191], v[204:207], v[114:117]
	v_mfma_f32_16x16x32_bf16 v[106:109], v[196:199], v[204:207], v[106:109]
	v_mfma_f32_16x16x32_bf16 v[98:101], v[188:191], v[212:215], v[98:101]
	v_mfma_f32_16x16x32_bf16 v[90:93], v[196:199], v[212:215], v[90:93]
	v_mfma_f32_16x16x32_bf16 v[82:85], v[188:191], v[220:223], v[82:85]
	v_mfma_f32_16x16x32_bf16 v[74:77], v[196:199], v[220:223], v[74:77]
	v_mfma_f32_16x16x32_bf16 v[70:73], v[188:191], v[228:231], v[70:73]
	v_mfma_f32_16x16x32_bf16 v[66:69], v[196:199], v[228:231], v[66:69]
	s_barrier
	s_setprio 0
	s_mov_b32 m0, s63
	v_lshl_add_u64 v[184:185], s[26:27], 0, v[134:135]
	s_add_u32 s78, s26, 0x100000
	ds_read_b128 v[200:203], v141 offset:16384
	ds_read_b128 v[204:207], v141 offset:17408
	ds_read_b128 v[208:211], v141 offset:18432
	ds_read_b128 v[212:215], v141 offset:19456
	ds_read_b128 v[216:219], v141 offset:20480
	ds_read_b128 v[220:223], v141 offset:21504
	ds_read_b128 v[224:227], v141 offset:22528
	ds_read_b128 v[228:231], v141 offset:23552
	global_load_lds_dwordx4 v[184:185], off
	v_lshl_add_u64 v[232:233], s[26:27], 0, v[130:131]
	s_mov_b32 m0, s64
	s_addc_u32 s79, s27, 0
	global_load_lds_dwordx4 v[232:233], off
	s_mov_b32 m0, s65
	v_lshl_add_u64 v[236:237], s[28:29], 0, v[132:133]
	global_load_lds_dwordx4 v134, s[78:79]
	s_mov_b32 m0, s66
	s_nop 0
	global_load_lds_dwordx4 v130, s[78:79]
	v_lshl_add_u64 v[234:235], s[28:29], 0, v[136:137]
	s_mov_b32 m0, s39
	s_nop 0
	global_load_lds_dwordx4 v[234:235], off
	s_mov_b32 m0, s40
	s_nop 0
	global_load_lds_dwordx4 v[236:237], off
	s_waitcnt vmcnt(8)
	s_waitcnt lgkmcnt(0)
	s_setprio 1
	s_barrier
	v_mfma_f32_16x16x32_bf16 v[62:65], v[164:167], v[200:203], v[62:65]
	v_mfma_f32_16x16x32_bf16 v[58:61], v[172:175], v[200:203], v[58:61]
	v_mfma_f32_16x16x32_bf16 v[54:57], v[164:167], v[208:211], v[54:57]
	v_mfma_f32_16x16x32_bf16 v[46:49], v[172:175], v[208:211], v[46:49]
	v_mfma_f32_16x16x32_bf16 v[38:41], v[164:167], v[216:219], v[38:41]
	v_mfma_f32_16x16x32_bf16 v[30:33], v[172:175], v[216:219], v[30:33]
	v_mfma_f32_16x16x32_bf16 v[22:25], v[164:167], v[224:227], v[22:25]
	v_mfma_f32_16x16x32_bf16 v[14:17], v[172:175], v[224:227], v[14:17]
	v_mfma_f32_16x16x32_bf16 v[62:65], v[168:171], v[204:207], v[62:65]
	v_mfma_f32_16x16x32_bf16 v[58:61], v[176:179], v[204:207], v[58:61]
	v_mfma_f32_16x16x32_bf16 v[54:57], v[168:171], v[212:215], v[54:57]
	v_mfma_f32_16x16x32_bf16 v[46:49], v[176:179], v[212:215], v[46:49]
	v_mfma_f32_16x16x32_bf16 v[38:41], v[168:171], v[220:223], v[38:41]
	v_mfma_f32_16x16x32_bf16 v[30:33], v[176:179], v[220:223], v[30:33]
	v_mfma_f32_16x16x32_bf16 v[22:25], v[168:171], v[228:231], v[22:25]
	v_mfma_f32_16x16x32_bf16 v[14:17], v[176:179], v[228:231], v[14:17]
	v_mfma_f32_16x16x32_bf16 v[50:53], v[180:183], v[200:203], v[50:53]
	v_mfma_f32_16x16x32_bf16 v[42:45], v[192:195], v[200:203], v[42:45]
	v_mfma_f32_16x16x32_bf16 v[34:37], v[180:183], v[208:211], v[34:37]
	v_mfma_f32_16x16x32_bf16 v[26:29], v[192:195], v[208:211], v[26:29]
	v_mfma_f32_16x16x32_bf16 v[18:21], v[180:183], v[216:219], v[18:21]
	v_mfma_f32_16x16x32_bf16 v[10:13], v[192:195], v[216:219], v[10:13]
	v_mfma_f32_16x16x32_bf16 v[6:9], v[180:183], v[224:227], v[6:9]
	v_mfma_f32_16x16x32_bf16 v[2:5], v[192:195], v[224:227], v[2:5]
	v_mfma_f32_16x16x32_bf16 v[50:53], v[188:191], v[204:207], v[50:53]
	v_mfma_f32_16x16x32_bf16 v[42:45], v[196:199], v[204:207], v[42:45]
	v_mfma_f32_16x16x32_bf16 v[34:37], v[188:191], v[212:215], v[34:37]
	v_mfma_f32_16x16x32_bf16 v[26:29], v[196:199], v[212:215], v[26:29]
	v_mfma_f32_16x16x32_bf16 v[18:21], v[188:191], v[220:223], v[18:21]
	v_mfma_f32_16x16x32_bf16 v[10:13], v[196:199], v[220:223], v[10:13]
	v_mfma_f32_16x16x32_bf16 v[6:9], v[188:191], v[228:231], v[6:9]
	v_mfma_f32_16x16x32_bf16 v[2:5], v[196:199], v[228:231], v[2:5]
	s_barrier
	s_setprio 0
	ds_read_b128 v[164:167], v145
	ds_read_b128 v[168:171], v145 offset:1024
	ds_read_b128 v[172:175], v145 offset:2048
	ds_read_b128 v[176:179], v145 offset:3072
	ds_read_b128 v[180:183], v147
	ds_read_b128 v[188:191], v147 offset:1024
	ds_read_b128 v[192:195], v147 offset:2048
	ds_read_b128 v[196:199], v147 offset:3072
	s_add_u32 s28, s28, 0x100000
	s_addc_u32 s29, s29, 0
	s_mov_b32 m0, s41
	ds_read_b128 v[200:203], v141 offset:32768
	ds_read_b128 v[204:207], v141 offset:33792
	ds_read_b128 v[208:211], v141 offset:34816
	ds_read_b128 v[212:215], v141 offset:35840
	ds_read_b128 v[216:219], v141 offset:36864
	ds_read_b128 v[220:223], v141 offset:37888
	ds_read_b128 v[224:227], v141 offset:38912
	ds_read_b128 v[228:231], v141 offset:39936
	global_load_lds_dwordx4 v136, s[28:29]
	s_mov_b32 m0, s42
	s_nop 0
	global_load_lds_dwordx4 v132, s[28:29]
	s_waitcnt vmcnt(8)
	s_waitcnt lgkmcnt(0)
	s_setprio 1
	s_barrier
	v_mfma_f32_16x16x32_bf16 v[126:129], v[164:167], v[200:203], v[126:129]
	v_mfma_f32_16x16x32_bf16 v[122:125], v[172:175], v[200:203], v[122:125]
	v_mfma_f32_16x16x32_bf16 v[118:121], v[164:167], v[208:211], v[118:121]
	v_mfma_f32_16x16x32_bf16 v[110:113], v[172:175], v[208:211], v[110:113]
	v_mfma_f32_16x16x32_bf16 v[102:105], v[164:167], v[216:219], v[102:105]
	v_mfma_f32_16x16x32_bf16 v[94:97], v[172:175], v[216:219], v[94:97]
	v_mfma_f32_16x16x32_bf16 v[86:89], v[164:167], v[224:227], v[86:89]
	v_mfma_f32_16x16x32_bf16 v[78:81], v[172:175], v[224:227], v[78:81]
	v_mfma_f32_16x16x32_bf16 v[126:129], v[168:171], v[204:207], v[126:129]
	v_mfma_f32_16x16x32_bf16 v[122:125], v[176:179], v[204:207], v[122:125]
	v_mfma_f32_16x16x32_bf16 v[118:121], v[168:171], v[212:215], v[118:121]
	v_mfma_f32_16x16x32_bf16 v[110:113], v[176:179], v[212:215], v[110:113]
	v_mfma_f32_16x16x32_bf16 v[102:105], v[168:171], v[220:223], v[102:105]
	v_mfma_f32_16x16x32_bf16 v[94:97], v[176:179], v[220:223], v[94:97]
	v_mfma_f32_16x16x32_bf16 v[86:89], v[168:171], v[228:231], v[86:89]
	v_mfma_f32_16x16x32_bf16 v[78:81], v[176:179], v[228:231], v[78:81]
	v_mfma_f32_16x16x32_bf16 v[114:117], v[180:183], v[200:203], v[114:117]
	v_mfma_f32_16x16x32_bf16 v[106:109], v[192:195], v[200:203], v[106:109]
	v_mfma_f32_16x16x32_bf16 v[98:101], v[180:183], v[208:211], v[98:101]
	v_mfma_f32_16x16x32_bf16 v[90:93], v[192:195], v[208:211], v[90:93]
	v_mfma_f32_16x16x32_bf16 v[82:85], v[180:183], v[216:219], v[82:85]
	v_mfma_f32_16x16x32_bf16 v[74:77], v[192:195], v[216:219], v[74:77]
	v_mfma_f32_16x16x32_bf16 v[70:73], v[180:183], v[224:227], v[70:73]
	v_mfma_f32_16x16x32_bf16 v[66:69], v[192:195], v[224:227], v[66:69]
	v_mfma_f32_16x16x32_bf16 v[114:117], v[188:191], v[204:207], v[114:117]
	v_mfma_f32_16x16x32_bf16 v[106:109], v[196:199], v[204:207], v[106:109]
	v_mfma_f32_16x16x32_bf16 v[98:101], v[188:191], v[212:215], v[98:101]
	v_mfma_f32_16x16x32_bf16 v[90:93], v[196:199], v[212:215], v[90:93]
	v_mfma_f32_16x16x32_bf16 v[82:85], v[188:191], v[220:223], v[82:85]
	v_mfma_f32_16x16x32_bf16 v[74:77], v[196:199], v[220:223], v[74:77]
	v_mfma_f32_16x16x32_bf16 v[70:73], v[188:191], v[228:231], v[70:73]
	v_mfma_f32_16x16x32_bf16 v[66:69], v[196:199], v[228:231], v[66:69]
	s_barrier
	s_setprio 0
	s_mov_b32 m0, s67
	v_lshl_add_u64 v[184:185], v[184:185], 0, s[12:13]
	s_add_u32 s26, s26, 0x100080
	ds_read_b128 v[200:203], v141 offset:49152
	ds_read_b128 v[204:207], v141 offset:50176
	ds_read_b128 v[208:211], v141 offset:51200
	ds_read_b128 v[212:215], v141 offset:52224
	ds_read_b128 v[216:219], v141 offset:53248
	ds_read_b128 v[220:223], v141 offset:54272
	ds_read_b128 v[224:227], v141 offset:55296
	ds_read_b128 v[228:231], v141 offset:56320
	global_load_lds_dwordx4 v[184:185], off
	v_lshl_add_u64 v[184:185], v[232:233], 0, s[12:13]
	s_mov_b32 m0, s68
	s_addc_u32 s27, s27, 0
	global_load_lds_dwordx4 v[184:185], off
	s_mov_b32 m0, s69
	s_nop 0
	global_load_lds_dwordx4 v134, s[26:27]
	s_add_i32 m0, s69, 0x2000
	s_nop 0
	global_load_lds_dwordx4 v130, s[26:27]
	v_lshl_add_u64 v[184:185], v[234:235], 0, s[12:13]
	s_mov_b32 m0, s49
	s_nop 0
	global_load_lds_dwordx4 v[184:185], off
	v_lshl_add_u64 v[184:185], v[236:237], 0, s[12:13]
	s_mov_b32 m0, s56
	s_nop 0
	global_load_lds_dwordx4 v[184:185], off
	s_waitcnt vmcnt(8)
	s_waitcnt lgkmcnt(0)
	s_setprio 1
	s_barrier
	v_mfma_f32_16x16x32_bf16 v[62:65], v[164:167], v[200:203], v[62:65]
	v_mfma_f32_16x16x32_bf16 v[58:61], v[172:175], v[200:203], v[58:61]
	v_mfma_f32_16x16x32_bf16 v[54:57], v[164:167], v[208:211], v[54:57]
	v_mfma_f32_16x16x32_bf16 v[46:49], v[172:175], v[208:211], v[46:49]
	v_mfma_f32_16x16x32_bf16 v[38:41], v[164:167], v[216:219], v[38:41]
	v_mfma_f32_16x16x32_bf16 v[30:33], v[172:175], v[216:219], v[30:33]
	v_mfma_f32_16x16x32_bf16 v[22:25], v[164:167], v[224:227], v[22:25]
	v_mfma_f32_16x16x32_bf16 v[14:17], v[172:175], v[224:227], v[14:17]
	v_mfma_f32_16x16x32_bf16 v[62:65], v[168:171], v[204:207], v[62:65]
	v_mfma_f32_16x16x32_bf16 v[58:61], v[176:179], v[204:207], v[58:61]
	v_mfma_f32_16x16x32_bf16 v[54:57], v[168:171], v[212:215], v[54:57]
	v_mfma_f32_16x16x32_bf16 v[46:49], v[176:179], v[212:215], v[46:49]
	v_mfma_f32_16x16x32_bf16 v[38:41], v[168:171], v[220:223], v[38:41]
	v_mfma_f32_16x16x32_bf16 v[30:33], v[176:179], v[220:223], v[30:33]
	v_mfma_f32_16x16x32_bf16 v[22:25], v[168:171], v[228:231], v[22:25]
	v_mfma_f32_16x16x32_bf16 v[14:17], v[176:179], v[228:231], v[14:17]
	v_mfma_f32_16x16x32_bf16 v[50:53], v[180:183], v[200:203], v[50:53]
	v_mfma_f32_16x16x32_bf16 v[42:45], v[192:195], v[200:203], v[42:45]
	v_mfma_f32_16x16x32_bf16 v[34:37], v[180:183], v[208:211], v[34:37]
	v_mfma_f32_16x16x32_bf16 v[26:29], v[192:195], v[208:211], v[26:29]
	v_mfma_f32_16x16x32_bf16 v[18:21], v[180:183], v[216:219], v[18:21]
	v_mfma_f32_16x16x32_bf16 v[10:13], v[192:195], v[216:219], v[10:13]
	v_mfma_f32_16x16x32_bf16 v[6:9], v[180:183], v[224:227], v[6:9]
	v_mfma_f32_16x16x32_bf16 v[2:5], v[192:195], v[224:227], v[2:5]
	v_mfma_f32_16x16x32_bf16 v[50:53], v[188:191], v[204:207], v[50:53]
	v_mfma_f32_16x16x32_bf16 v[42:45], v[196:199], v[204:207], v[42:45]
	v_mfma_f32_16x16x32_bf16 v[34:37], v[188:191], v[212:215], v[34:37]
	v_mfma_f32_16x16x32_bf16 v[26:29], v[196:199], v[212:215], v[26:29]
	v_mfma_f32_16x16x32_bf16 v[18:21], v[188:191], v[220:223], v[18:21]
	v_mfma_f32_16x16x32_bf16 v[10:13], v[196:199], v[220:223], v[10:13]
	v_mfma_f32_16x16x32_bf16 v[6:9], v[188:191], v[228:231], v[6:9]
	v_mfma_f32_16x16x32_bf16 v[2:5], v[196:199], v[228:231], v[2:5]
	s_barrier
	s_setprio 0
	s_add_i32 s77, s77, 2
	s_add_u32 s75, s75, 0x100
	s_addc_u32 s76, s76, 0
	s_add_u32 s24, s24, 0x100
	s_addc_u32 s25, s25, 0
	s_cmp_gt_u32 s77, 13
	s_cbranch_scc0 .LBB0_790
	s_and_b64 vcc, exec, s[18:19]
	s_cbranch_vccz .LBB0_793
	s_barrier

.LBB0_1198:
	v_add_u32_e32 v3, s61, v186
	ds_read_b128 v[134:137], v3
	ds_read_b128 v[138:141], v3 offset:1024
	ds_read_b128 v[142:145], v3 offset:2048
	ds_read_b128 v[146:149], v3 offset:3072
	v_add_u32_e32 v3, s62, v186
	s_add_u32 s30, s28, s8
	ds_read_b128 v[150:153], v3
	ds_read_b128 v[154:157], v3 offset:1024
	ds_read_b128 v[158:161], v3 offset:2048
	ds_read_b128 v[190:193], v3 offset:3072
	s_addc_u32 s31, s29, s9
	s_add_u32 s30, s30, 0x100
	s_addc_u32 s31, s31, 0
	s_add_u32 s71, s68, s8
	s_addc_u32 s72, s69, s9
	s_cmpk_eq_i32 s8, 0x1f00
	s_cselect_b32 s35, s25, s31
	s_cselect_b32 s34, s24, s30
	s_cselect_b32 s31, s65, s72
	s_cselect_b32 s30, s66, s71
	v_lshl_add_u64 v[4:5], v[182:183], 0, s[8:9]
	s_add_i32 m0, s40, 0xc000
	ds_read_b128 v[194:197], v189
	ds_read_b128 v[198:201], v189 offset:1024
	ds_read_b128 v[202:205], v189 offset:2048
	ds_read_b128 v[206:209], v189 offset:3072
	ds_read_b128 v[210:213], v189 offset:4096
	ds_read_b128 v[214:217], v189 offset:5120
	ds_read_b128 v[218:221], v189 offset:6144
	ds_read_b128 v[222:225], v189 offset:7168
	global_load_lds_dwordx4 v[4:5], off
	v_lshl_add_u64 v[4:5], v[180:181], 0, s[8:9]
	s_add_i32 m0, s40, 0xe000
	s_nop 0
	global_load_lds_dwordx4 v[4:5], off
	s_waitcnt vmcnt(8)
	s_waitcnt lgkmcnt(0)
	s_setprio 1
	s_barrier
	v_mfma_f32_16x16x32_bf16 v[130:133], v[134:137], v[194:197], v[130:133]
	v_mfma_f32_16x16x32_bf16 v[126:129], v[142:145], v[194:197], v[126:129]
	v_mfma_f32_16x16x32_bf16 v[114:117], v[134:137], v[202:205], v[114:117]
	v_mfma_f32_16x16x32_bf16 v[110:113], v[142:145], v[202:205], v[110:113]
	v_mfma_f32_16x16x32_bf16 v[98:101], v[134:137], v[210:213], v[98:101]
	v_mfma_f32_16x16x32_bf16 v[94:97], v[142:145], v[210:213], v[94:97]
	v_mfma_f32_16x16x32_bf16 v[82:85], v[134:137], v[218:221], v[82:85]
	v_mfma_f32_16x16x32_bf16 v[78:81], v[142:145], v[218:221], v[78:81]
	v_mfma_f32_16x16x32_bf16 v[130:133], v[138:141], v[198:201], v[130:133]
	v_mfma_f32_16x16x32_bf16 v[126:129], v[146:149], v[198:201], v[126:129]
	v_mfma_f32_16x16x32_bf16 v[114:117], v[138:141], v[206:209], v[114:117]
	v_mfma_f32_16x16x32_bf16 v[110:113], v[146:149], v[206:209], v[110:113]
	v_mfma_f32_16x16x32_bf16 v[98:101], v[138:141], v[214:217], v[98:101]
	v_mfma_f32_16x16x32_bf16 v[94:97], v[146:149], v[214:217], v[94:97]
	v_mfma_f32_16x16x32_bf16 v[82:85], v[138:141], v[222:225], v[82:85]
	v_mfma_f32_16x16x32_bf16 v[78:81], v[146:149], v[222:225], v[78:81]
	v_mfma_f32_16x16x32_bf16 v[122:125], v[150:153], v[194:197], v[122:125]
	v_mfma_f32_16x16x32_bf16 v[118:121], v[158:161], v[194:197], v[118:121]
	v_mfma_f32_16x16x32_bf16 v[106:109], v[150:153], v[202:205], v[106:109]
	v_mfma_f32_16x16x32_bf16 v[102:105], v[158:161], v[202:205], v[102:105]
	v_mfma_f32_16x16x32_bf16 v[90:93], v[150:153], v[210:213], v[90:93]
	v_mfma_f32_16x16x32_bf16 v[86:89], v[158:161], v[210:213], v[86:89]
	v_mfma_f32_16x16x32_bf16 v[74:77], v[150:153], v[218:221], v[74:77]
	v_mfma_f32_16x16x32_bf16 v[70:73], v[158:161], v[218:221], v[70:73]
	v_mfma_f32_16x16x32_bf16 v[122:125], v[154:157], v[198:201], v[122:125]
	v_mfma_f32_16x16x32_bf16 v[118:121], v[190:193], v[198:201], v[118:121]
	v_mfma_f32_16x16x32_bf16 v[106:109], v[154:157], v[206:209], v[106:109]
	v_mfma_f32_16x16x32_bf16 v[102:105], v[190:193], v[206:209], v[102:105]
	v_mfma_f32_16x16x32_bf16 v[90:93], v[154:157], v[214:217], v[90:93]
	v_mfma_f32_16x16x32_bf16 v[86:89], v[190:193], v[214:217], v[86:89]
	v_mfma_f32_16x16x32_bf16 v[74:77], v[154:157], v[222:225], v[74:77]
	v_mfma_f32_16x16x32_bf16 v[70:73], v[190:193], v[222:225], v[70:73]
	s_barrier
	s_setprio 0
	s_add_i32 s71, s61, s39
	v_lshl_add_u64 v[162:163], s[30:31], 0, v[166:167]
	s_mov_b32 m0, s71
	ds_read_b128 v[194:197], v189 offset:16384
	ds_read_b128 v[198:201], v189 offset:17408
	ds_read_b128 v[202:205], v189 offset:18432
	ds_read_b128 v[206:209], v189 offset:19456
	ds_read_b128 v[210:213], v189 offset:20480
	ds_read_b128 v[214:217], v189 offset:21504
	ds_read_b128 v[218:221], v189 offset:22528
	ds_read_b128 v[222:225], v189 offset:23552
	global_load_lds_dwordx4 v[162:163], off
	s_add_i32 m0, s71, 0x2000
	s_add_u32 s72, s30, 0x100000
	v_lshl_add_u64 v[184:185], s[30:31], 0, v[170:171]
	s_addc_u32 s73, s31, 0
	s_add_i32 s71, s62, s39
	global_load_lds_dwordx4 v[184:185], off
	s_mov_b32 m0, s71
	v_lshl_add_u64 v[226:227], s[34:35], 0, v[164:165]
	global_load_lds_dwordx4 v166, s[72:73]
	s_add_i32 m0, s71, 0x2000
	v_lshl_add_u64 v[228:229], s[34:35], 0, v[168:169]
	global_load_lds_dwordx4 v170, s[72:73]
	s_mov_b32 m0, s40
	s_nop 0
	global_load_lds_dwordx4 v[226:227], off
	s_mov_b32 m0, s41
	s_nop 0
	global_load_lds_dwordx4 v[228:229], off
	s_waitcnt vmcnt(8)
	s_waitcnt lgkmcnt(0)
	s_setprio 1
	s_barrier
	v_mfma_f32_16x16x32_bf16 v[66:69], v[134:137], v[194:197], v[66:69]
	v_mfma_f32_16x16x32_bf16 v[62:65], v[142:145], v[194:197], v[62:65]
	v_mfma_f32_16x16x32_bf16 v[50:53], v[134:137], v[202:205], v[50:53]
	v_mfma_f32_16x16x32_bf16 v[46:49], v[142:145], v[202:205], v[46:49]
	v_mfma_f32_16x16x32_bf16 v[34:37], v[134:137], v[210:213], v[34:37]
	v_mfma_f32_16x16x32_bf16 v[30:33], v[142:145], v[210:213], v[30:33]
	v_mfma_f32_16x16x32_bf16 v[18:21], v[134:137], v[218:221], v[18:21]
	v_mfma_f32_16x16x32_bf16 v[14:17], v[142:145], v[218:221], v[14:17]
	v_mfma_f32_16x16x32_bf16 v[66:69], v[138:141], v[198:201], v[66:69]
	v_mfma_f32_16x16x32_bf16 v[62:65], v[146:149], v[198:201], v[62:65]
	v_mfma_f32_16x16x32_bf16 v[50:53], v[138:141], v[206:209], v[50:53]
	v_mfma_f32_16x16x32_bf16 v[46:49], v[146:149], v[206:209], v[46:49]
	v_mfma_f32_16x16x32_bf16 v[34:37], v[138:141], v[214:217], v[34:37]
	v_mfma_f32_16x16x32_bf16 v[30:33], v[146:149], v[214:217], v[30:33]
	v_mfma_f32_16x16x32_bf16 v[18:21], v[138:141], v[222:225], v[18:21]
	v_mfma_f32_16x16x32_bf16 v[14:17], v[146:149], v[222:225], v[14:17]
	v_mfma_f32_16x16x32_bf16 v[58:61], v[150:153], v[194:197], v[58:61]
	v_mfma_f32_16x16x32_bf16 v[54:57], v[158:161], v[194:197], v[54:57]
	v_mfma_f32_16x16x32_bf16 v[42:45], v[150:153], v[202:205], v[42:45]
	v_mfma_f32_16x16x32_bf16 v[38:41], v[158:161], v[202:205], v[38:41]
	v_mfma_f32_16x16x32_bf16 v[26:29], v[150:153], v[210:213], v[26:29]
	v_mfma_f32_16x16x32_bf16 v[22:25], v[158:161], v[210:213], v[22:25]
	v_mfma_f32_16x16x32_bf16 v[10:13], v[150:153], v[218:221], v[10:13]
	v_mfma_f32_16x16x32_bf16 v[4:7], v[158:161], v[218:221], v[6:9]
	v_mfma_f32_16x16x32_bf16 v[58:61], v[154:157], v[198:201], v[58:61]
	v_mfma_f32_16x16x32_bf16 v[54:57], v[190:193], v[198:201], v[54:57]
	v_mfma_f32_16x16x32_bf16 v[42:45], v[154:157], v[206:209], v[42:45]
	v_mfma_f32_16x16x32_bf16 v[38:41], v[190:193], v[206:209], v[38:41]
	v_mfma_f32_16x16x32_bf16 v[26:29], v[154:157], v[214:217], v[26:29]
	v_mfma_f32_16x16x32_bf16 v[22:25], v[190:193], v[214:217], v[22:25]
	v_mfma_f32_16x16x32_bf16 v[10:13], v[154:157], v[222:225], v[10:13]
	v_mfma_f32_16x16x32_bf16 v[4:7], v[190:193], v[222:225], v[4:7]
	s_barrier
	s_setprio 0
	s_add_i32 s71, 0, 0x18000
	v_add_u32_e32 v3, s71, v186
	s_add_i32 s72, 0, 0x1c000
	ds_read_b128 v[134:137], v3
	ds_read_b128 v[138:141], v3 offset:1024
	ds_read_b128 v[142:145], v3 offset:2048
	ds_read_b128 v[146:149], v3 offset:3072
	v_add_u32_e32 v3, s72, v186
	ds_read_b128 v[150:153], v3
	ds_read_b128 v[154:157], v3 offset:1024
	ds_read_b128 v[158:161], v3 offset:2048
	ds_read_b128 v[190:193], v3 offset:3072
	s_add_u32 s34, s34, 0x480000
	s_addc_u32 s35, s35, 0
	s_mov_b32 m0, s42
	ds_read_b128 v[194:197], v189 offset:32768
	ds_read_b128 v[198:201], v189 offset:33792
	ds_read_b128 v[202:205], v189 offset:34816
	ds_read_b128 v[206:209], v189 offset:35840
	ds_read_b128 v[210:213], v189 offset:36864
	ds_read_b128 v[214:217], v189 offset:37888
	ds_read_b128 v[218:221], v189 offset:38912
	ds_read_b128 v[222:225], v189 offset:39936
	global_load_lds_dwordx4 v164, s[34:35]
	s_mov_b32 m0, s43
	s_nop 0
	global_load_lds_dwordx4 v168, s[34:35]
	s_waitcnt vmcnt(8)
	s_waitcnt lgkmcnt(0)
	s_setprio 1
	s_barrier
	v_mfma_f32_16x16x32_bf16 v[130:133], v[134:137], v[194:197], v[130:133]
	v_mfma_f32_16x16x32_bf16 v[126:129], v[142:145], v[194:197], v[126:129]
	v_mfma_f32_16x16x32_bf16 v[114:117], v[134:137], v[202:205], v[114:117]
	v_mfma_f32_16x16x32_bf16 v[110:113], v[142:145], v[202:205], v[110:113]
	v_mfma_f32_16x16x32_bf16 v[98:101], v[134:137], v[210:213], v[98:101]
	v_mfma_f32_16x16x32_bf16 v[94:97], v[142:145], v[210:213], v[94:97]
	v_mfma_f32_16x16x32_bf16 v[82:85], v[134:137], v[218:221], v[82:85]
	v_mfma_f32_16x16x32_bf16 v[78:81], v[142:145], v[218:221], v[78:81]
	v_mfma_f32_16x16x32_bf16 v[130:133], v[138:141], v[198:201], v[130:133]
	v_mfma_f32_16x16x32_bf16 v[126:129], v[146:149], v[198:201], v[126:129]
	v_mfma_f32_16x16x32_bf16 v[114:117], v[138:141], v[206:209], v[114:117]
	v_mfma_f32_16x16x32_bf16 v[110:113], v[146:149], v[206:209], v[110:113]
	v_mfma_f32_16x16x32_bf16 v[98:101], v[138:141], v[214:217], v[98:101]
	v_mfma_f32_16x16x32_bf16 v[94:97], v[146:149], v[214:217], v[94:97]
	v_mfma_f32_16x16x32_bf16 v[82:85], v[138:141], v[222:225], v[82:85]
	v_mfma_f32_16x16x32_bf16 v[78:81], v[146:149], v[222:225], v[78:81]
	v_mfma_f32_16x16x32_bf16 v[122:125], v[150:153], v[194:197], v[122:125]
	v_mfma_f32_16x16x32_bf16 v[118:121], v[158:161], v[194:197], v[118:121]
	v_mfma_f32_16x16x32_bf16 v[106:109], v[150:153], v[202:205], v[106:109]
	v_mfma_f32_16x16x32_bf16 v[102:105], v[158:161], v[202:205], v[102:105]
	v_mfma_f32_16x16x32_bf16 v[90:93], v[150:153], v[210:213], v[90:93]
	v_mfma_f32_16x16x32_bf16 v[86:89], v[158:161], v[210:213], v[86:89]
	v_mfma_f32_16x16x32_bf16 v[74:77], v[150:153], v[218:221], v[74:77]
	v_mfma_f32_16x16x32_bf16 v[70:73], v[158:161], v[218:221], v[70:73]
	v_mfma_f32_16x16x32_bf16 v[122:125], v[154:157], v[198:201], v[122:125]
	v_mfma_f32_16x16x32_bf16 v[118:121], v[190:193], v[198:201], v[118:121]
	v_mfma_f32_16x16x32_bf16 v[106:109], v[154:157], v[206:209], v[106:109]
	v_mfma_f32_16x16x32_bf16 v[102:105], v[190:193], v[206:209], v[102:105]
	v_mfma_f32_16x16x32_bf16 v[90:93], v[154:157], v[214:217], v[90:93]
	v_mfma_f32_16x16x32_bf16 v[86:89], v[190:193], v[214:217], v[86:89]
	v_mfma_f32_16x16x32_bf16 v[74:77], v[154:157], v[222:225], v[74:77]
	v_mfma_f32_16x16x32_bf16 v[70:73], v[190:193], v[222:225], v[70:73]
	s_barrier
	s_setprio 0
	s_add_i32 s34, s71, s39
	v_lshl_add_u64 v[8:9], v[162:163], 0, s[18:19]
	s_mov_b32 m0, s34
	ds_read_b128 v[194:197], v189 offset:49152
	ds_read_b128 v[198:201], v189 offset:50176
	ds_read_b128 v[202:205], v189 offset:51200
	ds_read_b128 v[206:209], v189 offset:52224
	ds_read_b128 v[210:213], v189 offset:53248
	ds_read_b128 v[214:217], v189 offset:54272
	ds_read_b128 v[218:221], v189 offset:55296
	ds_read_b128 v[222:225], v189 offset:56320
	global_load_lds_dwordx4 v[8:9], off
	s_add_i32 m0, s34, 0x2000
	s_add_u32 s30, s30, 0x100080
	v_lshl_add_u64 v[8:9], v[184:185], 0, s[18:19]
	s_addc_u32 s31, s31, 0
	s_add_i32 s34, s72, s39
	global_load_lds_dwordx4 v[8:9], off
	s_mov_b32 m0, s34
	s_nop 0
	global_load_lds_dwordx4 v166, s[30:31]
	s_add_i32 m0, s34, 0x2000
	s_nop 0
	global_load_lds_dwordx4 v170, s[30:31]
	v_lshl_add_u64 v[8:9], v[226:227], 0, s[18:19]
	s_mov_b32 m0, s47
	s_nop 0
	global_load_lds_dwordx4 v[8:9], off
	v_lshl_add_u64 v[8:9], v[228:229], 0, s[18:19]
	s_mov_b32 m0, s49
	s_nop 0
	global_load_lds_dwordx4 v[8:9], off
	s_waitcnt vmcnt(8)
	s_waitcnt lgkmcnt(0)
	s_setprio 1
	s_barrier
	v_mfma_f32_16x16x32_bf16 v[66:69], v[134:137], v[194:197], v[66:69]
	v_mfma_f32_16x16x32_bf16 v[62:65], v[142:145], v[194:197], v[62:65]
	v_mfma_f32_16x16x32_bf16 v[50:53], v[134:137], v[202:205], v[50:53]
	v_mfma_f32_16x16x32_bf16 v[46:49], v[142:145], v[202:205], v[46:49]
	v_mfma_f32_16x16x32_bf16 v[34:37], v[134:137], v[210:213], v[34:37]
	v_mfma_f32_16x16x32_bf16 v[30:33], v[142:145], v[210:213], v[30:33]
	v_mfma_f32_16x16x32_bf16 v[18:21], v[134:137], v[218:221], v[18:21]
	v_mfma_f32_16x16x32_bf16 v[14:17], v[142:145], v[218:221], v[14:17]
	v_mfma_f32_16x16x32_bf16 v[66:69], v[138:141], v[198:201], v[66:69]
	v_mfma_f32_16x16x32_bf16 v[62:65], v[146:149], v[198:201], v[62:65]
	v_mfma_f32_16x16x32_bf16 v[50:53], v[138:141], v[206:209], v[50:53]
	v_mfma_f32_16x16x32_bf16 v[46:49], v[146:149], v[206:209], v[46:49]
	v_mfma_f32_16x16x32_bf16 v[34:37], v[138:141], v[214:217], v[34:37]
	v_mfma_f32_16x16x32_bf16 v[30:33], v[146:149], v[214:217], v[30:33]
	v_mfma_f32_16x16x32_bf16 v[18:21], v[138:141], v[222:225], v[18:21]
	v_mfma_f32_16x16x32_bf16 v[14:17], v[146:149], v[222:225], v[14:17]
	v_mfma_f32_16x16x32_bf16 v[58:61], v[150:153], v[194:197], v[58:61]
	v_mfma_f32_16x16x32_bf16 v[54:57], v[158:161], v[194:197], v[54:57]
	v_mfma_f32_16x16x32_bf16 v[42:45], v[150:153], v[202:205], v[42:45]
	v_mfma_f32_16x16x32_bf16 v[38:41], v[158:161], v[202:205], v[38:41]
	v_mfma_f32_16x16x32_bf16 v[26:29], v[150:153], v[210:213], v[26:29]
	v_mfma_f32_16x16x32_bf16 v[22:25], v[158:161], v[210:213], v[22:25]
	v_mfma_f32_16x16x32_bf16 v[8:11], v[150:153], v[218:221], v[10:13]
	v_mfma_f32_16x16x32_bf16 v[4:7], v[158:161], v[218:221], v[4:7]
	v_mfma_f32_16x16x32_bf16 v[58:61], v[154:157], v[198:201], v[58:61]
	v_mfma_f32_16x16x32_bf16 v[54:57], v[190:193], v[198:201], v[54:57]
	v_mfma_f32_16x16x32_bf16 v[42:45], v[154:157], v[206:209], v[42:45]
	v_mfma_f32_16x16x32_bf16 v[38:41], v[190:193], v[206:209], v[38:41]
	v_mfma_f32_16x16x32_bf16 v[26:29], v[154:157], v[214:217], v[26:29]
	v_mfma_f32_16x16x32_bf16 v[22:25], v[190:193], v[214:217], v[22:25]
	v_mfma_f32_16x16x32_bf16 v[10:13], v[154:157], v[222:225], v[8:11]
	v_mfma_f32_16x16x32_bf16 v[6:9], v[190:193], v[222:225], v[4:7]
	s_barrier
	s_setprio 0
	s_add_i32 s70, s70, 2
	s_add_u32 s8, s8, 0x100
	s_addc_u32 s9, s9, 0
	s_cmp_gt_u32 s70, 61
	s_cbranch_scc1 .LBB0_1201

.LBB0_1281:
	ds_read_b128 v[146:149], v152
	ds_read_b128 v[156:159], v152 offset:1024
	ds_read_b128 v[160:163], v152 offset:2048
	ds_read_b128 v[164:167], v152 offset:3072
	ds_read_b128 v[168:171], v153
	ds_read_b128 v[172:175], v153 offset:1024
	ds_read_b128 v[176:179], v153 offset:2048
	ds_read_b128 v[180:183], v153 offset:3072
	s_add_u32 s40, s38, 0xfff00080
	s_addc_u32 s41, s39, -1
	s_cmp_eq_u32 s72, 60
	s_cselect_b32 s43, s27, s41
	s_cselect_b32 s42, s35, s40
	s_cselect_b32 s41, s15, s71
	s_cselect_b32 s40, s37, s70
	s_add_i32 m0, s49, 0xc000
	ds_read_b128 v[188:191], v154
	ds_read_b128 v[192:195], v154 offset:1024
	ds_read_b128 v[196:199], v154 offset:2048
	ds_read_b128 v[200:203], v154 offset:3072
	ds_read_b128 v[204:207], v154 offset:4096
	ds_read_b128 v[208:211], v154 offset:5120
	ds_read_b128 v[212:215], v154 offset:6144
	ds_read_b128 v[216:219], v154 offset:7168
	global_load_lds_dwordx4 v140, s[38:39]
	s_add_i32 m0, s49, 0xe000
	s_nop 0
	global_load_lds_dwordx4 v138, s[38:39]
	s_waitcnt vmcnt(8)
	s_waitcnt lgkmcnt(0)
	s_setprio 1
	s_barrier
	v_mfma_f32_16x16x32_bf16 v[126:129], v[146:149], v[188:191], v[126:129]
	v_mfma_f32_16x16x32_bf16 v[122:125], v[160:163], v[188:191], v[122:125]
	v_mfma_f32_16x16x32_bf16 v[110:113], v[146:149], v[196:199], v[110:113]
	v_mfma_f32_16x16x32_bf16 v[106:109], v[160:163], v[196:199], v[106:109]
	v_mfma_f32_16x16x32_bf16 v[94:97], v[146:149], v[204:207], v[94:97]
	v_mfma_f32_16x16x32_bf16 v[90:93], v[160:163], v[204:207], v[90:93]
	v_mfma_f32_16x16x32_bf16 v[78:81], v[146:149], v[212:215], v[78:81]
	v_mfma_f32_16x16x32_bf16 v[74:77], v[160:163], v[212:215], v[74:77]
	v_mfma_f32_16x16x32_bf16 v[126:129], v[156:159], v[192:195], v[126:129]
	v_mfma_f32_16x16x32_bf16 v[122:125], v[164:167], v[192:195], v[122:125]
	v_mfma_f32_16x16x32_bf16 v[110:113], v[156:159], v[200:203], v[110:113]
	v_mfma_f32_16x16x32_bf16 v[106:109], v[164:167], v[200:203], v[106:109]
	v_mfma_f32_16x16x32_bf16 v[94:97], v[156:159], v[208:211], v[94:97]
	v_mfma_f32_16x16x32_bf16 v[90:93], v[164:167], v[208:211], v[90:93]
	v_mfma_f32_16x16x32_bf16 v[78:81], v[156:159], v[216:219], v[78:81]
	v_mfma_f32_16x16x32_bf16 v[74:77], v[164:167], v[216:219], v[74:77]
	v_mfma_f32_16x16x32_bf16 v[118:121], v[168:171], v[188:191], v[118:121]
	v_mfma_f32_16x16x32_bf16 v[114:117], v[176:179], v[188:191], v[114:117]
	v_mfma_f32_16x16x32_bf16 v[102:105], v[168:171], v[196:199], v[102:105]
	v_mfma_f32_16x16x32_bf16 v[98:101], v[176:179], v[196:199], v[98:101]
	v_mfma_f32_16x16x32_bf16 v[86:89], v[168:171], v[204:207], v[86:89]
	v_mfma_f32_16x16x32_bf16 v[82:85], v[176:179], v[204:207], v[82:85]
	v_mfma_f32_16x16x32_bf16 v[70:73], v[168:171], v[212:215], v[70:73]
	v_mfma_f32_16x16x32_bf16 v[66:69], v[176:179], v[212:215], v[66:69]
	v_mfma_f32_16x16x32_bf16 v[118:121], v[172:175], v[192:195], v[118:121]
	v_mfma_f32_16x16x32_bf16 v[114:117], v[180:183], v[192:195], v[114:117]
	v_mfma_f32_16x16x32_bf16 v[102:105], v[172:175], v[200:203], v[102:105]
	v_mfma_f32_16x16x32_bf16 v[98:101], v[180:183], v[200:203], v[98:101]
	v_mfma_f32_16x16x32_bf16 v[86:89], v[172:175], v[208:211], v[86:89]
	v_mfma_f32_16x16x32_bf16 v[82:85], v[180:183], v[208:211], v[82:85]
	v_mfma_f32_16x16x32_bf16 v[70:73], v[172:175], v[216:219], v[70:73]
	v_mfma_f32_16x16x32_bf16 v[66:69], v[180:183], v[216:219], v[66:69]
	s_barrier
	s_setprio 0
	s_add_i32 s73, s68, s47
	v_lshl_add_u64 v[184:185], s[40:41], 0, v[132:133]
	s_mov_b32 m0, s73
	ds_read_b128 v[188:191], v154 offset:16384
	ds_read_b128 v[192:195], v154 offset:17408
	ds_read_b128 v[196:199], v154 offset:18432
	ds_read_b128 v[200:203], v154 offset:19456
	ds_read_b128 v[204:207], v154 offset:20480
	ds_read_b128 v[208:211], v154 offset:21504
	ds_read_b128 v[212:215], v154 offset:22528
	ds_read_b128 v[216:219], v154 offset:23552
	global_load_lds_dwordx4 v[184:185], off
	s_add_i32 m0, s73, 0x2000
	s_add_u32 s74, s40, 0x100000
	v_lshl_add_u64 v[220:221], s[40:41], 0, v[136:137]
	s_addc_u32 s75, s41, 0
	s_add_i32 s73, s69, s47
	global_load_lds_dwordx4 v[220:221], off
	s_mov_b32 m0, s73
	v_lshl_add_u64 v[224:225], s[42:43], 0, v[134:135]
	global_load_lds_dwordx4 v132, s[74:75]
	s_add_i32 m0, s73, 0x2000
	s_nop 0
	global_load_lds_dwordx4 v136, s[74:75]
	v_lshl_add_u64 v[222:223], s[42:43], 0, v[130:131]
	s_mov_b32 m0, s49
	s_nop 0
	global_load_lds_dwordx4 v[222:223], off
	s_mov_b32 m0, s56
	s_nop 0
	global_load_lds_dwordx4 v[224:225], off
	s_waitcnt vmcnt(8)
	s_waitcnt lgkmcnt(0)
	s_setprio 1
	s_barrier
	v_mfma_f32_16x16x32_bf16 v[62:65], v[146:149], v[188:191], v[62:65]
	v_mfma_f32_16x16x32_bf16 v[58:61], v[160:163], v[188:191], v[58:61]
	v_mfma_f32_16x16x32_bf16 v[46:49], v[146:149], v[196:199], v[46:49]
	v_mfma_f32_16x16x32_bf16 v[42:45], v[160:163], v[196:199], v[42:45]
	v_mfma_f32_16x16x32_bf16 v[30:33], v[146:149], v[204:207], v[30:33]
	v_mfma_f32_16x16x32_bf16 v[26:29], v[160:163], v[204:207], v[26:29]
	v_mfma_f32_16x16x32_bf16 v[14:17], v[146:149], v[212:215], v[14:17]
	v_mfma_f32_16x16x32_bf16 v[10:13], v[160:163], v[212:215], v[10:13]
	v_mfma_f32_16x16x32_bf16 v[62:65], v[156:159], v[192:195], v[62:65]
	v_mfma_f32_16x16x32_bf16 v[58:61], v[164:167], v[192:195], v[58:61]
	v_mfma_f32_16x16x32_bf16 v[46:49], v[156:159], v[200:203], v[46:49]
	v_mfma_f32_16x16x32_bf16 v[42:45], v[164:167], v[200:203], v[42:45]
	v_mfma_f32_16x16x32_bf16 v[30:33], v[156:159], v[208:211], v[30:33]
	v_mfma_f32_16x16x32_bf16 v[26:29], v[164:167], v[208:211], v[26:29]
	v_mfma_f32_16x16x32_bf16 v[14:17], v[156:159], v[216:219], v[14:17]
	v_mfma_f32_16x16x32_bf16 v[10:13], v[164:167], v[216:219], v[10:13]
	v_mfma_f32_16x16x32_bf16 v[54:57], v[168:171], v[188:191], v[54:57]
	v_mfma_f32_16x16x32_bf16 v[50:53], v[176:179], v[188:191], v[50:53]
	v_mfma_f32_16x16x32_bf16 v[38:41], v[168:171], v[196:199], v[38:41]
	v_mfma_f32_16x16x32_bf16 v[34:37], v[176:179], v[196:199], v[34:37]
	v_mfma_f32_16x16x32_bf16 v[22:25], v[168:171], v[204:207], v[22:25]
	v_mfma_f32_16x16x32_bf16 v[18:21], v[176:179], v[204:207], v[18:21]
	v_mfma_f32_16x16x32_bf16 v[6:9], v[168:171], v[212:215], v[6:9]
	v_mfma_f32_16x16x32_bf16 v[2:5], v[176:179], v[212:215], v[2:5]
	v_mfma_f32_16x16x32_bf16 v[54:57], v[172:175], v[192:195], v[54:57]
	v_mfma_f32_16x16x32_bf16 v[50:53], v[180:183], v[192:195], v[50:53]
	v_mfma_f32_16x16x32_bf16 v[38:41], v[172:175], v[200:203], v[38:41]
	v_mfma_f32_16x16x32_bf16 v[34:37], v[180:183], v[200:203], v[34:37]
	v_mfma_f32_16x16x32_bf16 v[22:25], v[172:175], v[208:211], v[22:25]
	v_mfma_f32_16x16x32_bf16 v[18:21], v[180:183], v[208:211], v[18:21]
	v_mfma_f32_16x16x32_bf16 v[6:9], v[172:175], v[216:219], v[6:9]
	v_mfma_f32_16x16x32_bf16 v[2:5], v[180:183], v[216:219], v[2:5]
	s_barrier
	s_setprio 0
	s_add_i32 s73, 0, 0x18000
	s_add_i32 s74, 0, 0x1c000
	v_add_u32_e32 v164, s73, v150
	v_add_u32_e32 v180, s74, v150
	ds_read_b128 v[146:149], v164
	ds_read_b128 v[156:159], v164 offset:1024
	ds_read_b128 v[160:163], v164 offset:2048
	ds_read_b128 v[164:167], v164 offset:3072
	ds_read_b128 v[168:171], v180
	ds_read_b128 v[172:175], v180 offset:1024
	ds_read_b128 v[176:179], v180 offset:2048
	ds_read_b128 v[180:183], v180 offset:3072
	s_add_u32 s42, s42, 0x100000
	s_addc_u32 s43, s43, 0
	s_mov_b32 m0, s57
	ds_read_b128 v[188:191], v154 offset:32768
	ds_read_b128 v[192:195], v154 offset:33792
	ds_read_b128 v[196:199], v154 offset:34816
	ds_read_b128 v[200:203], v154 offset:35840
	ds_read_b128 v[204:207], v154 offset:36864
	ds_read_b128 v[208:211], v154 offset:37888
	ds_read_b128 v[212:215], v154 offset:38912
	ds_read_b128 v[216:219], v154 offset:39936
	global_load_lds_dwordx4 v130, s[42:43]
	s_mov_b32 m0, s60
	s_nop 0
	global_load_lds_dwordx4 v134, s[42:43]
	s_waitcnt vmcnt(8)
	s_waitcnt lgkmcnt(0)
	s_setprio 1
	s_barrier
	v_mfma_f32_16x16x32_bf16 v[126:129], v[146:149], v[188:191], v[126:129]
	v_mfma_f32_16x16x32_bf16 v[122:125], v[160:163], v[188:191], v[122:125]
	v_mfma_f32_16x16x32_bf16 v[110:113], v[146:149], v[196:199], v[110:113]
	v_mfma_f32_16x16x32_bf16 v[106:109], v[160:163], v[196:199], v[106:109]
	v_mfma_f32_16x16x32_bf16 v[94:97], v[146:149], v[204:207], v[94:97]
	v_mfma_f32_16x16x32_bf16 v[90:93], v[160:163], v[204:207], v[90:93]
	v_mfma_f32_16x16x32_bf16 v[78:81], v[146:149], v[212:215], v[78:81]
	v_mfma_f32_16x16x32_bf16 v[74:77], v[160:163], v[212:215], v[74:77]
	v_mfma_f32_16x16x32_bf16 v[126:129], v[156:159], v[192:195], v[126:129]
	v_mfma_f32_16x16x32_bf16 v[122:125], v[164:167], v[192:195], v[122:125]
	v_mfma_f32_16x16x32_bf16 v[110:113], v[156:159], v[200:203], v[110:113]
	v_mfma_f32_16x16x32_bf16 v[106:109], v[164:167], v[200:203], v[106:109]
	v_mfma_f32_16x16x32_bf16 v[94:97], v[156:159], v[208:211], v[94:97]
	v_mfma_f32_16x16x32_bf16 v[90:93], v[164:167], v[208:211], v[90:93]
	v_mfma_f32_16x16x32_bf16 v[78:81], v[156:159], v[216:219], v[78:81]
	v_mfma_f32_16x16x32_bf16 v[74:77], v[164:167], v[216:219], v[74:77]
	v_mfma_f32_16x16x32_bf16 v[118:121], v[168:171], v[188:191], v[118:121]
	v_mfma_f32_16x16x32_bf16 v[114:117], v[176:179], v[188:191], v[114:117]
	v_mfma_f32_16x16x32_bf16 v[102:105], v[168:171], v[196:199], v[102:105]
	v_mfma_f32_16x16x32_bf16 v[98:101], v[176:179], v[196:199], v[98:101]
	v_mfma_f32_16x16x32_bf16 v[86:89], v[168:171], v[204:207], v[86:89]
	v_mfma_f32_16x16x32_bf16 v[82:85], v[176:179], v[204:207], v[82:85]
	v_mfma_f32_16x16x32_bf16 v[70:73], v[168:171], v[212:215], v[70:73]
	v_mfma_f32_16x16x32_bf16 v[66:69], v[176:179], v[212:215], v[66:69]
	v_mfma_f32_16x16x32_bf16 v[118:121], v[172:175], v[192:195], v[118:121]
	v_mfma_f32_16x16x32_bf16 v[114:117], v[180:183], v[192:195], v[114:117]
	v_mfma_f32_16x16x32_bf16 v[102:105], v[172:175], v[200:203], v[102:105]
	v_mfma_f32_16x16x32_bf16 v[98:101], v[180:183], v[200:203], v[98:101]
	v_mfma_f32_16x16x32_bf16 v[86:89], v[172:175], v[208:211], v[86:89]
	v_mfma_f32_16x16x32_bf16 v[82:85], v[180:183], v[208:211], v[82:85]
	v_mfma_f32_16x16x32_bf16 v[70:73], v[172:175], v[216:219], v[70:73]
	v_mfma_f32_16x16x32_bf16 v[66:69], v[180:183], v[216:219], v[66:69]
	s_barrier
	s_setprio 0
	s_add_i32 s42, s73, s47
	v_lshl_add_u64 v[184:185], v[184:185], 0, s[22:23]
	s_mov_b32 m0, s42
	ds_read_b128 v[188:191], v154 offset:49152
	ds_read_b128 v[192:195], v154 offset:50176
	ds_read_b128 v[196:199], v154 offset:51200
	ds_read_b128 v[200:203], v154 offset:52224
	ds_read_b128 v[204:207], v154 offset:53248
	ds_read_b128 v[208:211], v154 offset:54272
	ds_read_b128 v[212:215], v154 offset:55296
	ds_read_b128 v[216:219], v154 offset:56320
	global_load_lds_dwordx4 v[184:185], off
	s_add_i32 m0, s42, 0x2000
	s_add_u32 s40, s40, 0x100080
	v_lshl_add_u64 v[184:185], v[220:221], 0, s[22:23]
	s_addc_u32 s41, s41, 0
	s_add_i32 s42, s74, s47
	global_load_lds_dwordx4 v[184:185], off
	s_mov_b32 m0, s42
	s_nop 0
	global_load_lds_dwordx4 v132, s[40:41]
	s_add_i32 m0, s42, 0x2000
	s_nop 0
	global_load_lds_dwordx4 v136, s[40:41]
	v_lshl_add_u64 v[184:185], v[222:223], 0, s[22:23]
	s_mov_b32 m0, s63
	s_nop 0
	global_load_lds_dwordx4 v[184:185], off
	v_lshl_add_u64 v[184:185], v[224:225], 0, s[22:23]
	s_mov_b32 m0, s64
	s_nop 0
	global_load_lds_dwordx4 v[184:185], off
	s_waitcnt vmcnt(8)
	s_waitcnt lgkmcnt(0)
	s_setprio 1
	s_barrier
	v_mfma_f32_16x16x32_bf16 v[62:65], v[146:149], v[188:191], v[62:65]
	v_mfma_f32_16x16x32_bf16 v[58:61], v[160:163], v[188:191], v[58:61]
	v_mfma_f32_16x16x32_bf16 v[46:49], v[146:149], v[196:199], v[46:49]
	v_mfma_f32_16x16x32_bf16 v[42:45], v[160:163], v[196:199], v[42:45]
	v_mfma_f32_16x16x32_bf16 v[30:33], v[146:149], v[204:207], v[30:33]
	v_mfma_f32_16x16x32_bf16 v[26:29], v[160:163], v[204:207], v[26:29]
	v_mfma_f32_16x16x32_bf16 v[14:17], v[146:149], v[212:215], v[14:17]
	v_mfma_f32_16x16x32_bf16 v[10:13], v[160:163], v[212:215], v[10:13]
	v_mfma_f32_16x16x32_bf16 v[62:65], v[156:159], v[192:195], v[62:65]
	v_mfma_f32_16x16x32_bf16 v[58:61], v[164:167], v[192:195], v[58:61]
	v_mfma_f32_16x16x32_bf16 v[46:49], v[156:159], v[200:203], v[46:49]
	v_mfma_f32_16x16x32_bf16 v[42:45], v[164:167], v[200:203], v[42:45]
	v_mfma_f32_16x16x32_bf16 v[30:33], v[156:159], v[208:211], v[30:33]
	v_mfma_f32_16x16x32_bf16 v[26:29], v[164:167], v[208:211], v[26:29]
	v_mfma_f32_16x16x32_bf16 v[14:17], v[156:159], v[216:219], v[14:17]
	v_mfma_f32_16x16x32_bf16 v[10:13], v[164:167], v[216:219], v[10:13]
	v_mfma_f32_16x16x32_bf16 v[54:57], v[168:171], v[188:191], v[54:57]
	v_mfma_f32_16x16x32_bf16 v[50:53], v[176:179], v[188:191], v[50:53]
	v_mfma_f32_16x16x32_bf16 v[38:41], v[168:171], v[196:199], v[38:41]
	v_mfma_f32_16x16x32_bf16 v[34:37], v[176:179], v[196:199], v[34:37]
	v_mfma_f32_16x16x32_bf16 v[22:25], v[168:171], v[204:207], v[22:25]
	v_mfma_f32_16x16x32_bf16 v[18:21], v[176:179], v[204:207], v[18:21]
	v_mfma_f32_16x16x32_bf16 v[6:9], v[168:171], v[212:215], v[6:9]
	v_mfma_f32_16x16x32_bf16 v[2:5], v[176:179], v[212:215], v[2:5]
	v_mfma_f32_16x16x32_bf16 v[54:57], v[172:175], v[192:195], v[54:57]
	v_mfma_f32_16x16x32_bf16 v[50:53], v[180:183], v[192:195], v[50:53]
	v_mfma_f32_16x16x32_bf16 v[38:41], v[172:175], v[200:203], v[38:41]
	v_mfma_f32_16x16x32_bf16 v[34:37], v[180:183], v[200:203], v[34:37]
	v_mfma_f32_16x16x32_bf16 v[22:25], v[172:175], v[208:211], v[22:25]
	v_mfma_f32_16x16x32_bf16 v[18:21], v[180:183], v[208:211], v[18:21]
	v_mfma_f32_16x16x32_bf16 v[6:9], v[172:175], v[216:219], v[6:9]
	v_mfma_f32_16x16x32_bf16 v[2:5], v[180:183], v[216:219], v[2:5]
	s_barrier
	s_setprio 0
	s_add_i32 s72, s72, 2
	s_add_u32 s70, s70, 0x100
	s_addc_u32 s71, s71, 0
	s_add_u32 s38, s38, 0x100
	s_addc_u32 s39, s39, 0
	s_cmp_gt_u32 s72, 61
	s_cbranch_scc0 .LBB0_1281
	s_and_b64 vcc, exec, s[24:25]
	s_cbranch_vccz .LBB0_1284
	s_barrier

.LBB0_1368:
	ds_read_b128 v[146:149], v196
	ds_read_b128 v[150:153], v196 offset:1024
	ds_read_b128 v[154:157], v196 offset:2048
	ds_read_b128 v[158:161], v196 offset:3072
	ds_read_b128 v[162:165], v197
	ds_read_b128 v[166:169], v197 offset:1024
	ds_read_b128 v[170:173], v197 offset:2048
	ds_read_b128 v[174:177], v197 offset:3072
	s_add_u32 s34, s30, 0xfff00080
	s_addc_u32 s35, s31, -1
	s_cmp_eq_u32 s71, 60
	s_cselect_b32 s37, s11, s35
	s_cselect_b32 s36, s27, s34
	s_cselect_b32 s35, s25, s70
	s_cselect_b32 s34, s24, s69
	s_add_i32 m0, s42, 0xc000
	ds_read_b128 v[202:205], v198
	ds_read_b128 v[206:209], v198 offset:1024
	ds_read_b128 v[210:213], v198 offset:2048
	ds_read_b128 v[214:217], v198 offset:3072
	ds_read_b128 v[218:221], v198 offset:4096
	ds_read_b128 v[222:225], v198 offset:5120
	ds_read_b128 v[226:229], v198 offset:6144
	ds_read_b128 v[230:233], v198 offset:7168
	global_load_lds_dwordx4 v140, s[30:31]
	s_add_i32 m0, s42, 0xe000
	s_nop 0
	global_load_lds_dwordx4 v138, s[30:31]
	s_waitcnt vmcnt(8)
	s_waitcnt lgkmcnt(0)
	s_setprio 1
	s_barrier
	v_mfma_f32_16x16x32_bf16 v[126:129], v[146:149], v[202:205], v[126:129]
	v_mfma_f32_16x16x32_bf16 v[122:125], v[154:157], v[202:205], v[122:125]
	v_mfma_f32_16x16x32_bf16 v[110:113], v[146:149], v[210:213], v[110:113]
	v_mfma_f32_16x16x32_bf16 v[106:109], v[154:157], v[210:213], v[106:109]
	v_mfma_f32_16x16x32_bf16 v[94:97], v[146:149], v[218:221], v[94:97]
	v_mfma_f32_16x16x32_bf16 v[90:93], v[154:157], v[218:221], v[90:93]
	v_mfma_f32_16x16x32_bf16 v[78:81], v[146:149], v[226:229], v[78:81]
	v_mfma_f32_16x16x32_bf16 v[74:77], v[154:157], v[226:229], v[74:77]
	v_mfma_f32_16x16x32_bf16 v[126:129], v[150:153], v[206:209], v[126:129]
	v_mfma_f32_16x16x32_bf16 v[122:125], v[158:161], v[206:209], v[122:125]
	v_mfma_f32_16x16x32_bf16 v[110:113], v[150:153], v[214:217], v[110:113]
	v_mfma_f32_16x16x32_bf16 v[106:109], v[158:161], v[214:217], v[106:109]
	v_mfma_f32_16x16x32_bf16 v[94:97], v[150:153], v[222:225], v[94:97]
	v_mfma_f32_16x16x32_bf16 v[90:93], v[158:161], v[222:225], v[90:93]
	v_mfma_f32_16x16x32_bf16 v[78:81], v[150:153], v[230:233], v[78:81]
	v_mfma_f32_16x16x32_bf16 v[74:77], v[158:161], v[230:233], v[74:77]
	v_mfma_f32_16x16x32_bf16 v[118:121], v[162:165], v[202:205], v[118:121]
	v_mfma_f32_16x16x32_bf16 v[114:117], v[170:173], v[202:205], v[114:117]
	v_mfma_f32_16x16x32_bf16 v[102:105], v[162:165], v[210:213], v[102:105]
	v_mfma_f32_16x16x32_bf16 v[98:101], v[170:173], v[210:213], v[98:101]
	v_mfma_f32_16x16x32_bf16 v[86:89], v[162:165], v[218:221], v[86:89]
	v_mfma_f32_16x16x32_bf16 v[82:85], v[170:173], v[218:221], v[82:85]
	v_mfma_f32_16x16x32_bf16 v[70:73], v[162:165], v[226:229], v[70:73]
	v_mfma_f32_16x16x32_bf16 v[66:69], v[170:173], v[226:229], v[66:69]
	v_mfma_f32_16x16x32_bf16 v[118:121], v[166:169], v[206:209], v[118:121]
	v_mfma_f32_16x16x32_bf16 v[114:117], v[174:177], v[206:209], v[114:117]
	v_mfma_f32_16x16x32_bf16 v[102:105], v[166:169], v[214:217], v[102:105]
	v_mfma_f32_16x16x32_bf16 v[98:101], v[174:177], v[214:217], v[98:101]
	v_mfma_f32_16x16x32_bf16 v[86:89], v[166:169], v[222:225], v[86:89]
	v_mfma_f32_16x16x32_bf16 v[82:85], v[174:177], v[222:225], v[82:85]
	v_mfma_f32_16x16x32_bf16 v[70:73], v[166:169], v[230:233], v[70:73]
	v_mfma_f32_16x16x32_bf16 v[66:69], v[174:177], v[230:233], v[66:69]
	s_barrier
	s_setprio 0
	s_add_i32 s72, s62, s41
	v_lshl_add_u64 v[234:235], s[34:35], 0, v[134:135]
	s_mov_b32 m0, s72
	ds_read_b128 v[202:205], v198 offset:16384
	ds_read_b128 v[206:209], v198 offset:17408
	ds_read_b128 v[210:213], v198 offset:18432
	ds_read_b128 v[214:217], v198 offset:19456
	ds_read_b128 v[218:221], v198 offset:20480
	ds_read_b128 v[222:225], v198 offset:21504
	ds_read_b128 v[226:229], v198 offset:22528
	ds_read_b128 v[230:233], v198 offset:23552
	global_load_lds_dwordx4 v[234:235], off
	s_add_i32 m0, s72, 0x2000
	s_add_u32 s72, s34, 0x100000
	v_lshl_add_u64 v[236:237], s[34:35], 0, v[130:131]
	s_addc_u32 s73, s35, 0
	s_add_i32 s74, s63, s41
	global_load_lds_dwordx4 v[236:237], off
	s_mov_b32 m0, s74
	v_lshl_add_u64 v[240:241], s[36:37], 0, v[132:133]
	global_load_lds_dwordx4 v134, s[72:73]
	s_add_i32 m0, s74, 0x2000
	s_nop 0
	global_load_lds_dwordx4 v130, s[72:73]
	v_lshl_add_u64 v[238:239], s[36:37], 0, v[136:137]
	s_mov_b32 m0, s42
	s_nop 0
	global_load_lds_dwordx4 v[238:239], off
	s_mov_b32 m0, s43
	s_nop 0
	global_load_lds_dwordx4 v[240:241], off
	s_waitcnt vmcnt(8)
	s_waitcnt lgkmcnt(0)
	s_setprio 1
	s_barrier
	v_mfma_f32_16x16x32_bf16 v[62:65], v[146:149], v[202:205], v[62:65]
	v_mfma_f32_16x16x32_bf16 v[58:61], v[154:157], v[202:205], v[58:61]
	v_mfma_f32_16x16x32_bf16 v[46:49], v[146:149], v[210:213], v[46:49]
	v_mfma_f32_16x16x32_bf16 v[42:45], v[154:157], v[210:213], v[42:45]
	v_mfma_f32_16x16x32_bf16 v[30:33], v[146:149], v[218:221], v[30:33]
	v_mfma_f32_16x16x32_bf16 v[26:29], v[154:157], v[218:221], v[26:29]
	v_mfma_f32_16x16x32_bf16 v[14:17], v[146:149], v[226:229], v[14:17]
	v_mfma_f32_16x16x32_bf16 v[10:13], v[154:157], v[226:229], v[10:13]
	v_mfma_f32_16x16x32_bf16 v[62:65], v[150:153], v[206:209], v[62:65]
	v_mfma_f32_16x16x32_bf16 v[58:61], v[158:161], v[206:209], v[58:61]
	v_mfma_f32_16x16x32_bf16 v[46:49], v[150:153], v[214:217], v[46:49]
	v_mfma_f32_16x16x32_bf16 v[42:45], v[158:161], v[214:217], v[42:45]
	v_mfma_f32_16x16x32_bf16 v[30:33], v[150:153], v[222:225], v[30:33]
	v_mfma_f32_16x16x32_bf16 v[26:29], v[158:161], v[222:225], v[26:29]
	v_mfma_f32_16x16x32_bf16 v[14:17], v[150:153], v[230:233], v[14:17]
	v_mfma_f32_16x16x32_bf16 v[10:13], v[158:161], v[230:233], v[10:13]
	v_mfma_f32_16x16x32_bf16 v[54:57], v[162:165], v[202:205], v[54:57]
	v_mfma_f32_16x16x32_bf16 v[50:53], v[170:173], v[202:205], v[50:53]
	v_mfma_f32_16x16x32_bf16 v[38:41], v[162:165], v[210:213], v[38:41]
	v_mfma_f32_16x16x32_bf16 v[34:37], v[170:173], v[210:213], v[34:37]
	v_mfma_f32_16x16x32_bf16 v[22:25], v[162:165], v[218:221], v[22:25]
	v_mfma_f32_16x16x32_bf16 v[18:21], v[170:173], v[218:221], v[18:21]
	v_mfma_f32_16x16x32_bf16 v[6:9], v[162:165], v[226:229], v[6:9]
	v_mfma_f32_16x16x32_bf16 v[2:5], v[170:173], v[226:229], v[2:5]
	v_mfma_f32_16x16x32_bf16 v[54:57], v[166:169], v[206:209], v[54:57]
	v_mfma_f32_16x16x32_bf16 v[50:53], v[174:177], v[206:209], v[50:53]
	v_mfma_f32_16x16x32_bf16 v[38:41], v[166:169], v[214:217], v[38:41]
	v_mfma_f32_16x16x32_bf16 v[34:37], v[174:177], v[214:217], v[34:37]
	v_mfma_f32_16x16x32_bf16 v[22:25], v[166:169], v[222:225], v[22:25]
	v_mfma_f32_16x16x32_bf16 v[18:21], v[174:177], v[222:225], v[18:21]
	v_mfma_f32_16x16x32_bf16 v[6:9], v[166:169], v[230:233], v[6:9]
	v_mfma_f32_16x16x32_bf16 v[2:5], v[174:177], v[230:233], v[2:5]
	s_barrier
	s_setprio 0
	s_add_i32 s72, 0, 0x18000
	s_add_i32 s73, 0, 0x1c000
	v_add_u32_e32 v158, s72, v178
	v_add_u32_e32 v174, s73, v178
	ds_read_b128 v[146:149], v158
	ds_read_b128 v[150:153], v158 offset:1024
	ds_read_b128 v[154:157], v158 offset:2048
	ds_read_b128 v[158:161], v158 offset:3072
	ds_read_b128 v[162:165], v174
	ds_read_b128 v[166:169], v174 offset:1024
	ds_read_b128 v[170:173], v174 offset:2048
	ds_read_b128 v[174:177], v174 offset:3072
	s_add_u32 s36, s36, 0x100000
	s_addc_u32 s37, s37, 0
	s_mov_b32 m0, s44
	ds_read_b128 v[202:205], v198 offset:32768
	ds_read_b128 v[206:209], v198 offset:33792
	ds_read_b128 v[210:213], v198 offset:34816
	ds_read_b128 v[214:217], v198 offset:35840
	ds_read_b128 v[218:221], v198 offset:36864
	ds_read_b128 v[222:225], v198 offset:37888
	ds_read_b128 v[226:229], v198 offset:38912
	ds_read_b128 v[230:233], v198 offset:39936
	global_load_lds_dwordx4 v136, s[36:37]
	s_mov_b32 m0, s45
	s_nop 0
	global_load_lds_dwordx4 v132, s[36:37]
	s_waitcnt vmcnt(8)
	s_waitcnt lgkmcnt(0)
	s_setprio 1
	s_barrier
	v_mfma_f32_16x16x32_bf16 v[126:129], v[146:149], v[202:205], v[126:129]
	v_mfma_f32_16x16x32_bf16 v[122:125], v[154:157], v[202:205], v[122:125]
	v_mfma_f32_16x16x32_bf16 v[110:113], v[146:149], v[210:213], v[110:113]
	v_mfma_f32_16x16x32_bf16 v[106:109], v[154:157], v[210:213], v[106:109]
	v_mfma_f32_16x16x32_bf16 v[94:97], v[146:149], v[218:221], v[94:97]
	v_mfma_f32_16x16x32_bf16 v[90:93], v[154:157], v[218:221], v[90:93]
	v_mfma_f32_16x16x32_bf16 v[78:81], v[146:149], v[226:229], v[78:81]
	v_mfma_f32_16x16x32_bf16 v[74:77], v[154:157], v[226:229], v[74:77]
	v_mfma_f32_16x16x32_bf16 v[126:129], v[150:153], v[206:209], v[126:129]
	v_mfma_f32_16x16x32_bf16 v[122:125], v[158:161], v[206:209], v[122:125]
	v_mfma_f32_16x16x32_bf16 v[110:113], v[150:153], v[214:217], v[110:113]
	v_mfma_f32_16x16x32_bf16 v[106:109], v[158:161], v[214:217], v[106:109]
	v_mfma_f32_16x16x32_bf16 v[94:97], v[150:153], v[222:225], v[94:97]
	v_mfma_f32_16x16x32_bf16 v[90:93], v[158:161], v[222:225], v[90:93]
	v_mfma_f32_16x16x32_bf16 v[78:81], v[150:153], v[230:233], v[78:81]
	v_mfma_f32_16x16x32_bf16 v[74:77], v[158:161], v[230:233], v[74:77]
	v_mfma_f32_16x16x32_bf16 v[118:121], v[162:165], v[202:205], v[118:121]
	v_mfma_f32_16x16x32_bf16 v[114:117], v[170:173], v[202:205], v[114:117]
	v_mfma_f32_16x16x32_bf16 v[102:105], v[162:165], v[210:213], v[102:105]
	v_mfma_f32_16x16x32_bf16 v[98:101], v[170:173], v[210:213], v[98:101]
	v_mfma_f32_16x16x32_bf16 v[86:89], v[162:165], v[218:221], v[86:89]
	v_mfma_f32_16x16x32_bf16 v[82:85], v[170:173], v[218:221], v[82:85]
	v_mfma_f32_16x16x32_bf16 v[70:73], v[162:165], v[226:229], v[70:73]
	v_mfma_f32_16x16x32_bf16 v[66:69], v[170:173], v[226:229], v[66:69]
	v_mfma_f32_16x16x32_bf16 v[118:121], v[166:169], v[206:209], v[118:121]
	v_mfma_f32_16x16x32_bf16 v[114:117], v[174:177], v[206:209], v[114:117]
	v_mfma_f32_16x16x32_bf16 v[102:105], v[166:169], v[214:217], v[102:105]
	v_mfma_f32_16x16x32_bf16 v[98:101], v[174:177], v[214:217], v[98:101]
	v_mfma_f32_16x16x32_bf16 v[86:89], v[166:169], v[222:225], v[86:89]
	v_mfma_f32_16x16x32_bf16 v[82:85], v[174:177], v[222:225], v[82:85]
	v_mfma_f32_16x16x32_bf16 v[70:73], v[166:169], v[230:233], v[70:73]
	v_mfma_f32_16x16x32_bf16 v[66:69], v[174:177], v[230:233], v[66:69]
	s_barrier
	s_setprio 0
	s_add_i32 s36, s72, s41
	v_lshl_add_u64 v[234:235], v[234:235], 0, s[20:21]
	s_mov_b32 m0, s36
	ds_read_b128 v[202:205], v198 offset:49152
	ds_read_b128 v[206:209], v198 offset:50176
	ds_read_b128 v[210:213], v198 offset:51200
	ds_read_b128 v[214:217], v198 offset:52224
	ds_read_b128 v[218:221], v198 offset:53248
	ds_read_b128 v[222:225], v198 offset:54272
	ds_read_b128 v[226:229], v198 offset:55296
	ds_read_b128 v[230:233], v198 offset:56320
	global_load_lds_dwordx4 v[234:235], off
	s_add_i32 m0, s36, 0x2000
	s_add_u32 s34, s34, 0x100080
	v_lshl_add_u64 v[234:235], v[236:237], 0, s[20:21]
	s_addc_u32 s35, s35, 0
	s_add_i32 s36, s73, s41
	global_load_lds_dwordx4 v[234:235], off
	s_mov_b32 m0, s36
	s_nop 0
	global_load_lds_dwordx4 v134, s[34:35]
	s_add_i32 m0, s36, 0x2000
	s_nop 0
	global_load_lds_dwordx4 v130, s[34:35]
	v_lshl_add_u64 v[234:235], v[238:239], 0, s[20:21]
	s_mov_b32 m0, s56
	s_nop 0
	global_load_lds_dwordx4 v[234:235], off
	v_lshl_add_u64 v[234:235], v[240:241], 0, s[20:21]
	s_mov_b32 m0, s57
	s_nop 0
	global_load_lds_dwordx4 v[234:235], off
	s_waitcnt vmcnt(8)
	s_waitcnt lgkmcnt(0)
	s_setprio 1
	s_barrier
	v_mfma_f32_16x16x32_bf16 v[62:65], v[146:149], v[202:205], v[62:65]
	v_mfma_f32_16x16x32_bf16 v[58:61], v[154:157], v[202:205], v[58:61]
	v_mfma_f32_16x16x32_bf16 v[46:49], v[146:149], v[210:213], v[46:49]
	v_mfma_f32_16x16x32_bf16 v[42:45], v[154:157], v[210:213], v[42:45]
	v_mfma_f32_16x16x32_bf16 v[30:33], v[146:149], v[218:221], v[30:33]
	v_mfma_f32_16x16x32_bf16 v[26:29], v[154:157], v[218:221], v[26:29]
	v_mfma_f32_16x16x32_bf16 v[14:17], v[146:149], v[226:229], v[14:17]
	v_mfma_f32_16x16x32_bf16 v[10:13], v[154:157], v[226:229], v[10:13]
	v_mfma_f32_16x16x32_bf16 v[62:65], v[150:153], v[206:209], v[62:65]
	v_mfma_f32_16x16x32_bf16 v[58:61], v[158:161], v[206:209], v[58:61]
	v_mfma_f32_16x16x32_bf16 v[46:49], v[150:153], v[214:217], v[46:49]
	v_mfma_f32_16x16x32_bf16 v[42:45], v[158:161], v[214:217], v[42:45]
	v_mfma_f32_16x16x32_bf16 v[30:33], v[150:153], v[222:225], v[30:33]
	v_mfma_f32_16x16x32_bf16 v[26:29], v[158:161], v[222:225], v[26:29]
	v_mfma_f32_16x16x32_bf16 v[14:17], v[150:153], v[230:233], v[14:17]
	v_mfma_f32_16x16x32_bf16 v[10:13], v[158:161], v[230:233], v[10:13]
	v_mfma_f32_16x16x32_bf16 v[54:57], v[162:165], v[202:205], v[54:57]
	v_mfma_f32_16x16x32_bf16 v[50:53], v[170:173], v[202:205], v[50:53]
	v_mfma_f32_16x16x32_bf16 v[38:41], v[162:165], v[210:213], v[38:41]
	v_mfma_f32_16x16x32_bf16 v[34:37], v[170:173], v[210:213], v[34:37]
	v_mfma_f32_16x16x32_bf16 v[22:25], v[162:165], v[218:221], v[22:25]
	v_mfma_f32_16x16x32_bf16 v[18:21], v[170:173], v[218:221], v[18:21]
	v_mfma_f32_16x16x32_bf16 v[6:9], v[162:165], v[226:229], v[6:9]
	v_mfma_f32_16x16x32_bf16 v[2:5], v[170:173], v[226:229], v[2:5]
	v_mfma_f32_16x16x32_bf16 v[54:57], v[166:169], v[206:209], v[54:57]
	v_mfma_f32_16x16x32_bf16 v[50:53], v[174:177], v[206:209], v[50:53]
	v_mfma_f32_16x16x32_bf16 v[38:41], v[166:169], v[214:217], v[38:41]
	v_mfma_f32_16x16x32_bf16 v[34:37], v[174:177], v[214:217], v[34:37]
	v_mfma_f32_16x16x32_bf16 v[22:25], v[166:169], v[222:225], v[22:25]
	v_mfma_f32_16x16x32_bf16 v[18:21], v[174:177], v[222:225], v[18:21]
	v_mfma_f32_16x16x32_bf16 v[6:9], v[166:169], v[230:233], v[6:9]
	v_mfma_f32_16x16x32_bf16 v[2:5], v[174:177], v[230:233], v[2:5]
	s_barrier
	s_setprio 0
	s_add_i32 s71, s71, 2
	s_add_u32 s69, s69, 0x100
	s_addc_u32 s70, s70, 0
	s_add_u32 s30, s30, 0x100
	s_addc_u32 s31, s31, 0
	s_cmp_gt_u32 s71, 61
	s_cbranch_scc0 .LBB0_1368
	s_and_b64 vcc, exec, s[22:23]
	s_cbranch_vccz .LBB0_1371
	s_barrier

.LBB0_1483:
	ds_read_b128 v[146:149], v152
	ds_read_b128 v[156:159], v152 offset:1024
	ds_read_b128 v[160:163], v152 offset:2048
	ds_read_b128 v[164:167], v152 offset:3072
	ds_read_b128 v[168:171], v153
	ds_read_b128 v[172:175], v153 offset:1024
	ds_read_b128 v[176:179], v153 offset:2048
	ds_read_b128 v[180:183], v153 offset:3072
	s_add_u32 s38, s10, 0xfffc0080
	s_addc_u32 s39, s11, -1
	s_cmp_eq_u32 s66, 12
	s_cselect_b32 s41, s25, s39
	s_cselect_b32 s40, s27, s38
	s_cselect_b32 s39, s29, s65
	s_cselect_b32 s38, s28, s64
	s_add_i32 m0, s35, 0xc000
	ds_read_b128 v[188:191], v154
	ds_read_b128 v[192:195], v154 offset:1024
	ds_read_b128 v[196:199], v154 offset:2048
	ds_read_b128 v[200:203], v154 offset:3072
	ds_read_b128 v[204:207], v154 offset:4096
	ds_read_b128 v[208:211], v154 offset:5120
	ds_read_b128 v[212:215], v154 offset:6144
	ds_read_b128 v[216:219], v154 offset:7168
	global_load_lds_dwordx4 v140, s[10:11]
	s_add_i32 m0, s35, 0xe000
	s_nop 0
	global_load_lds_dwordx4 v138, s[10:11]
	s_waitcnt vmcnt(8)
	s_waitcnt lgkmcnt(0)
	s_setprio 1
	s_barrier
	v_mfma_f32_16x16x32_bf16 v[126:129], v[146:149], v[188:191], v[126:129]
	v_mfma_f32_16x16x32_bf16 v[122:125], v[160:163], v[188:191], v[122:125]
	v_mfma_f32_16x16x32_bf16 v[110:113], v[146:149], v[196:199], v[110:113]
	v_mfma_f32_16x16x32_bf16 v[106:109], v[160:163], v[196:199], v[106:109]
	v_mfma_f32_16x16x32_bf16 v[94:97], v[146:149], v[204:207], v[94:97]
	v_mfma_f32_16x16x32_bf16 v[90:93], v[160:163], v[204:207], v[90:93]
	v_mfma_f32_16x16x32_bf16 v[78:81], v[146:149], v[212:215], v[78:81]
	v_mfma_f32_16x16x32_bf16 v[74:77], v[160:163], v[212:215], v[74:77]
	v_mfma_f32_16x16x32_bf16 v[126:129], v[156:159], v[192:195], v[126:129]
	v_mfma_f32_16x16x32_bf16 v[122:125], v[164:167], v[192:195], v[122:125]
	v_mfma_f32_16x16x32_bf16 v[110:113], v[156:159], v[200:203], v[110:113]
	v_mfma_f32_16x16x32_bf16 v[106:109], v[164:167], v[200:203], v[106:109]
	v_mfma_f32_16x16x32_bf16 v[94:97], v[156:159], v[208:211], v[94:97]
	v_mfma_f32_16x16x32_bf16 v[90:93], v[164:167], v[208:211], v[90:93]
	v_mfma_f32_16x16x32_bf16 v[78:81], v[156:159], v[216:219], v[78:81]
	v_mfma_f32_16x16x32_bf16 v[74:77], v[164:167], v[216:219], v[74:77]
	v_mfma_f32_16x16x32_bf16 v[118:121], v[168:171], v[188:191], v[118:121]
	v_mfma_f32_16x16x32_bf16 v[114:117], v[176:179], v[188:191], v[114:117]
	v_mfma_f32_16x16x32_bf16 v[102:105], v[168:171], v[196:199], v[102:105]
	v_mfma_f32_16x16x32_bf16 v[98:101], v[176:179], v[196:199], v[98:101]
	v_mfma_f32_16x16x32_bf16 v[86:89], v[168:171], v[204:207], v[86:89]
	v_mfma_f32_16x16x32_bf16 v[82:85], v[176:179], v[204:207], v[82:85]
	v_mfma_f32_16x16x32_bf16 v[70:73], v[168:171], v[212:215], v[70:73]
	v_mfma_f32_16x16x32_bf16 v[66:69], v[176:179], v[212:215], v[66:69]
	v_mfma_f32_16x16x32_bf16 v[118:121], v[172:175], v[192:195], v[118:121]
	v_mfma_f32_16x16x32_bf16 v[114:117], v[180:183], v[192:195], v[114:117]
	v_mfma_f32_16x16x32_bf16 v[102:105], v[172:175], v[200:203], v[102:105]
	v_mfma_f32_16x16x32_bf16 v[98:101], v[180:183], v[200:203], v[98:101]
	v_mfma_f32_16x16x32_bf16 v[86:89], v[172:175], v[208:211], v[86:89]
	v_mfma_f32_16x16x32_bf16 v[82:85], v[180:183], v[208:211], v[82:85]
	v_mfma_f32_16x16x32_bf16 v[70:73], v[172:175], v[216:219], v[70:73]
	v_mfma_f32_16x16x32_bf16 v[66:69], v[180:183], v[216:219], v[66:69]
	s_barrier
	s_setprio 0
	s_add_i32 s67, s62, s45
	v_lshl_add_u64 v[184:185], s[38:39], 0, v[132:133]
	s_mov_b32 m0, s67
	ds_read_b128 v[188:191], v154 offset:16384
	ds_read_b128 v[192:195], v154 offset:17408
	ds_read_b128 v[196:199], v154 offset:18432
	ds_read_b128 v[200:203], v154 offset:19456
	ds_read_b128 v[204:207], v154 offset:20480
	ds_read_b128 v[208:211], v154 offset:21504
	ds_read_b128 v[212:215], v154 offset:22528
	ds_read_b128 v[216:219], v154 offset:23552
	global_load_lds_dwordx4 v[184:185], off
	s_add_i32 m0, s67, 0x2000
	s_add_u32 s68, s38, 0x40000
	v_lshl_add_u64 v[220:221], s[38:39], 0, v[136:137]
	s_addc_u32 s69, s39, 0
	s_add_i32 s67, s63, s45
	global_load_lds_dwordx4 v[220:221], off
	s_mov_b32 m0, s67
	v_lshl_add_u64 v[224:225], s[40:41], 0, v[134:135]
	global_load_lds_dwordx4 v132, s[68:69]
	s_add_i32 m0, s67, 0x2000
	s_nop 0
	global_load_lds_dwordx4 v136, s[68:69]
	v_lshl_add_u64 v[222:223], s[40:41], 0, v[130:131]
	s_mov_b32 m0, s35
	s_nop 0
	global_load_lds_dwordx4 v[222:223], off
	s_mov_b32 m0, s37
	s_nop 0
	global_load_lds_dwordx4 v[224:225], off
	s_waitcnt vmcnt(8)
	s_waitcnt lgkmcnt(0)
	s_setprio 1
	s_barrier
	v_mfma_f32_16x16x32_bf16 v[62:65], v[146:149], v[188:191], v[62:65]
	v_mfma_f32_16x16x32_bf16 v[58:61], v[160:163], v[188:191], v[58:61]
	v_mfma_f32_16x16x32_bf16 v[46:49], v[146:149], v[196:199], v[46:49]
	v_mfma_f32_16x16x32_bf16 v[42:45], v[160:163], v[196:199], v[42:45]
	v_mfma_f32_16x16x32_bf16 v[30:33], v[146:149], v[204:207], v[30:33]
	v_mfma_f32_16x16x32_bf16 v[26:29], v[160:163], v[204:207], v[26:29]
	v_mfma_f32_16x16x32_bf16 v[14:17], v[146:149], v[212:215], v[14:17]
	v_mfma_f32_16x16x32_bf16 v[10:13], v[160:163], v[212:215], v[10:13]
	v_mfma_f32_16x16x32_bf16 v[62:65], v[156:159], v[192:195], v[62:65]
	v_mfma_f32_16x16x32_bf16 v[58:61], v[164:167], v[192:195], v[58:61]
	v_mfma_f32_16x16x32_bf16 v[46:49], v[156:159], v[200:203], v[46:49]
	v_mfma_f32_16x16x32_bf16 v[42:45], v[164:167], v[200:203], v[42:45]
	v_mfma_f32_16x16x32_bf16 v[30:33], v[156:159], v[208:211], v[30:33]
	v_mfma_f32_16x16x32_bf16 v[26:29], v[164:167], v[208:211], v[26:29]
	v_mfma_f32_16x16x32_bf16 v[14:17], v[156:159], v[216:219], v[14:17]
	v_mfma_f32_16x16x32_bf16 v[10:13], v[164:167], v[216:219], v[10:13]
	v_mfma_f32_16x16x32_bf16 v[54:57], v[168:171], v[188:191], v[54:57]
	v_mfma_f32_16x16x32_bf16 v[50:53], v[176:179], v[188:191], v[50:53]
	v_mfma_f32_16x16x32_bf16 v[38:41], v[168:171], v[196:199], v[38:41]
	v_mfma_f32_16x16x32_bf16 v[34:37], v[176:179], v[196:199], v[34:37]
	v_mfma_f32_16x16x32_bf16 v[22:25], v[168:171], v[204:207], v[22:25]
	v_mfma_f32_16x16x32_bf16 v[18:21], v[176:179], v[204:207], v[18:21]
	v_mfma_f32_16x16x32_bf16 v[6:9], v[168:171], v[212:215], v[6:9]
	v_mfma_f32_16x16x32_bf16 v[2:5], v[176:179], v[212:215], v[2:5]
	v_mfma_f32_16x16x32_bf16 v[54:57], v[172:175], v[192:195], v[54:57]
	v_mfma_f32_16x16x32_bf16 v[50:53], v[180:183], v[192:195], v[50:53]
	v_mfma_f32_16x16x32_bf16 v[38:41], v[172:175], v[200:203], v[38:41]
	v_mfma_f32_16x16x32_bf16 v[34:37], v[180:183], v[200:203], v[34:37]
	v_mfma_f32_16x16x32_bf16 v[22:25], v[172:175], v[208:211], v[22:25]
	v_mfma_f32_16x16x32_bf16 v[18:21], v[180:183], v[208:211], v[18:21]
	v_mfma_f32_16x16x32_bf16 v[6:9], v[172:175], v[216:219], v[6:9]
	v_mfma_f32_16x16x32_bf16 v[2:5], v[180:183], v[216:219], v[2:5]
	s_barrier
	s_setprio 0
	s_add_i32 s67, 0, 0x18000
	s_add_i32 s68, 0, 0x1c000
	v_add_u32_e32 v164, s67, v150
	v_add_u32_e32 v180, s68, v150
	ds_read_b128 v[146:149], v164
	ds_read_b128 v[156:159], v164 offset:1024
	ds_read_b128 v[160:163], v164 offset:2048
	ds_read_b128 v[164:167], v164 offset:3072
	ds_read_b128 v[168:171], v180
	ds_read_b128 v[172:175], v180 offset:1024
	ds_read_b128 v[176:179], v180 offset:2048
	ds_read_b128 v[180:183], v180 offset:3072
	s_add_u32 s40, s40, 0x40000
	s_addc_u32 s41, s41, 0
	s_mov_b32 m0, s46
	ds_read_b128 v[188:191], v154 offset:32768
	ds_read_b128 v[192:195], v154 offset:33792
	ds_read_b128 v[196:199], v154 offset:34816
	ds_read_b128 v[200:203], v154 offset:35840
	ds_read_b128 v[204:207], v154 offset:36864
	ds_read_b128 v[208:211], v154 offset:37888
	ds_read_b128 v[212:215], v154 offset:38912
	ds_read_b128 v[216:219], v154 offset:39936
	global_load_lds_dwordx4 v130, s[40:41]
	s_mov_b32 m0, s47
	s_nop 0
	global_load_lds_dwordx4 v134, s[40:41]
	s_waitcnt vmcnt(8)
	s_waitcnt lgkmcnt(0)
	s_setprio 1
	s_barrier
	v_mfma_f32_16x16x32_bf16 v[126:129], v[146:149], v[188:191], v[126:129]
	v_mfma_f32_16x16x32_bf16 v[122:125], v[160:163], v[188:191], v[122:125]
	v_mfma_f32_16x16x32_bf16 v[110:113], v[146:149], v[196:199], v[110:113]
	v_mfma_f32_16x16x32_bf16 v[106:109], v[160:163], v[196:199], v[106:109]
	v_mfma_f32_16x16x32_bf16 v[94:97], v[146:149], v[204:207], v[94:97]
	v_mfma_f32_16x16x32_bf16 v[90:93], v[160:163], v[204:207], v[90:93]
	v_mfma_f32_16x16x32_bf16 v[78:81], v[146:149], v[212:215], v[78:81]
	v_mfma_f32_16x16x32_bf16 v[74:77], v[160:163], v[212:215], v[74:77]
	v_mfma_f32_16x16x32_bf16 v[126:129], v[156:159], v[192:195], v[126:129]
	v_mfma_f32_16x16x32_bf16 v[122:125], v[164:167], v[192:195], v[122:125]
	v_mfma_f32_16x16x32_bf16 v[110:113], v[156:159], v[200:203], v[110:113]
	v_mfma_f32_16x16x32_bf16 v[106:109], v[164:167], v[200:203], v[106:109]
	v_mfma_f32_16x16x32_bf16 v[94:97], v[156:159], v[208:211], v[94:97]
	v_mfma_f32_16x16x32_bf16 v[90:93], v[164:167], v[208:211], v[90:93]
	v_mfma_f32_16x16x32_bf16 v[78:81], v[156:159], v[216:219], v[78:81]
	v_mfma_f32_16x16x32_bf16 v[74:77], v[164:167], v[216:219], v[74:77]
	v_mfma_f32_16x16x32_bf16 v[118:121], v[168:171], v[188:191], v[118:121]
	v_mfma_f32_16x16x32_bf16 v[114:117], v[176:179], v[188:191], v[114:117]
	v_mfma_f32_16x16x32_bf16 v[102:105], v[168:171], v[196:199], v[102:105]
	v_mfma_f32_16x16x32_bf16 v[98:101], v[176:179], v[196:199], v[98:101]
	v_mfma_f32_16x16x32_bf16 v[86:89], v[168:171], v[204:207], v[86:89]
	v_mfma_f32_16x16x32_bf16 v[82:85], v[176:179], v[204:207], v[82:85]
	v_mfma_f32_16x16x32_bf16 v[70:73], v[168:171], v[212:215], v[70:73]
	v_mfma_f32_16x16x32_bf16 v[66:69], v[176:179], v[212:215], v[66:69]
	v_mfma_f32_16x16x32_bf16 v[118:121], v[172:175], v[192:195], v[118:121]
	v_mfma_f32_16x16x32_bf16 v[114:117], v[180:183], v[192:195], v[114:117]
	v_mfma_f32_16x16x32_bf16 v[102:105], v[172:175], v[200:203], v[102:105]
	v_mfma_f32_16x16x32_bf16 v[98:101], v[180:183], v[200:203], v[98:101]
	v_mfma_f32_16x16x32_bf16 v[86:89], v[172:175], v[208:211], v[86:89]
	v_mfma_f32_16x16x32_bf16 v[82:85], v[180:183], v[208:211], v[82:85]
	v_mfma_f32_16x16x32_bf16 v[70:73], v[172:175], v[216:219], v[70:73]
	v_mfma_f32_16x16x32_bf16 v[66:69], v[180:183], v[216:219], v[66:69]
	s_barrier
	s_setprio 0
	s_add_i32 s40, s67, s45
	v_lshl_add_u64 v[184:185], v[184:185], 0, s[20:21]
	s_mov_b32 m0, s40
	ds_read_b128 v[188:191], v154 offset:49152
	ds_read_b128 v[192:195], v154 offset:50176
	ds_read_b128 v[196:199], v154 offset:51200
	ds_read_b128 v[200:203], v154 offset:52224
	ds_read_b128 v[204:207], v154 offset:53248
	ds_read_b128 v[208:211], v154 offset:54272
	ds_read_b128 v[212:215], v154 offset:55296
	ds_read_b128 v[216:219], v154 offset:56320
	global_load_lds_dwordx4 v[184:185], off
	s_add_i32 m0, s40, 0x2000
	s_add_u32 s38, s38, 0x40080
	v_lshl_add_u64 v[184:185], v[220:221], 0, s[20:21]
	s_addc_u32 s39, s39, 0
	s_add_i32 s40, s68, s45
	global_load_lds_dwordx4 v[184:185], off
	s_mov_b32 m0, s40
	s_nop 0
	global_load_lds_dwordx4 v132, s[38:39]
	s_add_i32 m0, s40, 0x2000
	s_nop 0
	global_load_lds_dwordx4 v136, s[38:39]
	v_lshl_add_u64 v[184:185], v[222:223], 0, s[20:21]
	s_mov_b32 m0, s57
	s_nop 0
	global_load_lds_dwordx4 v[184:185], off
	v_lshl_add_u64 v[184:185], v[224:225], 0, s[20:21]
	s_mov_b32 m0, s60
	s_nop 0
	global_load_lds_dwordx4 v[184:185], off
	s_waitcnt vmcnt(8)
	s_waitcnt lgkmcnt(0)
	s_setprio 1
	s_barrier
	v_mfma_f32_16x16x32_bf16 v[62:65], v[146:149], v[188:191], v[62:65]
	v_mfma_f32_16x16x32_bf16 v[58:61], v[160:163], v[188:191], v[58:61]
	v_mfma_f32_16x16x32_bf16 v[46:49], v[146:149], v[196:199], v[46:49]
	v_mfma_f32_16x16x32_bf16 v[42:45], v[160:163], v[196:199], v[42:45]
	v_mfma_f32_16x16x32_bf16 v[30:33], v[146:149], v[204:207], v[30:33]
	v_mfma_f32_16x16x32_bf16 v[26:29], v[160:163], v[204:207], v[26:29]
	v_mfma_f32_16x16x32_bf16 v[14:17], v[146:149], v[212:215], v[14:17]
	v_mfma_f32_16x16x32_bf16 v[10:13], v[160:163], v[212:215], v[10:13]
	v_mfma_f32_16x16x32_bf16 v[62:65], v[156:159], v[192:195], v[62:65]
	v_mfma_f32_16x16x32_bf16 v[58:61], v[164:167], v[192:195], v[58:61]
	v_mfma_f32_16x16x32_bf16 v[46:49], v[156:159], v[200:203], v[46:49]
	v_mfma_f32_16x16x32_bf16 v[42:45], v[164:167], v[200:203], v[42:45]
	v_mfma_f32_16x16x32_bf16 v[30:33], v[156:159], v[208:211], v[30:33]
	v_mfma_f32_16x16x32_bf16 v[26:29], v[164:167], v[208:211], v[26:29]
	v_mfma_f32_16x16x32_bf16 v[14:17], v[156:159], v[216:219], v[14:17]
	v_mfma_f32_16x16x32_bf16 v[10:13], v[164:167], v[216:219], v[10:13]
	v_mfma_f32_16x16x32_bf16 v[54:57], v[168:171], v[188:191], v[54:57]
	v_mfma_f32_16x16x32_bf16 v[50:53], v[176:179], v[188:191], v[50:53]
	v_mfma_f32_16x16x32_bf16 v[38:41], v[168:171], v[196:199], v[38:41]
	v_mfma_f32_16x16x32_bf16 v[34:37], v[176:179], v[196:199], v[34:37]
	v_mfma_f32_16x16x32_bf16 v[22:25], v[168:171], v[204:207], v[22:25]
	v_mfma_f32_16x16x32_bf16 v[18:21], v[176:179], v[204:207], v[18:21]
	v_mfma_f32_16x16x32_bf16 v[6:9], v[168:171], v[212:215], v[6:9]
	v_mfma_f32_16x16x32_bf16 v[2:5], v[176:179], v[212:215], v[2:5]
	v_mfma_f32_16x16x32_bf16 v[54:57], v[172:175], v[192:195], v[54:57]
	v_mfma_f32_16x16x32_bf16 v[50:53], v[180:183], v[192:195], v[50:53]
	v_mfma_f32_16x16x32_bf16 v[38:41], v[172:175], v[200:203], v[38:41]
	v_mfma_f32_16x16x32_bf16 v[34:37], v[180:183], v[200:203], v[34:37]
	v_mfma_f32_16x16x32_bf16 v[22:25], v[172:175], v[208:211], v[22:25]
	v_mfma_f32_16x16x32_bf16 v[18:21], v[180:183], v[208:211], v[18:21]
	v_mfma_f32_16x16x32_bf16 v[6:9], v[172:175], v[216:219], v[6:9]
	v_mfma_f32_16x16x32_bf16 v[2:5], v[180:183], v[216:219], v[2:5]
	s_barrier
	s_setprio 0
	s_add_i32 s66, s66, 2
	s_add_u32 s64, s64, 0x100
	s_addc_u32 s65, s65, 0
	s_add_u32 s10, s10, 0x100
	s_addc_u32 s11, s11, 0
	s_cmp_gt_u32 s66, 13
	s_cbranch_scc0 .LBB0_1483
	v_lshl_add_u32 v245, s34, 8, v1
	v_lshl_or_b32 v246, s36, 8, v151
	v_lshlrev_b32_e32 v245, 13, v245
	v_lshl_add_u32 v245, v246, 1, v245
	global_load_dwordx4 v[146:149], v245, s[16:17]
	global_load_dwordx4 v[156:159], v245, s[16:17] offset:256
	s_add_u32 s10, s16, 0x20000
	s_addc_u32 s11, s17, 0
	global_load_dwordx4 v[160:163], v245, s[10:11]
	global_load_dwordx4 v[164:167], v245, s[10:11] offset:256
	s_add_u32 s10, s16, 0x40000
	s_addc_u32 s11, s17, 0
	global_load_dwordx4 v[168:171], v245, s[10:11]
	global_load_dwordx4 v[172:175], v245, s[10:11] offset:256
	s_add_u32 s10, s16, 0x60000
	s_addc_u32 s11, s17, 0
	global_load_dwordx4 v[176:179], v245, s[10:11]
	global_load_dwordx4 v[180:183], v245, s[10:11] offset:256
	s_add_u32 s10, s16, 0x100000
	s_addc_u32 s11, s17, 0
	global_load_dwordx4 v[188:191], v245, s[10:11]
	global_load_dwordx4 v[192:195], v245, s[10:11] offset:256
	s_add_u32 s10, s16, 0x120000
	s_addc_u32 s11, s17, 0
	global_load_dwordx4 v[196:199], v245, s[10:11]
	global_load_dwordx4 v[200:203], v245, s[10:11] offset:256
	s_add_u32 s10, s16, 0x140000
	s_addc_u32 s11, s17, 0
	global_load_dwordx4 v[204:207], v245, s[10:11]
	global_load_dwordx4 v[208:211], v245, s[10:11] offset:256
	s_add_u32 s10, s16, 0x160000
	s_addc_u32 s11, s17, 0
	global_load_dwordx4 v[212:215], v245, s[10:11]
	global_load_dwordx4 v[216:219], v245, s[10:11] offset:256
	s_and_b64 vcc, exec, s[22:23]
	s_cbranch_vccz .LBB0_1486
	s_barrier

.LBB0_1644:
	v_add_u32_e32 v3, s75, v165
	ds_read_b128 v[134:137], v3
	ds_read_b128 v[138:141], v3 offset:1024
	ds_read_b128 v[142:145], v3 offset:2048
	ds_read_b128 v[146:149], v3 offset:3072
	v_add_u32_e32 v3, s76, v165
	s_add_u32 s16, s42, s44
	ds_read_b128 v[150:153], v3
	ds_read_b128 v[154:157], v3 offset:1024
	ds_read_b128 v[158:161], v3 offset:2048
	ds_read_b128 v[188:191], v3 offset:3072
	s_addc_u32 s17, s43, s45
	s_add_u32 s16, s16, 0x100
	s_addc_u32 s17, s17, 0
	s_add_u32 s46, s78, s44
	s_addc_u32 s47, s79, s45
	s_cmpk_eq_i32 s44, 0x1f00
	s_cselect_b32 s61, s39, s17
	s_cselect_b32 s60, s38, s16
	s_cselect_b32 s47, s28, s47
	s_cselect_b32 s46, s29, s46
	v_lshl_add_u64 v[4:5], v[180:181], 0, s[44:45]
	s_add_i32 m0, s63, 0xc000
	ds_read_b128 v[192:195], v185
	ds_read_b128 v[196:199], v185 offset:1024
	ds_read_b128 v[200:203], v185 offset:2048
	ds_read_b128 v[204:207], v185 offset:3072
	ds_read_b128 v[208:211], v185 offset:4096
	ds_read_b128 v[212:215], v185 offset:5120
	ds_read_b128 v[216:219], v185 offset:6144
	ds_read_b128 v[220:223], v185 offset:7168
	global_load_lds_dwordx4 v[4:5], off
	v_lshl_add_u64 v[4:5], v[178:179], 0, s[44:45]
	s_add_i32 m0, s63, 0xe000
	s_nop 0
	global_load_lds_dwordx4 v[4:5], off
	s_waitcnt vmcnt(8)
	s_waitcnt lgkmcnt(0)
	s_setprio 1
	s_barrier
	v_mfma_f32_16x16x32_bf16 v[130:133], v[134:137], v[192:195], v[130:133]
	v_mfma_f32_16x16x32_bf16 v[126:129], v[142:145], v[192:195], v[126:129]
	v_mfma_f32_16x16x32_bf16 v[114:117], v[134:137], v[200:203], v[114:117]
	v_mfma_f32_16x16x32_bf16 v[110:113], v[142:145], v[200:203], v[110:113]
	v_mfma_f32_16x16x32_bf16 v[98:101], v[134:137], v[208:211], v[98:101]
	v_mfma_f32_16x16x32_bf16 v[94:97], v[142:145], v[208:211], v[94:97]
	v_mfma_f32_16x16x32_bf16 v[82:85], v[134:137], v[216:219], v[82:85]
	v_mfma_f32_16x16x32_bf16 v[78:81], v[142:145], v[216:219], v[78:81]
	v_mfma_f32_16x16x32_bf16 v[130:133], v[138:141], v[196:199], v[130:133]
	v_mfma_f32_16x16x32_bf16 v[126:129], v[146:149], v[196:199], v[126:129]
	v_mfma_f32_16x16x32_bf16 v[114:117], v[138:141], v[204:207], v[114:117]
	v_mfma_f32_16x16x32_bf16 v[110:113], v[146:149], v[204:207], v[110:113]
	v_mfma_f32_16x16x32_bf16 v[98:101], v[138:141], v[212:215], v[98:101]
	v_mfma_f32_16x16x32_bf16 v[94:97], v[146:149], v[212:215], v[94:97]
	v_mfma_f32_16x16x32_bf16 v[82:85], v[138:141], v[220:223], v[82:85]
	v_mfma_f32_16x16x32_bf16 v[78:81], v[146:149], v[220:223], v[78:81]
	v_mfma_f32_16x16x32_bf16 v[122:125], v[150:153], v[192:195], v[122:125]
	v_mfma_f32_16x16x32_bf16 v[118:121], v[158:161], v[192:195], v[118:121]
	v_mfma_f32_16x16x32_bf16 v[106:109], v[150:153], v[200:203], v[106:109]
	v_mfma_f32_16x16x32_bf16 v[102:105], v[158:161], v[200:203], v[102:105]
	v_mfma_f32_16x16x32_bf16 v[90:93], v[150:153], v[208:211], v[90:93]
	v_mfma_f32_16x16x32_bf16 v[86:89], v[158:161], v[208:211], v[86:89]
	v_mfma_f32_16x16x32_bf16 v[74:77], v[150:153], v[216:219], v[74:77]
	v_mfma_f32_16x16x32_bf16 v[70:73], v[158:161], v[216:219], v[70:73]
	v_mfma_f32_16x16x32_bf16 v[122:125], v[154:157], v[196:199], v[122:125]
	v_mfma_f32_16x16x32_bf16 v[118:121], v[188:191], v[196:199], v[118:121]
	v_mfma_f32_16x16x32_bf16 v[106:109], v[154:157], v[204:207], v[106:109]
	v_mfma_f32_16x16x32_bf16 v[102:105], v[188:191], v[204:207], v[102:105]
	v_mfma_f32_16x16x32_bf16 v[90:93], v[154:157], v[212:215], v[90:93]
	v_mfma_f32_16x16x32_bf16 v[86:89], v[188:191], v[212:215], v[86:89]
	v_mfma_f32_16x16x32_bf16 v[74:77], v[154:157], v[220:223], v[74:77]
	v_mfma_f32_16x16x32_bf16 v[70:73], v[188:191], v[220:223], v[70:73]
	s_barrier
	s_setprio 0
	s_add_i32 s16, s75, s62
	v_lshl_add_u64 v[162:163], s[46:47], 0, v[168:169]
	s_mov_b32 m0, s16
	ds_read_b128 v[192:195], v185 offset:16384
	ds_read_b128 v[196:199], v185 offset:17408
	ds_read_b128 v[200:203], v185 offset:18432
	ds_read_b128 v[204:207], v185 offset:19456
	ds_read_b128 v[208:211], v185 offset:20480
	ds_read_b128 v[212:215], v185 offset:21504
	ds_read_b128 v[216:219], v185 offset:22528
	ds_read_b128 v[220:223], v185 offset:23552
	global_load_lds_dwordx4 v[162:163], off
	s_add_i32 m0, s16, 0x2000
	s_add_u32 s16, s46, 0x100000
	v_lshl_add_u64 v[182:183], s[46:47], 0, v[172:173]
	s_addc_u32 s17, s47, 0
	s_add_i32 s81, s76, s62
	global_load_lds_dwordx4 v[182:183], off
	s_mov_b32 m0, s81
	v_lshl_add_u64 v[224:225], s[60:61], 0, v[166:167]
	global_load_lds_dwordx4 v168, s[16:17]
	s_add_i32 m0, s81, 0x2000
	v_lshl_add_u64 v[226:227], s[60:61], 0, v[170:171]
	global_load_lds_dwordx4 v172, s[16:17]
	s_mov_b32 m0, s63
	s_nop 0
	global_load_lds_dwordx4 v[224:225], off
	s_mov_b32 m0, s64
	s_nop 0
	global_load_lds_dwordx4 v[226:227], off
	s_waitcnt vmcnt(8)
	s_waitcnt lgkmcnt(0)
	s_setprio 1
	s_barrier
	v_mfma_f32_16x16x32_bf16 v[66:69], v[134:137], v[192:195], v[66:69]
	v_mfma_f32_16x16x32_bf16 v[62:65], v[142:145], v[192:195], v[62:65]
	v_mfma_f32_16x16x32_bf16 v[50:53], v[134:137], v[200:203], v[50:53]
	v_mfma_f32_16x16x32_bf16 v[46:49], v[142:145], v[200:203], v[46:49]
	v_mfma_f32_16x16x32_bf16 v[34:37], v[134:137], v[208:211], v[34:37]
	v_mfma_f32_16x16x32_bf16 v[30:33], v[142:145], v[208:211], v[30:33]
	v_mfma_f32_16x16x32_bf16 v[18:21], v[134:137], v[216:219], v[18:21]
	v_mfma_f32_16x16x32_bf16 v[14:17], v[142:145], v[216:219], v[14:17]
	v_mfma_f32_16x16x32_bf16 v[66:69], v[138:141], v[196:199], v[66:69]
	v_mfma_f32_16x16x32_bf16 v[62:65], v[146:149], v[196:199], v[62:65]
	v_mfma_f32_16x16x32_bf16 v[50:53], v[138:141], v[204:207], v[50:53]
	v_mfma_f32_16x16x32_bf16 v[46:49], v[146:149], v[204:207], v[46:49]
	v_mfma_f32_16x16x32_bf16 v[34:37], v[138:141], v[212:215], v[34:37]
	v_mfma_f32_16x16x32_bf16 v[30:33], v[146:149], v[212:215], v[30:33]
	v_mfma_f32_16x16x32_bf16 v[18:21], v[138:141], v[220:223], v[18:21]
	v_mfma_f32_16x16x32_bf16 v[14:17], v[146:149], v[220:223], v[14:17]
	v_mfma_f32_16x16x32_bf16 v[58:61], v[150:153], v[192:195], v[58:61]
	v_mfma_f32_16x16x32_bf16 v[54:57], v[158:161], v[192:195], v[54:57]
	v_mfma_f32_16x16x32_bf16 v[42:45], v[150:153], v[200:203], v[42:45]
	v_mfma_f32_16x16x32_bf16 v[38:41], v[158:161], v[200:203], v[38:41]
	v_mfma_f32_16x16x32_bf16 v[26:29], v[150:153], v[208:211], v[26:29]
	v_mfma_f32_16x16x32_bf16 v[22:25], v[158:161], v[208:211], v[22:25]
	v_mfma_f32_16x16x32_bf16 v[10:13], v[150:153], v[216:219], v[10:13]
	v_mfma_f32_16x16x32_bf16 v[4:7], v[158:161], v[216:219], v[6:9]
	v_mfma_f32_16x16x32_bf16 v[58:61], v[154:157], v[196:199], v[58:61]
	v_mfma_f32_16x16x32_bf16 v[54:57], v[188:191], v[196:199], v[54:57]
	v_mfma_f32_16x16x32_bf16 v[42:45], v[154:157], v[204:207], v[42:45]
	v_mfma_f32_16x16x32_bf16 v[38:41], v[188:191], v[204:207], v[38:41]
	v_mfma_f32_16x16x32_bf16 v[26:29], v[154:157], v[212:215], v[26:29]
	v_mfma_f32_16x16x32_bf16 v[22:25], v[188:191], v[212:215], v[22:25]
	v_mfma_f32_16x16x32_bf16 v[10:13], v[154:157], v[220:223], v[10:13]
	v_mfma_f32_16x16x32_bf16 v[4:7], v[188:191], v[220:223], v[4:7]
	s_barrier
	s_setprio 0
	s_add_i32 s81, 0, 0x18000
	v_add_u32_e32 v3, s81, v165
	s_add_i32 s82, 0, 0x1c000
	ds_read_b128 v[134:137], v3
	ds_read_b128 v[138:141], v3 offset:1024
	ds_read_b128 v[142:145], v3 offset:2048
	ds_read_b128 v[146:149], v3 offset:3072
	v_add_u32_e32 v3, s82, v165
	ds_read_b128 v[150:153], v3
	ds_read_b128 v[154:157], v3 offset:1024
	ds_read_b128 v[158:161], v3 offset:2048
	ds_read_b128 v[188:191], v3 offset:3072
	s_add_u32 s16, s60, 0x480000
	s_addc_u32 s17, s61, 0
	s_mov_b32 m0, s65
	ds_read_b128 v[192:195], v185 offset:32768
	ds_read_b128 v[196:199], v185 offset:33792
	ds_read_b128 v[200:203], v185 offset:34816
	ds_read_b128 v[204:207], v185 offset:35840
	ds_read_b128 v[208:211], v185 offset:36864
	ds_read_b128 v[212:215], v185 offset:37888
	ds_read_b128 v[216:219], v185 offset:38912
	ds_read_b128 v[220:223], v185 offset:39936
	global_load_lds_dwordx4 v166, s[16:17]
	s_mov_b32 m0, s66
	s_nop 0
	global_load_lds_dwordx4 v170, s[16:17]
	s_waitcnt vmcnt(8)
	s_waitcnt lgkmcnt(0)
	s_setprio 1
	s_barrier
	v_mfma_f32_16x16x32_bf16 v[130:133], v[134:137], v[192:195], v[130:133]
	v_mfma_f32_16x16x32_bf16 v[126:129], v[142:145], v[192:195], v[126:129]
	v_mfma_f32_16x16x32_bf16 v[114:117], v[134:137], v[200:203], v[114:117]
	v_mfma_f32_16x16x32_bf16 v[110:113], v[142:145], v[200:203], v[110:113]
	v_mfma_f32_16x16x32_bf16 v[98:101], v[134:137], v[208:211], v[98:101]
	v_mfma_f32_16x16x32_bf16 v[94:97], v[142:145], v[208:211], v[94:97]
	v_mfma_f32_16x16x32_bf16 v[82:85], v[134:137], v[216:219], v[82:85]
	v_mfma_f32_16x16x32_bf16 v[78:81], v[142:145], v[216:219], v[78:81]
	v_mfma_f32_16x16x32_bf16 v[130:133], v[138:141], v[196:199], v[130:133]
	v_mfma_f32_16x16x32_bf16 v[126:129], v[146:149], v[196:199], v[126:129]
	v_mfma_f32_16x16x32_bf16 v[114:117], v[138:141], v[204:207], v[114:117]
	v_mfma_f32_16x16x32_bf16 v[110:113], v[146:149], v[204:207], v[110:113]
	v_mfma_f32_16x16x32_bf16 v[98:101], v[138:141], v[212:215], v[98:101]
	v_mfma_f32_16x16x32_bf16 v[94:97], v[146:149], v[212:215], v[94:97]
	v_mfma_f32_16x16x32_bf16 v[82:85], v[138:141], v[220:223], v[82:85]
	v_mfma_f32_16x16x32_bf16 v[78:81], v[146:149], v[220:223], v[78:81]
	v_mfma_f32_16x16x32_bf16 v[122:125], v[150:153], v[192:195], v[122:125]
	v_mfma_f32_16x16x32_bf16 v[118:121], v[158:161], v[192:195], v[118:121]
	v_mfma_f32_16x16x32_bf16 v[106:109], v[150:153], v[200:203], v[106:109]
	v_mfma_f32_16x16x32_bf16 v[102:105], v[158:161], v[200:203], v[102:105]
	v_mfma_f32_16x16x32_bf16 v[90:93], v[150:153], v[208:211], v[90:93]
	v_mfma_f32_16x16x32_bf16 v[86:89], v[158:161], v[208:211], v[86:89]
	v_mfma_f32_16x16x32_bf16 v[74:77], v[150:153], v[216:219], v[74:77]
	v_mfma_f32_16x16x32_bf16 v[70:73], v[158:161], v[216:219], v[70:73]
	v_mfma_f32_16x16x32_bf16 v[122:125], v[154:157], v[196:199], v[122:125]
	v_mfma_f32_16x16x32_bf16 v[118:121], v[188:191], v[196:199], v[118:121]
	v_mfma_f32_16x16x32_bf16 v[106:109], v[154:157], v[204:207], v[106:109]
	v_mfma_f32_16x16x32_bf16 v[102:105], v[188:191], v[204:207], v[102:105]
	v_mfma_f32_16x16x32_bf16 v[90:93], v[154:157], v[212:215], v[90:93]
	v_mfma_f32_16x16x32_bf16 v[86:89], v[188:191], v[212:215], v[86:89]
	v_mfma_f32_16x16x32_bf16 v[74:77], v[154:157], v[220:223], v[74:77]
	v_mfma_f32_16x16x32_bf16 v[70:73], v[188:191], v[220:223], v[70:73]
	s_barrier
	s_setprio 0
	s_add_i32 s16, s81, s62
	v_lshl_add_u64 v[8:9], v[162:163], 0, s[14:15]
	s_mov_b32 m0, s16
	ds_read_b128 v[192:195], v185 offset:49152
	ds_read_b128 v[196:199], v185 offset:50176
	ds_read_b128 v[200:203], v185 offset:51200
	ds_read_b128 v[204:207], v185 offset:52224
	ds_read_b128 v[208:211], v185 offset:53248
	ds_read_b128 v[212:215], v185 offset:54272
	ds_read_b128 v[216:219], v185 offset:55296
	ds_read_b128 v[220:223], v185 offset:56320
	global_load_lds_dwordx4 v[8:9], off
	s_add_i32 m0, s16, 0x2000
	s_add_u32 s16, s46, 0x100080
	v_lshl_add_u64 v[8:9], v[182:183], 0, s[14:15]
	s_addc_u32 s17, s47, 0
	s_add_i32 s46, s82, s62
	global_load_lds_dwordx4 v[8:9], off
	s_mov_b32 m0, s46
	s_nop 0
	global_load_lds_dwordx4 v168, s[16:17]
	s_add_i32 m0, s46, 0x2000
	s_nop 0
	global_load_lds_dwordx4 v172, s[16:17]
	v_lshl_add_u64 v[8:9], v[224:225], 0, s[14:15]
	s_mov_b32 m0, s70
	s_nop 0
	global_load_lds_dwordx4 v[8:9], off
	v_lshl_add_u64 v[8:9], v[226:227], 0, s[14:15]
	s_mov_b32 m0, s71
	s_nop 0
	global_load_lds_dwordx4 v[8:9], off
	s_waitcnt vmcnt(8)
	s_waitcnt lgkmcnt(0)
	s_setprio 1
	s_barrier
	v_mfma_f32_16x16x32_bf16 v[66:69], v[134:137], v[192:195], v[66:69]
	v_mfma_f32_16x16x32_bf16 v[62:65], v[142:145], v[192:195], v[62:65]
	v_mfma_f32_16x16x32_bf16 v[50:53], v[134:137], v[200:203], v[50:53]
	v_mfma_f32_16x16x32_bf16 v[46:49], v[142:145], v[200:203], v[46:49]
	v_mfma_f32_16x16x32_bf16 v[34:37], v[134:137], v[208:211], v[34:37]
	v_mfma_f32_16x16x32_bf16 v[30:33], v[142:145], v[208:211], v[30:33]
	v_mfma_f32_16x16x32_bf16 v[18:21], v[134:137], v[216:219], v[18:21]
	v_mfma_f32_16x16x32_bf16 v[14:17], v[142:145], v[216:219], v[14:17]
	v_mfma_f32_16x16x32_bf16 v[66:69], v[138:141], v[196:199], v[66:69]
	v_mfma_f32_16x16x32_bf16 v[62:65], v[146:149], v[196:199], v[62:65]
	v_mfma_f32_16x16x32_bf16 v[50:53], v[138:141], v[204:207], v[50:53]
	v_mfma_f32_16x16x32_bf16 v[46:49], v[146:149], v[204:207], v[46:49]
	v_mfma_f32_16x16x32_bf16 v[34:37], v[138:141], v[212:215], v[34:37]
	v_mfma_f32_16x16x32_bf16 v[30:33], v[146:149], v[212:215], v[30:33]
	v_mfma_f32_16x16x32_bf16 v[18:21], v[138:141], v[220:223], v[18:21]
	v_mfma_f32_16x16x32_bf16 v[14:17], v[146:149], v[220:223], v[14:17]
	v_mfma_f32_16x16x32_bf16 v[58:61], v[150:153], v[192:195], v[58:61]
	v_mfma_f32_16x16x32_bf16 v[54:57], v[158:161], v[192:195], v[54:57]
	v_mfma_f32_16x16x32_bf16 v[42:45], v[150:153], v[200:203], v[42:45]
	v_mfma_f32_16x16x32_bf16 v[38:41], v[158:161], v[200:203], v[38:41]
	v_mfma_f32_16x16x32_bf16 v[26:29], v[150:153], v[208:211], v[26:29]
	v_mfma_f32_16x16x32_bf16 v[22:25], v[158:161], v[208:211], v[22:25]
	v_mfma_f32_16x16x32_bf16 v[8:11], v[150:153], v[216:219], v[10:13]
	v_mfma_f32_16x16x32_bf16 v[4:7], v[158:161], v[216:219], v[4:7]
	v_mfma_f32_16x16x32_bf16 v[58:61], v[154:157], v[196:199], v[58:61]
	v_mfma_f32_16x16x32_bf16 v[54:57], v[188:191], v[196:199], v[54:57]
	v_mfma_f32_16x16x32_bf16 v[42:45], v[154:157], v[204:207], v[42:45]
	v_mfma_f32_16x16x32_bf16 v[38:41], v[188:191], v[204:207], v[38:41]
	v_mfma_f32_16x16x32_bf16 v[26:29], v[154:157], v[212:215], v[26:29]
	v_mfma_f32_16x16x32_bf16 v[22:25], v[188:191], v[212:215], v[22:25]
	v_mfma_f32_16x16x32_bf16 v[10:13], v[154:157], v[220:223], v[8:11]
	v_mfma_f32_16x16x32_bf16 v[6:9], v[188:191], v[220:223], v[4:7]
	s_barrier
	s_setprio 0
	s_add_i32 s80, s80, 2
	s_add_u32 s44, s44, 0x100
	s_addc_u32 s45, s45, 0
	s_cmp_gt_u32 s80, 61
	s_cbranch_scc1 .LBB0_1647

.LBB0_1689:
	ds_read_b128 v[142:145], v148
	ds_read_b128 v[152:155], v148 offset:1024
	ds_read_b128 v[156:159], v148 offset:2048
	ds_read_b128 v[160:163], v148 offset:3072
	ds_read_b128 v[166:169], v149
	ds_read_b128 v[170:173], v149 offset:1024
	ds_read_b128 v[174:177], v149 offset:2048
	ds_read_b128 v[178:181], v149 offset:3072
	s_add_u32 s6, s70, 0xfff00080
	s_addc_u32 s7, s71, -1
	s_cmp_eq_u32 s86, 60
	s_cselect_b32 s75, s61, s7
	s_cselect_b32 s74, s67, s6
	s_cselect_b32 s73, s47, s85
	s_cselect_b32 s72, s69, s84
	s_add_i32 m0, s28, 0xc000
	ds_read_b128 v[182:185], v150
	ds_read_b128 v[188:191], v150 offset:1024
	ds_read_b128 v[192:195], v150 offset:2048
	ds_read_b128 v[196:199], v150 offset:3072
	ds_read_b128 v[200:203], v150 offset:4096
	ds_read_b128 v[204:207], v150 offset:5120
	ds_read_b128 v[208:211], v150 offset:6144
	ds_read_b128 v[212:215], v150 offset:7168
	global_load_lds_dwordx4 v140, s[70:71]
	s_add_i32 m0, s28, 0xe000
	s_nop 0
	global_load_lds_dwordx4 v138, s[70:71]
	s_waitcnt vmcnt(8)
	s_waitcnt lgkmcnt(0)
	s_setprio 1
	s_barrier
	v_mfma_f32_16x16x32_bf16 v[126:129], v[142:145], v[182:185], v[126:129]
	v_mfma_f32_16x16x32_bf16 v[122:125], v[156:159], v[182:185], v[122:125]
	v_mfma_f32_16x16x32_bf16 v[110:113], v[142:145], v[192:195], v[110:113]
	v_mfma_f32_16x16x32_bf16 v[106:109], v[156:159], v[192:195], v[106:109]
	v_mfma_f32_16x16x32_bf16 v[94:97], v[142:145], v[200:203], v[94:97]
	v_mfma_f32_16x16x32_bf16 v[90:93], v[156:159], v[200:203], v[90:93]
	v_mfma_f32_16x16x32_bf16 v[78:81], v[142:145], v[208:211], v[78:81]
	v_mfma_f32_16x16x32_bf16 v[74:77], v[156:159], v[208:211], v[74:77]
	v_mfma_f32_16x16x32_bf16 v[126:129], v[152:155], v[188:191], v[126:129]
	v_mfma_f32_16x16x32_bf16 v[122:125], v[160:163], v[188:191], v[122:125]
	v_mfma_f32_16x16x32_bf16 v[110:113], v[152:155], v[196:199], v[110:113]
	v_mfma_f32_16x16x32_bf16 v[106:109], v[160:163], v[196:199], v[106:109]
	v_mfma_f32_16x16x32_bf16 v[94:97], v[152:155], v[204:207], v[94:97]
	v_mfma_f32_16x16x32_bf16 v[90:93], v[160:163], v[204:207], v[90:93]
	v_mfma_f32_16x16x32_bf16 v[78:81], v[152:155], v[212:215], v[78:81]
	v_mfma_f32_16x16x32_bf16 v[74:77], v[160:163], v[212:215], v[74:77]
	v_mfma_f32_16x16x32_bf16 v[118:121], v[166:169], v[182:185], v[118:121]
	v_mfma_f32_16x16x32_bf16 v[114:117], v[174:177], v[182:185], v[114:117]
	v_mfma_f32_16x16x32_bf16 v[102:105], v[166:169], v[192:195], v[102:105]
	v_mfma_f32_16x16x32_bf16 v[98:101], v[174:177], v[192:195], v[98:101]
	v_mfma_f32_16x16x32_bf16 v[86:89], v[166:169], v[200:203], v[86:89]
	v_mfma_f32_16x16x32_bf16 v[82:85], v[174:177], v[200:203], v[82:85]
	v_mfma_f32_16x16x32_bf16 v[70:73], v[166:169], v[208:211], v[70:73]
	v_mfma_f32_16x16x32_bf16 v[66:69], v[174:177], v[208:211], v[66:69]
	v_mfma_f32_16x16x32_bf16 v[118:121], v[170:173], v[188:191], v[118:121]
	v_mfma_f32_16x16x32_bf16 v[114:117], v[178:181], v[188:191], v[114:117]
	v_mfma_f32_16x16x32_bf16 v[102:105], v[170:173], v[196:199], v[102:105]
	v_mfma_f32_16x16x32_bf16 v[98:101], v[178:181], v[196:199], v[98:101]
	v_mfma_f32_16x16x32_bf16 v[86:89], v[170:173], v[204:207], v[86:89]
	v_mfma_f32_16x16x32_bf16 v[82:85], v[178:181], v[204:207], v[82:85]
	v_mfma_f32_16x16x32_bf16 v[70:73], v[170:173], v[212:215], v[70:73]
	v_mfma_f32_16x16x32_bf16 v[66:69], v[178:181], v[212:215], v[66:69]
	s_barrier
	s_setprio 0
	s_add_i32 s6, s82, s27
	v_lshl_add_u64 v[216:217], s[72:73], 0, v[132:133]
	s_mov_b32 m0, s6
	ds_read_b128 v[182:185], v150 offset:16384
	ds_read_b128 v[188:191], v150 offset:17408
	ds_read_b128 v[192:195], v150 offset:18432
	ds_read_b128 v[196:199], v150 offset:19456
	ds_read_b128 v[200:203], v150 offset:20480
	ds_read_b128 v[204:207], v150 offset:21504
	ds_read_b128 v[208:211], v150 offset:22528
	ds_read_b128 v[212:215], v150 offset:23552
	global_load_lds_dwordx4 v[216:217], off
	s_add_i32 m0, s6, 0x2000
	s_add_u32 s6, s72, 0x100000
	v_lshl_add_u64 v[218:219], s[72:73], 0, v[136:137]
	s_addc_u32 s7, s73, 0
	s_add_i32 s16, s83, s27
	global_load_lds_dwordx4 v[218:219], off
	s_mov_b32 m0, s16
	v_lshl_add_u64 v[222:223], s[74:75], 0, v[134:135]
	global_load_lds_dwordx4 v132, s[6:7]
	s_add_i32 m0, s16, 0x2000
	s_nop 0
	global_load_lds_dwordx4 v136, s[6:7]
	v_lshl_add_u64 v[220:221], s[74:75], 0, v[130:131]
	s_mov_b32 m0, s28
	s_nop 0
	global_load_lds_dwordx4 v[220:221], off
	s_mov_b32 m0, s29
	s_nop 0
	global_load_lds_dwordx4 v[222:223], off
	s_waitcnt vmcnt(8)
	s_waitcnt lgkmcnt(0)
	s_setprio 1
	s_barrier
	v_mfma_f32_16x16x32_bf16 v[62:65], v[142:145], v[182:185], v[62:65]
	v_mfma_f32_16x16x32_bf16 v[58:61], v[156:159], v[182:185], v[58:61]
	v_mfma_f32_16x16x32_bf16 v[46:49], v[142:145], v[192:195], v[46:49]
	v_mfma_f32_16x16x32_bf16 v[42:45], v[156:159], v[192:195], v[42:45]
	v_mfma_f32_16x16x32_bf16 v[30:33], v[142:145], v[200:203], v[30:33]
	v_mfma_f32_16x16x32_bf16 v[26:29], v[156:159], v[200:203], v[26:29]
	v_mfma_f32_16x16x32_bf16 v[14:17], v[142:145], v[208:211], v[14:17]
	v_mfma_f32_16x16x32_bf16 v[10:13], v[156:159], v[208:211], v[10:13]
	v_mfma_f32_16x16x32_bf16 v[62:65], v[152:155], v[188:191], v[62:65]
	v_mfma_f32_16x16x32_bf16 v[58:61], v[160:163], v[188:191], v[58:61]
	v_mfma_f32_16x16x32_bf16 v[46:49], v[152:155], v[196:199], v[46:49]
	v_mfma_f32_16x16x32_bf16 v[42:45], v[160:163], v[196:199], v[42:45]
	v_mfma_f32_16x16x32_bf16 v[30:33], v[152:155], v[204:207], v[30:33]
	v_mfma_f32_16x16x32_bf16 v[26:29], v[160:163], v[204:207], v[26:29]
	v_mfma_f32_16x16x32_bf16 v[14:17], v[152:155], v[212:215], v[14:17]
	v_mfma_f32_16x16x32_bf16 v[10:13], v[160:163], v[212:215], v[10:13]
	v_mfma_f32_16x16x32_bf16 v[54:57], v[166:169], v[182:185], v[54:57]
	v_mfma_f32_16x16x32_bf16 v[50:53], v[174:177], v[182:185], v[50:53]
	v_mfma_f32_16x16x32_bf16 v[38:41], v[166:169], v[192:195], v[38:41]
	v_mfma_f32_16x16x32_bf16 v[34:37], v[174:177], v[192:195], v[34:37]
	v_mfma_f32_16x16x32_bf16 v[22:25], v[166:169], v[200:203], v[22:25]
	v_mfma_f32_16x16x32_bf16 v[18:21], v[174:177], v[200:203], v[18:21]
	v_mfma_f32_16x16x32_bf16 v[6:9], v[166:169], v[208:211], v[6:9]
	v_mfma_f32_16x16x32_bf16 v[2:5], v[174:177], v[208:211], v[2:5]
	v_mfma_f32_16x16x32_bf16 v[54:57], v[170:173], v[188:191], v[54:57]
	v_mfma_f32_16x16x32_bf16 v[50:53], v[178:181], v[188:191], v[50:53]
	v_mfma_f32_16x16x32_bf16 v[38:41], v[170:173], v[196:199], v[38:41]
	v_mfma_f32_16x16x32_bf16 v[34:37], v[178:181], v[196:199], v[34:37]
	v_mfma_f32_16x16x32_bf16 v[22:25], v[170:173], v[204:207], v[22:25]
	v_mfma_f32_16x16x32_bf16 v[18:21], v[178:181], v[204:207], v[18:21]
	v_mfma_f32_16x16x32_bf16 v[6:9], v[170:173], v[212:215], v[6:9]
	v_mfma_f32_16x16x32_bf16 v[2:5], v[178:181], v[212:215], v[2:5]
	s_barrier
	s_setprio 0
	s_add_i32 s16, 0, 0x18000
	s_add_i32 s17, 0, 0x1c000
	v_add_u32_e32 v160, s16, v146
	v_add_u32_e32 v165, s17, v146
	ds_read_b128 v[142:145], v160
	ds_read_b128 v[152:155], v160 offset:1024
	ds_read_b128 v[156:159], v160 offset:2048
	ds_read_b128 v[160:163], v160 offset:3072
	ds_read_b128 v[166:169], v165
	ds_read_b128 v[170:173], v165 offset:1024
	ds_read_b128 v[174:177], v165 offset:2048
	ds_read_b128 v[178:181], v165 offset:3072
	s_add_u32 s6, s74, 0x100000
	s_addc_u32 s7, s75, 0
	s_mov_b32 m0, s56
	ds_read_b128 v[182:185], v150 offset:32768
	ds_read_b128 v[188:191], v150 offset:33792
	ds_read_b128 v[192:195], v150 offset:34816
	ds_read_b128 v[196:199], v150 offset:35840
	ds_read_b128 v[200:203], v150 offset:36864
	ds_read_b128 v[204:207], v150 offset:37888
	ds_read_b128 v[208:211], v150 offset:38912
	ds_read_b128 v[212:215], v150 offset:39936
	global_load_lds_dwordx4 v130, s[6:7]
	s_mov_b32 m0, s57
	s_nop 0
	global_load_lds_dwordx4 v134, s[6:7]
	s_waitcnt vmcnt(8)
	s_waitcnt lgkmcnt(0)
	s_setprio 1
	s_barrier
	v_mfma_f32_16x16x32_bf16 v[126:129], v[142:145], v[182:185], v[126:129]
	v_mfma_f32_16x16x32_bf16 v[122:125], v[156:159], v[182:185], v[122:125]
	v_mfma_f32_16x16x32_bf16 v[110:113], v[142:145], v[192:195], v[110:113]
	v_mfma_f32_16x16x32_bf16 v[106:109], v[156:159], v[192:195], v[106:109]
	v_mfma_f32_16x16x32_bf16 v[94:97], v[142:145], v[200:203], v[94:97]
	v_mfma_f32_16x16x32_bf16 v[90:93], v[156:159], v[200:203], v[90:93]
	v_mfma_f32_16x16x32_bf16 v[78:81], v[142:145], v[208:211], v[78:81]
	v_mfma_f32_16x16x32_bf16 v[74:77], v[156:159], v[208:211], v[74:77]
	v_mfma_f32_16x16x32_bf16 v[126:129], v[152:155], v[188:191], v[126:129]
	v_mfma_f32_16x16x32_bf16 v[122:125], v[160:163], v[188:191], v[122:125]
	v_mfma_f32_16x16x32_bf16 v[110:113], v[152:155], v[196:199], v[110:113]
	v_mfma_f32_16x16x32_bf16 v[106:109], v[160:163], v[196:199], v[106:109]
	v_mfma_f32_16x16x32_bf16 v[94:97], v[152:155], v[204:207], v[94:97]
	v_mfma_f32_16x16x32_bf16 v[90:93], v[160:163], v[204:207], v[90:93]
	v_mfma_f32_16x16x32_bf16 v[78:81], v[152:155], v[212:215], v[78:81]
	v_mfma_f32_16x16x32_bf16 v[74:77], v[160:163], v[212:215], v[74:77]
	v_mfma_f32_16x16x32_bf16 v[118:121], v[166:169], v[182:185], v[118:121]
	v_mfma_f32_16x16x32_bf16 v[114:117], v[174:177], v[182:185], v[114:117]
	v_mfma_f32_16x16x32_bf16 v[102:105], v[166:169], v[192:195], v[102:105]
	v_mfma_f32_16x16x32_bf16 v[98:101], v[174:177], v[192:195], v[98:101]
	v_mfma_f32_16x16x32_bf16 v[86:89], v[166:169], v[200:203], v[86:89]
	v_mfma_f32_16x16x32_bf16 v[82:85], v[174:177], v[200:203], v[82:85]
	v_mfma_f32_16x16x32_bf16 v[70:73], v[166:169], v[208:211], v[70:73]
	v_mfma_f32_16x16x32_bf16 v[66:69], v[174:177], v[208:211], v[66:69]
	v_mfma_f32_16x16x32_bf16 v[118:121], v[170:173], v[188:191], v[118:121]
	v_mfma_f32_16x16x32_bf16 v[114:117], v[178:181], v[188:191], v[114:117]
	v_mfma_f32_16x16x32_bf16 v[102:105], v[170:173], v[196:199], v[102:105]
	v_mfma_f32_16x16x32_bf16 v[98:101], v[178:181], v[196:199], v[98:101]
	v_mfma_f32_16x16x32_bf16 v[86:89], v[170:173], v[204:207], v[86:89]
	v_mfma_f32_16x16x32_bf16 v[82:85], v[178:181], v[204:207], v[82:85]
	v_mfma_f32_16x16x32_bf16 v[70:73], v[170:173], v[212:215], v[70:73]
	v_mfma_f32_16x16x32_bf16 v[66:69], v[178:181], v[212:215], v[66:69]
	s_barrier
	s_setprio 0
	s_add_i32 s6, s16, s27
	v_lshl_add_u64 v[216:217], v[216:217], 0, s[40:41]
	s_mov_b32 m0, s6
	ds_read_b128 v[182:185], v150 offset:49152
	ds_read_b128 v[188:191], v150 offset:50176
	ds_read_b128 v[192:195], v150 offset:51200
	ds_read_b128 v[196:199], v150 offset:52224
	ds_read_b128 v[200:203], v150 offset:53248
	ds_read_b128 v[204:207], v150 offset:54272
	ds_read_b128 v[208:211], v150 offset:55296
	ds_read_b128 v[212:215], v150 offset:56320
	global_load_lds_dwordx4 v[216:217], off
	s_add_i32 m0, s6, 0x2000
	s_add_u32 s6, s72, 0x100080
	v_lshl_add_u64 v[216:217], v[218:219], 0, s[40:41]
	s_addc_u32 s7, s73, 0
	s_add_i32 s16, s17, s27
	global_load_lds_dwordx4 v[216:217], off
	s_mov_b32 m0, s16
	s_nop 0
	global_load_lds_dwordx4 v132, s[6:7]
	s_add_i32 m0, s16, 0x2000
	s_nop 0
	global_load_lds_dwordx4 v136, s[6:7]
	v_lshl_add_u64 v[216:217], v[220:221], 0, s[40:41]
	s_mov_b32 m0, s77
	s_nop 0
	global_load_lds_dwordx4 v[216:217], off
	v_lshl_add_u64 v[216:217], v[222:223], 0, s[40:41]
	s_mov_b32 m0, s78
	s_nop 0
	global_load_lds_dwordx4 v[216:217], off
	s_waitcnt vmcnt(8)
	s_waitcnt lgkmcnt(0)
	s_setprio 1
	s_barrier
	v_mfma_f32_16x16x32_bf16 v[62:65], v[142:145], v[182:185], v[62:65]
	v_mfma_f32_16x16x32_bf16 v[58:61], v[156:159], v[182:185], v[58:61]
	v_mfma_f32_16x16x32_bf16 v[46:49], v[142:145], v[192:195], v[46:49]
	v_mfma_f32_16x16x32_bf16 v[42:45], v[156:159], v[192:195], v[42:45]
	v_mfma_f32_16x16x32_bf16 v[30:33], v[142:145], v[200:203], v[30:33]
	v_mfma_f32_16x16x32_bf16 v[26:29], v[156:159], v[200:203], v[26:29]
	v_mfma_f32_16x16x32_bf16 v[14:17], v[142:145], v[208:211], v[14:17]
	v_mfma_f32_16x16x32_bf16 v[10:13], v[156:159], v[208:211], v[10:13]
	v_mfma_f32_16x16x32_bf16 v[62:65], v[152:155], v[188:191], v[62:65]
	v_mfma_f32_16x16x32_bf16 v[58:61], v[160:163], v[188:191], v[58:61]
	v_mfma_f32_16x16x32_bf16 v[46:49], v[152:155], v[196:199], v[46:49]
	v_mfma_f32_16x16x32_bf16 v[42:45], v[160:163], v[196:199], v[42:45]
	v_mfma_f32_16x16x32_bf16 v[30:33], v[152:155], v[204:207], v[30:33]
	v_mfma_f32_16x16x32_bf16 v[26:29], v[160:163], v[204:207], v[26:29]
	v_mfma_f32_16x16x32_bf16 v[14:17], v[152:155], v[212:215], v[14:17]
	v_mfma_f32_16x16x32_bf16 v[10:13], v[160:163], v[212:215], v[10:13]
	v_mfma_f32_16x16x32_bf16 v[54:57], v[166:169], v[182:185], v[54:57]
	v_mfma_f32_16x16x32_bf16 v[50:53], v[174:177], v[182:185], v[50:53]
	v_mfma_f32_16x16x32_bf16 v[38:41], v[166:169], v[192:195], v[38:41]
	v_mfma_f32_16x16x32_bf16 v[34:37], v[174:177], v[192:195], v[34:37]
	v_mfma_f32_16x16x32_bf16 v[22:25], v[166:169], v[200:203], v[22:25]
	v_mfma_f32_16x16x32_bf16 v[18:21], v[174:177], v[200:203], v[18:21]
	v_mfma_f32_16x16x32_bf16 v[6:9], v[166:169], v[208:211], v[6:9]
	v_mfma_f32_16x16x32_bf16 v[2:5], v[174:177], v[208:211], v[2:5]
	v_mfma_f32_16x16x32_bf16 v[54:57], v[170:173], v[188:191], v[54:57]
	v_mfma_f32_16x16x32_bf16 v[50:53], v[178:181], v[188:191], v[50:53]
	v_mfma_f32_16x16x32_bf16 v[38:41], v[170:173], v[196:199], v[38:41]
	v_mfma_f32_16x16x32_bf16 v[34:37], v[178:181], v[196:199], v[34:37]
	v_mfma_f32_16x16x32_bf16 v[22:25], v[170:173], v[204:207], v[22:25]
	v_mfma_f32_16x16x32_bf16 v[18:21], v[178:181], v[204:207], v[18:21]
	v_mfma_f32_16x16x32_bf16 v[6:9], v[170:173], v[212:215], v[6:9]
	v_mfma_f32_16x16x32_bf16 v[2:5], v[178:181], v[212:215], v[2:5]
	s_barrier
	s_setprio 0
	s_add_i32 s86, s86, 2
	s_add_u32 s84, s84, 0x100
	s_addc_u32 s85, s85, 0
	s_add_u32 s70, s70, 0x100
	s_addc_u32 s71, s71, 0
	s_cmp_gt_u32 s86, 61
	s_cbranch_scc0 .LBB0_1689
	s_and_b64 vcc, exec, s[44:45]
	s_cbranch_vccz .LBB0_1692
	s_barrier

.LBB0_1771:
	ds_read_b128 v[130:133], v185
	ds_read_b128 v[134:137], v185 offset:1024
	ds_read_b128 v[138:141], v185 offset:2048
	ds_read_b128 v[142:145], v185 offset:3072
	ds_read_b128 v[146:149], v188
	ds_read_b128 v[150:153], v188 offset:1024
	ds_read_b128 v[168:171], v188 offset:2048
	ds_read_b128 v[172:175], v188 offset:3072
	s_add_u32 s6, s8, 0xfff80080
	s_addc_u32 s7, s9, -1
	s_cmp_eq_u32 s71, 28
	s_cselect_b32 s81, s26, s7
	s_cselect_b32 s80, s27, s6
	s_cselect_b32 s79, s28, s41
	s_cselect_b32 s78, s29, s40
	s_add_i32 m0, s11, 0xc000
	ds_read_b128 v[192:195], v189
	ds_read_b128 v[196:199], v189 offset:1024
	ds_read_b128 v[200:203], v189 offset:2048
	ds_read_b128 v[204:207], v189 offset:3072
	ds_read_b128 v[208:211], v189 offset:4096
	ds_read_b128 v[212:215], v189 offset:5120
	ds_read_b128 v[216:219], v189 offset:6144
	ds_read_b128 v[220:223], v189 offset:7168
	global_load_lds_dwordx4 v162, s[8:9]
	s_add_i32 m0, s11, 0xe000
	s_nop 0
	global_load_lds_dwordx4 v166, s[8:9]
	s_waitcnt vmcnt(8)
	s_waitcnt lgkmcnt(0)
	s_setprio 1
	s_barrier
	v_mfma_i32_16x16x64_i8 v[126:129], v[130:133], v[192:195], v[126:129]
	v_mfma_i32_16x16x64_i8 v[122:125], v[138:141], v[192:195], v[122:125]
	v_mfma_i32_16x16x64_i8 v[110:113], v[130:133], v[200:203], v[110:113]
	v_mfma_i32_16x16x64_i8 v[106:109], v[138:141], v[200:203], v[106:109]
	v_mfma_i32_16x16x64_i8 v[94:97], v[130:133], v[208:211], v[94:97]
	v_mfma_i32_16x16x64_i8 v[90:93], v[138:141], v[208:211], v[90:93]
	v_mfma_i32_16x16x64_i8 v[78:81], v[130:133], v[216:219], v[78:81]
	v_mfma_i32_16x16x64_i8 v[74:77], v[138:141], v[216:219], v[74:77]
	v_mfma_i32_16x16x64_i8 v[126:129], v[134:137], v[196:199], v[126:129]
	v_mfma_i32_16x16x64_i8 v[122:125], v[142:145], v[196:199], v[122:125]
	v_mfma_i32_16x16x64_i8 v[110:113], v[134:137], v[204:207], v[110:113]
	v_mfma_i32_16x16x64_i8 v[106:109], v[142:145], v[204:207], v[106:109]
	v_mfma_i32_16x16x64_i8 v[94:97], v[134:137], v[212:215], v[94:97]
	v_mfma_i32_16x16x64_i8 v[90:93], v[142:145], v[212:215], v[90:93]
	v_mfma_i32_16x16x64_i8 v[78:81], v[134:137], v[220:223], v[78:81]
	v_mfma_i32_16x16x64_i8 v[74:77], v[142:145], v[220:223], v[74:77]
	v_mfma_i32_16x16x64_i8 v[118:121], v[146:149], v[192:195], v[118:121]
	v_mfma_i32_16x16x64_i8 v[114:117], v[168:171], v[192:195], v[114:117]
	v_mfma_i32_16x16x64_i8 v[102:105], v[146:149], v[200:203], v[102:105]
	v_mfma_i32_16x16x64_i8 v[98:101], v[168:171], v[200:203], v[98:101]
	v_mfma_i32_16x16x64_i8 v[86:89], v[146:149], v[208:211], v[86:89]
	v_mfma_i32_16x16x64_i8 v[82:85], v[168:171], v[208:211], v[82:85]
	v_mfma_i32_16x16x64_i8 v[70:73], v[146:149], v[216:219], v[70:73]
	v_mfma_i32_16x16x64_i8 v[66:69], v[168:171], v[216:219], v[66:69]
	v_mfma_i32_16x16x64_i8 v[118:121], v[150:153], v[196:199], v[118:121]
	v_mfma_i32_16x16x64_i8 v[114:117], v[172:175], v[196:199], v[114:117]
	v_mfma_i32_16x16x64_i8 v[102:105], v[150:153], v[204:207], v[102:105]
	v_mfma_i32_16x16x64_i8 v[98:101], v[172:175], v[204:207], v[98:101]
	v_mfma_i32_16x16x64_i8 v[86:89], v[150:153], v[212:215], v[86:89]
	v_mfma_i32_16x16x64_i8 v[82:85], v[172:175], v[212:215], v[82:85]
	v_mfma_i32_16x16x64_i8 v[70:73], v[150:153], v[220:223], v[70:73]
	v_mfma_i32_16x16x64_i8 v[66:69], v[172:175], v[220:223], v[66:69]
	s_barrier
	s_setprio 0
	s_add_i32 s6, s87, s67
	v_lshl_add_u64 v[176:177], s[78:79], 0, v[156:157]
	s_mov_b32 m0, s6
	ds_read_b128 v[192:195], v189 offset:16384
	ds_read_b128 v[196:199], v189 offset:17408
	ds_read_b128 v[200:203], v189 offset:18432
	ds_read_b128 v[204:207], v189 offset:19456
	ds_read_b128 v[208:211], v189 offset:20480
	ds_read_b128 v[212:215], v189 offset:21504
	ds_read_b128 v[216:219], v189 offset:22528
	ds_read_b128 v[220:223], v189 offset:23552
	global_load_lds_dwordx4 v[176:177], off
	s_add_i32 m0, s6, 0x2000
	s_add_u32 s6, s78, 0x80000
	v_lshl_add_u64 v[182:183], s[78:79], 0, v[160:161]
	s_addc_u32 s7, s79, 0
	s_add_i32 s16, s88, s67
	global_load_lds_dwordx4 v[182:183], off
	s_mov_b32 m0, s16
	v_lshl_add_u64 v[226:227], s[80:81], 0, v[158:159]
	global_load_lds_dwordx4 v156, s[6:7]
	s_add_i32 m0, s16, 0x2000
	s_nop 0
	global_load_lds_dwordx4 v160, s[6:7]
	v_lshl_add_u64 v[224:225], s[80:81], 0, v[154:155]
	s_mov_b32 m0, s11
	s_nop 0
	global_load_lds_dwordx4 v[224:225], off
	s_mov_b32 m0, s56
	s_nop 0
	global_load_lds_dwordx4 v[226:227], off
	s_waitcnt vmcnt(8)
	s_waitcnt lgkmcnt(0)
	s_setprio 1
	s_barrier
	v_mfma_i32_16x16x64_i8 v[62:65], v[130:133], v[192:195], v[62:65]
	v_mfma_i32_16x16x64_i8 v[58:61], v[138:141], v[192:195], v[58:61]
	v_mfma_i32_16x16x64_i8 v[46:49], v[130:133], v[200:203], v[46:49]
	v_mfma_i32_16x16x64_i8 v[42:45], v[138:141], v[200:203], v[42:45]
	v_mfma_i32_16x16x64_i8 v[30:33], v[130:133], v[208:211], v[30:33]
	v_mfma_i32_16x16x64_i8 v[26:29], v[138:141], v[208:211], v[26:29]
	v_mfma_i32_16x16x64_i8 v[14:17], v[130:133], v[216:219], v[14:17]
	v_mfma_i32_16x16x64_i8 v[10:13], v[138:141], v[216:219], v[10:13]
	v_mfma_i32_16x16x64_i8 v[62:65], v[134:137], v[196:199], v[62:65]
	v_mfma_i32_16x16x64_i8 v[58:61], v[142:145], v[196:199], v[58:61]
	v_mfma_i32_16x16x64_i8 v[46:49], v[134:137], v[204:207], v[46:49]
	v_mfma_i32_16x16x64_i8 v[42:45], v[142:145], v[204:207], v[42:45]
	v_mfma_i32_16x16x64_i8 v[30:33], v[134:137], v[212:215], v[30:33]
	v_mfma_i32_16x16x64_i8 v[26:29], v[142:145], v[212:215], v[26:29]
	v_mfma_i32_16x16x64_i8 v[14:17], v[134:137], v[220:223], v[14:17]
	v_mfma_i32_16x16x64_i8 v[10:13], v[142:145], v[220:223], v[10:13]
	v_mfma_i32_16x16x64_i8 v[54:57], v[146:149], v[192:195], v[54:57]
	v_mfma_i32_16x16x64_i8 v[50:53], v[168:171], v[192:195], v[50:53]
	v_mfma_i32_16x16x64_i8 v[38:41], v[146:149], v[200:203], v[38:41]
	v_mfma_i32_16x16x64_i8 v[34:37], v[168:171], v[200:203], v[34:37]
	v_mfma_i32_16x16x64_i8 v[22:25], v[146:149], v[208:211], v[22:25]
	v_mfma_i32_16x16x64_i8 v[18:21], v[168:171], v[208:211], v[18:21]
	v_mfma_i32_16x16x64_i8 v[6:9], v[146:149], v[216:219], v[6:9]
	v_mfma_i32_16x16x64_i8 v[2:5], v[168:171], v[216:219], v[2:5]
	v_mfma_i32_16x16x64_i8 v[54:57], v[150:153], v[196:199], v[54:57]
	v_mfma_i32_16x16x64_i8 v[50:53], v[172:175], v[196:199], v[50:53]
	v_mfma_i32_16x16x64_i8 v[38:41], v[150:153], v[204:207], v[38:41]
	v_mfma_i32_16x16x64_i8 v[34:37], v[172:175], v[204:207], v[34:37]
	v_mfma_i32_16x16x64_i8 v[22:25], v[150:153], v[212:215], v[22:25]
	v_mfma_i32_16x16x64_i8 v[18:21], v[172:175], v[212:215], v[18:21]
	v_mfma_i32_16x16x64_i8 v[6:9], v[150:153], v[220:223], v[6:9]
	v_mfma_i32_16x16x64_i8 v[2:5], v[172:175], v[220:223], v[2:5]
	s_barrier
	s_setprio 0
	s_add_i32 s16, 0, 0x18000
	s_add_i32 s17, 0, 0x1c000
	v_add_u32_e32 v142, s16, v179
	v_add_u32_e32 v172, s17, v179
	ds_read_b128 v[130:133], v142
	ds_read_b128 v[134:137], v142 offset:1024
	ds_read_b128 v[138:141], v142 offset:2048
	ds_read_b128 v[142:145], v142 offset:3072
	ds_read_b128 v[146:149], v172
	ds_read_b128 v[150:153], v172 offset:1024
	ds_read_b128 v[168:171], v172 offset:2048
	ds_read_b128 v[172:175], v172 offset:3072
	s_add_u32 s6, s80, 0x80000
	s_addc_u32 s7, s81, 0
	s_mov_b32 m0, s57
	ds_read_b128 v[192:195], v189 offset:32768
	ds_read_b128 v[196:199], v189 offset:33792
	ds_read_b128 v[200:203], v189 offset:34816
	ds_read_b128 v[204:207], v189 offset:35840
	ds_read_b128 v[208:211], v189 offset:36864
	ds_read_b128 v[212:215], v189 offset:37888
	ds_read_b128 v[216:219], v189 offset:38912
	ds_read_b128 v[220:223], v189 offset:39936
	global_load_lds_dwordx4 v154, s[6:7]
	s_mov_b32 m0, s82
	s_nop 0
	global_load_lds_dwordx4 v158, s[6:7]
	s_waitcnt vmcnt(8)
	s_waitcnt lgkmcnt(0)
	s_setprio 1
	s_barrier
	v_mfma_i32_16x16x64_i8 v[126:129], v[130:133], v[192:195], v[126:129]
	v_mfma_i32_16x16x64_i8 v[122:125], v[138:141], v[192:195], v[122:125]
	v_mfma_i32_16x16x64_i8 v[110:113], v[130:133], v[200:203], v[110:113]
	v_mfma_i32_16x16x64_i8 v[106:109], v[138:141], v[200:203], v[106:109]
	v_mfma_i32_16x16x64_i8 v[94:97], v[130:133], v[208:211], v[94:97]
	v_mfma_i32_16x16x64_i8 v[90:93], v[138:141], v[208:211], v[90:93]
	v_mfma_i32_16x16x64_i8 v[78:81], v[130:133], v[216:219], v[78:81]
	v_mfma_i32_16x16x64_i8 v[74:77], v[138:141], v[216:219], v[74:77]
	v_mfma_i32_16x16x64_i8 v[126:129], v[134:137], v[196:199], v[126:129]
	v_mfma_i32_16x16x64_i8 v[122:125], v[142:145], v[196:199], v[122:125]
	v_mfma_i32_16x16x64_i8 v[110:113], v[134:137], v[204:207], v[110:113]
	v_mfma_i32_16x16x64_i8 v[106:109], v[142:145], v[204:207], v[106:109]
	v_mfma_i32_16x16x64_i8 v[94:97], v[134:137], v[212:215], v[94:97]
	v_mfma_i32_16x16x64_i8 v[90:93], v[142:145], v[212:215], v[90:93]
	v_mfma_i32_16x16x64_i8 v[78:81], v[134:137], v[220:223], v[78:81]
	v_mfma_i32_16x16x64_i8 v[74:77], v[142:145], v[220:223], v[74:77]
	v_mfma_i32_16x16x64_i8 v[118:121], v[146:149], v[192:195], v[118:121]
	v_mfma_i32_16x16x64_i8 v[114:117], v[168:171], v[192:195], v[114:117]
	v_mfma_i32_16x16x64_i8 v[102:105], v[146:149], v[200:203], v[102:105]
	v_mfma_i32_16x16x64_i8 v[98:101], v[168:171], v[200:203], v[98:101]
	v_mfma_i32_16x16x64_i8 v[86:89], v[146:149], v[208:211], v[86:89]
	v_mfma_i32_16x16x64_i8 v[82:85], v[168:171], v[208:211], v[82:85]
	v_mfma_i32_16x16x64_i8 v[70:73], v[146:149], v[216:219], v[70:73]
	v_mfma_i32_16x16x64_i8 v[66:69], v[168:171], v[216:219], v[66:69]
	v_mfma_i32_16x16x64_i8 v[118:121], v[150:153], v[196:199], v[118:121]
	v_mfma_i32_16x16x64_i8 v[114:117], v[172:175], v[196:199], v[114:117]
	v_mfma_i32_16x16x64_i8 v[102:105], v[150:153], v[204:207], v[102:105]
	v_mfma_i32_16x16x64_i8 v[98:101], v[172:175], v[204:207], v[98:101]
	v_mfma_i32_16x16x64_i8 v[86:89], v[150:153], v[212:215], v[86:89]
	v_mfma_i32_16x16x64_i8 v[82:85], v[172:175], v[212:215], v[82:85]
	v_mfma_i32_16x16x64_i8 v[70:73], v[150:153], v[220:223], v[70:73]
	v_mfma_i32_16x16x64_i8 v[66:69], v[172:175], v[220:223], v[66:69]
	s_barrier
	s_setprio 0
	s_add_i32 s6, s16, s67
	v_lshl_add_u64 v[176:177], v[176:177], 0, s[62:63]
	s_mov_b32 m0, s6
	ds_read_b128 v[192:195], v189 offset:49152
	ds_read_b128 v[196:199], v189 offset:50176
	ds_read_b128 v[200:203], v189 offset:51200
	ds_read_b128 v[204:207], v189 offset:52224
	ds_read_b128 v[208:211], v189 offset:53248
	ds_read_b128 v[212:215], v189 offset:54272
	ds_read_b128 v[216:219], v189 offset:55296
	ds_read_b128 v[220:223], v189 offset:56320
	global_load_lds_dwordx4 v[176:177], off
	s_add_i32 m0, s6, 0x2000
	s_add_u32 s6, s78, 0x80080
	v_lshl_add_u64 v[176:177], v[182:183], 0, s[62:63]
	s_addc_u32 s7, s79, 0
	s_add_i32 s16, s17, s67
	global_load_lds_dwordx4 v[176:177], off
	s_mov_b32 m0, s16
	s_nop 0
	global_load_lds_dwordx4 v156, s[6:7]
	s_add_i32 m0, s16, 0x2000
	s_nop 0
	global_load_lds_dwordx4 v160, s[6:7]
	v_lshl_add_u64 v[176:177], v[224:225], 0, s[62:63]
	s_mov_b32 m0, s84
	s_nop 0
	global_load_lds_dwordx4 v[176:177], off
	v_lshl_add_u64 v[176:177], v[226:227], 0, s[62:63]
	s_mov_b32 m0, s85
	s_nop 0
	global_load_lds_dwordx4 v[176:177], off
	s_waitcnt vmcnt(8)
	s_waitcnt lgkmcnt(0)
	s_setprio 1
	s_barrier
	v_mfma_i32_16x16x64_i8 v[62:65], v[130:133], v[192:195], v[62:65]
	v_mfma_i32_16x16x64_i8 v[58:61], v[138:141], v[192:195], v[58:61]
	v_mfma_i32_16x16x64_i8 v[46:49], v[130:133], v[200:203], v[46:49]
	v_mfma_i32_16x16x64_i8 v[42:45], v[138:141], v[200:203], v[42:45]
	v_mfma_i32_16x16x64_i8 v[30:33], v[130:133], v[208:211], v[30:33]
	v_mfma_i32_16x16x64_i8 v[26:29], v[138:141], v[208:211], v[26:29]
	v_mfma_i32_16x16x64_i8 v[14:17], v[130:133], v[216:219], v[14:17]
	v_mfma_i32_16x16x64_i8 v[10:13], v[138:141], v[216:219], v[10:13]
	v_mfma_i32_16x16x64_i8 v[62:65], v[134:137], v[196:199], v[62:65]
	v_mfma_i32_16x16x64_i8 v[58:61], v[142:145], v[196:199], v[58:61]
	v_mfma_i32_16x16x64_i8 v[46:49], v[134:137], v[204:207], v[46:49]
	v_mfma_i32_16x16x64_i8 v[42:45], v[142:145], v[204:207], v[42:45]
	v_mfma_i32_16x16x64_i8 v[30:33], v[134:137], v[212:215], v[30:33]
	v_mfma_i32_16x16x64_i8 v[26:29], v[142:145], v[212:215], v[26:29]
	v_mfma_i32_16x16x64_i8 v[14:17], v[134:137], v[220:223], v[14:17]
	v_mfma_i32_16x16x64_i8 v[10:13], v[142:145], v[220:223], v[10:13]
	v_mfma_i32_16x16x64_i8 v[54:57], v[146:149], v[192:195], v[54:57]
	v_mfma_i32_16x16x64_i8 v[50:53], v[168:171], v[192:195], v[50:53]
	v_mfma_i32_16x16x64_i8 v[38:41], v[146:149], v[200:203], v[38:41]
	v_mfma_i32_16x16x64_i8 v[34:37], v[168:171], v[200:203], v[34:37]
	v_mfma_i32_16x16x64_i8 v[22:25], v[146:149], v[208:211], v[22:25]
	v_mfma_i32_16x16x64_i8 v[18:21], v[168:171], v[208:211], v[18:21]
	v_mfma_i32_16x16x64_i8 v[6:9], v[146:149], v[216:219], v[6:9]
	v_mfma_i32_16x16x64_i8 v[2:5], v[168:171], v[216:219], v[2:5]
	v_mfma_i32_16x16x64_i8 v[54:57], v[150:153], v[196:199], v[54:57]
	v_mfma_i32_16x16x64_i8 v[50:53], v[172:175], v[196:199], v[50:53]
	v_mfma_i32_16x16x64_i8 v[38:41], v[150:153], v[204:207], v[38:41]
	v_mfma_i32_16x16x64_i8 v[34:37], v[172:175], v[204:207], v[34:37]
	v_mfma_i32_16x16x64_i8 v[22:25], v[150:153], v[212:215], v[22:25]
	v_mfma_i32_16x16x64_i8 v[18:21], v[172:175], v[212:215], v[18:21]
	v_mfma_i32_16x16x64_i8 v[6:9], v[150:153], v[220:223], v[6:9]
	v_mfma_i32_16x16x64_i8 v[2:5], v[172:175], v[220:223], v[2:5]
	s_barrier
	s_setprio 0
	s_add_i32 s71, s71, 2
	s_add_u32 s8, s8, 0x100
	s_addc_u32 s9, s9, 0
	s_add_u32 s40, s40, 0x100
	s_addc_u32 s41, s41, 0
	s_cmp_gt_u32 s71, 29
	s_cbranch_scc0 .LBB0_1771
	s_and_b64 vcc, exec, s[64:65]
	s_cbranch_vccz .LBB0_1774
	s_barrier

.LBB0_1814:
	ds_read_b128 v[122:125], v195
	ds_read_b128 v[134:137], v195 offset:1024
	ds_read_b128 v[138:141], v195 offset:2048
	ds_read_b128 v[142:145], v195 offset:3072
	ds_read_b128 v[146:149], v196
	ds_read_b128 v[150:153], v196 offset:1024
	ds_read_b128 v[154:157], v196 offset:2048
	ds_read_b128 v[200:203], v196 offset:3072
	s_add_u32 s6, s78, 0xfff00080
	s_addc_u32 s7, s79, -1
	s_cmp_eq_u32 s61, 12
	s_cselect_b32 s83, s75, s7
	s_cselect_b32 s82, s74, s6
	s_cselect_b32 s81, s77, s27
	s_cselect_b32 s80, s76, s13
	s_add_i32 m0, s85, 0xc000
	ds_read_b128 v[204:207], v197
	ds_read_b128 v[208:211], v197 offset:1024
	ds_read_b128 v[212:215], v197 offset:2048
	ds_read_b128 v[216:219], v197 offset:3072
	ds_read_b128 v[220:223], v197 offset:4096
	ds_read_b128 v[224:227], v197 offset:5120
	ds_read_b128 v[228:231], v197 offset:6144
	ds_read_b128 v[232:235], v197 offset:7168
	global_load_lds_dwordx4 v174, s[78:79]
	s_add_i32 m0, s85, 0xe000
	s_nop 0
	global_load_lds_dwordx4 v172, s[78:79]
	s_waitcnt vmcnt(8)
	s_waitcnt lgkmcnt(0)
	s_setprio 1
	s_barrier
	v_mfma_f32_16x16x32_bf16 v[130:133], v[122:125], v[204:207], v[130:133]
	v_mfma_f32_16x16x32_bf16 v[126:129], v[138:141], v[204:207], v[126:129]
	v_mfma_f32_16x16x32_bf16 v[110:113], v[122:125], v[212:215], v[110:113]
	v_mfma_f32_16x16x32_bf16 v[106:109], v[138:141], v[212:215], v[106:109]
	v_mfma_f32_16x16x32_bf16 v[94:97], v[122:125], v[220:223], v[94:97]
	v_mfma_f32_16x16x32_bf16 v[90:93], v[138:141], v[220:223], v[90:93]
	v_mfma_f32_16x16x32_bf16 v[78:81], v[122:125], v[228:231], v[78:81]
	v_mfma_f32_16x16x32_bf16 v[74:77], v[138:141], v[228:231], v[74:77]
	v_mfma_f32_16x16x32_bf16 v[130:133], v[134:137], v[208:211], v[130:133]
	v_mfma_f32_16x16x32_bf16 v[126:129], v[142:145], v[208:211], v[126:129]
	v_mfma_f32_16x16x32_bf16 v[110:113], v[134:137], v[216:219], v[110:113]
	v_mfma_f32_16x16x32_bf16 v[106:109], v[142:145], v[216:219], v[106:109]
	v_mfma_f32_16x16x32_bf16 v[94:97], v[134:137], v[224:227], v[94:97]
	v_mfma_f32_16x16x32_bf16 v[90:93], v[142:145], v[224:227], v[90:93]
	v_mfma_f32_16x16x32_bf16 v[78:81], v[134:137], v[232:235], v[78:81]
	v_mfma_f32_16x16x32_bf16 v[74:77], v[142:145], v[232:235], v[74:77]
	v_mfma_f32_16x16x32_bf16 v[118:121], v[146:149], v[204:207], v[118:121]
	v_mfma_f32_16x16x32_bf16 v[114:117], v[154:157], v[204:207], v[114:117]
	v_mfma_f32_16x16x32_bf16 v[102:105], v[146:149], v[212:215], v[102:105]
	v_mfma_f32_16x16x32_bf16 v[98:101], v[154:157], v[212:215], v[98:101]
	v_mfma_f32_16x16x32_bf16 v[86:89], v[146:149], v[220:223], v[86:89]
	v_mfma_f32_16x16x32_bf16 v[82:85], v[154:157], v[220:223], v[82:85]
	v_mfma_f32_16x16x32_bf16 v[70:73], v[146:149], v[228:231], v[70:73]
	v_mfma_f32_16x16x32_bf16 v[66:69], v[154:157], v[228:231], v[66:69]
	v_mfma_f32_16x16x32_bf16 v[118:121], v[150:153], v[208:211], v[118:121]
	v_mfma_f32_16x16x32_bf16 v[114:117], v[200:203], v[208:211], v[114:117]
	v_mfma_f32_16x16x32_bf16 v[102:105], v[150:153], v[216:219], v[102:105]
	v_mfma_f32_16x16x32_bf16 v[98:101], v[200:203], v[216:219], v[98:101]
	v_mfma_f32_16x16x32_bf16 v[86:89], v[150:153], v[224:227], v[86:89]
	v_mfma_f32_16x16x32_bf16 v[82:85], v[200:203], v[224:227], v[82:85]
	v_mfma_f32_16x16x32_bf16 v[70:73], v[150:153], v[232:235], v[70:73]
	v_mfma_f32_16x16x32_bf16 v[66:69], v[200:203], v[232:235], v[66:69]
	s_barrier
	s_setprio 0
	s_add_i32 s6, s28, s84
	v_lshl_add_u64 v[176:177], s[80:81], 0, v[160:161]
	s_mov_b32 m0, s6
	ds_read_b128 v[204:207], v197 offset:16384
	ds_read_b128 v[208:211], v197 offset:17408
	ds_read_b128 v[212:215], v197 offset:18432
	ds_read_b128 v[216:219], v197 offset:19456
	ds_read_b128 v[220:223], v197 offset:20480
	ds_read_b128 v[224:227], v197 offset:21504
	ds_read_b128 v[228:231], v197 offset:22528
	ds_read_b128 v[232:235], v197 offset:23552
	global_load_lds_dwordx4 v[176:177], off
	s_add_i32 m0, s6, 0x2000
	s_add_u32 s6, s80, 0x100000
	v_lshl_add_u64 v[236:237], s[80:81], 0, v[166:167]
	s_addc_u32 s7, s81, 0
	s_add_i32 s16, s29, s84
	global_load_lds_dwordx4 v[236:237], off
	s_mov_b32 m0, s16
	v_lshl_add_u64 v[240:241], s[82:83], 0, v[162:163]
	global_load_lds_dwordx4 v160, s[6:7]
	s_add_i32 m0, s16, 0x2000
	s_nop 0
	global_load_lds_dwordx4 v166, s[6:7]
	v_lshl_add_u64 v[238:239], s[82:83], 0, v[158:159]
	s_mov_b32 m0, s85
	s_nop 0
	global_load_lds_dwordx4 v[238:239], off
	s_mov_b32 m0, s86
	s_nop 0
	global_load_lds_dwordx4 v[240:241], off
	s_waitcnt vmcnt(8)
	s_waitcnt lgkmcnt(0)
	s_setprio 1
	s_barrier
	v_mfma_f32_16x16x32_bf16 v[62:65], v[122:125], v[204:207], v[62:65]
	v_mfma_f32_16x16x32_bf16 v[58:61], v[138:141], v[204:207], v[58:61]
	v_mfma_f32_16x16x32_bf16 v[46:49], v[122:125], v[212:215], v[46:49]
	v_mfma_f32_16x16x32_bf16 v[42:45], v[138:141], v[212:215], v[42:45]
	v_mfma_f32_16x16x32_bf16 v[30:33], v[122:125], v[220:223], v[30:33]
	v_mfma_f32_16x16x32_bf16 v[26:29], v[138:141], v[220:223], v[26:29]
	v_mfma_f32_16x16x32_bf16 v[14:17], v[122:125], v[228:231], v[14:17]
	v_mfma_f32_16x16x32_bf16 v[10:13], v[138:141], v[228:231], v[10:13]
	v_mfma_f32_16x16x32_bf16 v[62:65], v[134:137], v[208:211], v[62:65]
	v_mfma_f32_16x16x32_bf16 v[58:61], v[142:145], v[208:211], v[58:61]
	v_mfma_f32_16x16x32_bf16 v[46:49], v[134:137], v[216:219], v[46:49]
	v_mfma_f32_16x16x32_bf16 v[42:45], v[142:145], v[216:219], v[42:45]
	v_mfma_f32_16x16x32_bf16 v[30:33], v[134:137], v[224:227], v[30:33]
	v_mfma_f32_16x16x32_bf16 v[26:29], v[142:145], v[224:227], v[26:29]
	v_mfma_f32_16x16x32_bf16 v[14:17], v[134:137], v[232:235], v[14:17]
	v_mfma_f32_16x16x32_bf16 v[10:13], v[142:145], v[232:235], v[10:13]
	v_mfma_f32_16x16x32_bf16 v[54:57], v[146:149], v[204:207], v[54:57]
	v_mfma_f32_16x16x32_bf16 v[50:53], v[154:157], v[204:207], v[50:53]
	v_mfma_f32_16x16x32_bf16 v[38:41], v[146:149], v[212:215], v[38:41]
	v_mfma_f32_16x16x32_bf16 v[34:37], v[154:157], v[212:215], v[34:37]
	v_mfma_f32_16x16x32_bf16 v[22:25], v[146:149], v[220:223], v[22:25]
	v_mfma_f32_16x16x32_bf16 v[18:21], v[154:157], v[220:223], v[18:21]
	v_mfma_f32_16x16x32_bf16 v[6:9], v[146:149], v[228:231], v[6:9]
	v_mfma_f32_16x16x32_bf16 v[2:5], v[154:157], v[228:231], v[2:5]
	v_mfma_f32_16x16x32_bf16 v[54:57], v[150:153], v[208:211], v[54:57]
	v_mfma_f32_16x16x32_bf16 v[50:53], v[200:203], v[208:211], v[50:53]
	v_mfma_f32_16x16x32_bf16 v[38:41], v[150:153], v[216:219], v[38:41]
	v_mfma_f32_16x16x32_bf16 v[34:37], v[200:203], v[216:219], v[34:37]
	v_mfma_f32_16x16x32_bf16 v[22:25], v[150:153], v[224:227], v[22:25]
	v_mfma_f32_16x16x32_bf16 v[18:21], v[200:203], v[224:227], v[18:21]
	v_mfma_f32_16x16x32_bf16 v[6:9], v[150:153], v[232:235], v[6:9]
	v_mfma_f32_16x16x32_bf16 v[2:5], v[200:203], v[232:235], v[2:5]
	s_barrier
	s_setprio 0
	s_add_i32 s16, 0, 0x18000
	s_add_i32 s17, 0, 0x1c000
	v_add_u32_e32 v142, s16, v171
	v_add_u32_e32 v168, s17, v171
	ds_read_b128 v[122:125], v142
	ds_read_b128 v[134:137], v142 offset:1024
	ds_read_b128 v[138:141], v142 offset:2048
	ds_read_b128 v[142:145], v142 offset:3072
	ds_read_b128 v[146:149], v168
	ds_read_b128 v[150:153], v168 offset:1024
	ds_read_b128 v[154:157], v168 offset:2048
	ds_read_b128 v[200:203], v168 offset:3072
	s_add_u32 s6, s82, 0x100000
	s_addc_u32 s7, s83, 0
	s_mov_b32 m0, s87
	ds_read_b128 v[204:207], v197 offset:32768
	ds_read_b128 v[208:211], v197 offset:33792
	ds_read_b128 v[212:215], v197 offset:34816
	ds_read_b128 v[216:219], v197 offset:35840
	ds_read_b128 v[220:223], v197 offset:36864
	ds_read_b128 v[224:227], v197 offset:37888
	ds_read_b128 v[228:231], v197 offset:38912
	ds_read_b128 v[232:235], v197 offset:39936
	global_load_lds_dwordx4 v158, s[6:7]
	s_mov_b32 m0, s88
	s_nop 0
	global_load_lds_dwordx4 v162, s[6:7]
	s_waitcnt vmcnt(8)
	s_waitcnt lgkmcnt(0)
	s_setprio 1
	s_barrier
	v_mfma_f32_16x16x32_bf16 v[130:133], v[122:125], v[204:207], v[130:133]
	v_mfma_f32_16x16x32_bf16 v[126:129], v[138:141], v[204:207], v[126:129]
	v_mfma_f32_16x16x32_bf16 v[110:113], v[122:125], v[212:215], v[110:113]
	v_mfma_f32_16x16x32_bf16 v[106:109], v[138:141], v[212:215], v[106:109]
	v_mfma_f32_16x16x32_bf16 v[94:97], v[122:125], v[220:223], v[94:97]
	v_mfma_f32_16x16x32_bf16 v[90:93], v[138:141], v[220:223], v[90:93]
	v_mfma_f32_16x16x32_bf16 v[78:81], v[122:125], v[228:231], v[78:81]
	v_mfma_f32_16x16x32_bf16 v[74:77], v[138:141], v[228:231], v[74:77]
	v_mfma_f32_16x16x32_bf16 v[130:133], v[134:137], v[208:211], v[130:133]
	v_mfma_f32_16x16x32_bf16 v[126:129], v[142:145], v[208:211], v[126:129]
	v_mfma_f32_16x16x32_bf16 v[110:113], v[134:137], v[216:219], v[110:113]
	v_mfma_f32_16x16x32_bf16 v[106:109], v[142:145], v[216:219], v[106:109]
	v_mfma_f32_16x16x32_bf16 v[94:97], v[134:137], v[224:227], v[94:97]
	v_mfma_f32_16x16x32_bf16 v[90:93], v[142:145], v[224:227], v[90:93]
	v_mfma_f32_16x16x32_bf16 v[78:81], v[134:137], v[232:235], v[78:81]
	v_mfma_f32_16x16x32_bf16 v[74:77], v[142:145], v[232:235], v[74:77]
	v_mfma_f32_16x16x32_bf16 v[118:121], v[146:149], v[204:207], v[118:121]
	v_mfma_f32_16x16x32_bf16 v[114:117], v[154:157], v[204:207], v[114:117]
	v_mfma_f32_16x16x32_bf16 v[102:105], v[146:149], v[212:215], v[102:105]
	v_mfma_f32_16x16x32_bf16 v[98:101], v[154:157], v[212:215], v[98:101]
	v_mfma_f32_16x16x32_bf16 v[86:89], v[146:149], v[220:223], v[86:89]
	v_mfma_f32_16x16x32_bf16 v[82:85], v[154:157], v[220:223], v[82:85]
	v_mfma_f32_16x16x32_bf16 v[70:73], v[146:149], v[228:231], v[70:73]
	v_mfma_f32_16x16x32_bf16 v[66:69], v[154:157], v[228:231], v[66:69]
	v_mfma_f32_16x16x32_bf16 v[118:121], v[150:153], v[208:211], v[118:121]
	v_mfma_f32_16x16x32_bf16 v[114:117], v[200:203], v[208:211], v[114:117]
	v_mfma_f32_16x16x32_bf16 v[102:105], v[150:153], v[216:219], v[102:105]
	v_mfma_f32_16x16x32_bf16 v[98:101], v[200:203], v[216:219], v[98:101]
	v_mfma_f32_16x16x32_bf16 v[86:89], v[150:153], v[224:227], v[86:89]
	v_mfma_f32_16x16x32_bf16 v[82:85], v[200:203], v[224:227], v[82:85]
	v_mfma_f32_16x16x32_bf16 v[70:73], v[150:153], v[232:235], v[70:73]
	v_mfma_f32_16x16x32_bf16 v[66:69], v[200:203], v[232:235], v[66:69]
	s_barrier
	s_setprio 0
	s_add_i32 s6, s16, s84
	v_lshl_add_u64 v[176:177], v[176:177], 0, s[66:67]
	s_mov_b32 m0, s6
	ds_read_b128 v[204:207], v197 offset:49152
	ds_read_b128 v[208:211], v197 offset:50176
	ds_read_b128 v[212:215], v197 offset:51200
	ds_read_b128 v[216:219], v197 offset:52224
	ds_read_b128 v[220:223], v197 offset:53248
	ds_read_b128 v[224:227], v197 offset:54272
	ds_read_b128 v[228:231], v197 offset:55296
	ds_read_b128 v[232:235], v197 offset:56320
	global_load_lds_dwordx4 v[176:177], off
	s_add_i32 m0, s6, 0x2000
	s_add_u32 s6, s80, 0x100080
	v_lshl_add_u64 v[176:177], v[236:237], 0, s[66:67]
	s_addc_u32 s7, s81, 0
	s_add_i32 s16, s17, s84
	global_load_lds_dwordx4 v[176:177], off
	s_mov_b32 m0, s16
	s_nop 0
	global_load_lds_dwordx4 v160, s[6:7]
	s_add_i32 m0, s16, 0x2000
	s_nop 0
	global_load_lds_dwordx4 v166, s[6:7]
	v_lshl_add_u64 v[176:177], v[238:239], 0, s[66:67]
	s_mov_b32 m0, s94
	s_nop 0
	global_load_lds_dwordx4 v[176:177], off
	v_lshl_add_u64 v[176:177], v[240:241], 0, s[66:67]
	s_mov_b32 m0, s95
	s_nop 0
	global_load_lds_dwordx4 v[176:177], off
	s_waitcnt vmcnt(8)
	s_waitcnt lgkmcnt(0)
	s_setprio 1
	s_barrier
	v_mfma_f32_16x16x32_bf16 v[62:65], v[122:125], v[204:207], v[62:65]
	v_mfma_f32_16x16x32_bf16 v[58:61], v[138:141], v[204:207], v[58:61]
	v_mfma_f32_16x16x32_bf16 v[46:49], v[122:125], v[212:215], v[46:49]
	v_mfma_f32_16x16x32_bf16 v[42:45], v[138:141], v[212:215], v[42:45]
	v_mfma_f32_16x16x32_bf16 v[30:33], v[122:125], v[220:223], v[30:33]
	v_mfma_f32_16x16x32_bf16 v[26:29], v[138:141], v[220:223], v[26:29]
	v_mfma_f32_16x16x32_bf16 v[14:17], v[122:125], v[228:231], v[14:17]
	v_mfma_f32_16x16x32_bf16 v[10:13], v[138:141], v[228:231], v[10:13]
	v_mfma_f32_16x16x32_bf16 v[62:65], v[134:137], v[208:211], v[62:65]
	v_mfma_f32_16x16x32_bf16 v[58:61], v[142:145], v[208:211], v[58:61]
	v_mfma_f32_16x16x32_bf16 v[46:49], v[134:137], v[216:219], v[46:49]
	v_mfma_f32_16x16x32_bf16 v[42:45], v[142:145], v[216:219], v[42:45]
	v_mfma_f32_16x16x32_bf16 v[30:33], v[134:137], v[224:227], v[30:33]
	v_mfma_f32_16x16x32_bf16 v[26:29], v[142:145], v[224:227], v[26:29]
	v_mfma_f32_16x16x32_bf16 v[14:17], v[134:137], v[232:235], v[14:17]
	v_mfma_f32_16x16x32_bf16 v[10:13], v[142:145], v[232:235], v[10:13]
	v_mfma_f32_16x16x32_bf16 v[54:57], v[146:149], v[204:207], v[54:57]
	v_mfma_f32_16x16x32_bf16 v[50:53], v[154:157], v[204:207], v[50:53]
	v_mfma_f32_16x16x32_bf16 v[38:41], v[146:149], v[212:215], v[38:41]
	v_mfma_f32_16x16x32_bf16 v[34:37], v[154:157], v[212:215], v[34:37]
	v_mfma_f32_16x16x32_bf16 v[22:25], v[146:149], v[220:223], v[22:25]
	v_mfma_f32_16x16x32_bf16 v[18:21], v[154:157], v[220:223], v[18:21]
	v_mfma_f32_16x16x32_bf16 v[6:9], v[146:149], v[228:231], v[6:9]
	v_mfma_f32_16x16x32_bf16 v[2:5], v[154:157], v[228:231], v[2:5]
	v_mfma_f32_16x16x32_bf16 v[54:57], v[150:153], v[208:211], v[54:57]
	v_mfma_f32_16x16x32_bf16 v[50:53], v[200:203], v[208:211], v[50:53]
	v_mfma_f32_16x16x32_bf16 v[38:41], v[150:153], v[216:219], v[38:41]
	v_mfma_f32_16x16x32_bf16 v[34:37], v[200:203], v[216:219], v[34:37]
	v_mfma_f32_16x16x32_bf16 v[22:25], v[150:153], v[224:227], v[22:25]
	v_mfma_f32_16x16x32_bf16 v[18:21], v[200:203], v[224:227], v[18:21]
	v_mfma_f32_16x16x32_bf16 v[6:9], v[150:153], v[232:235], v[6:9]
	v_mfma_f32_16x16x32_bf16 v[2:5], v[200:203], v[232:235], v[2:5]
	s_barrier
	s_setprio 0
	s_add_i32 s61, s61, 2
	s_add_u32 s13, s13, 0x100
	s_addc_u32 s27, s27, 0
	s_add_u32 s78, s78, 0x100
	s_addc_u32 s79, s79, 0
	s_cmp_gt_u32 s61, 13
	s_cbranch_scc0 .LBB0_1814
	s_and_b64 vcc, exec, s[68:69]
	s_cbranch_vccz .LBB0_1817
	s_barrier

.LBB0_1923:
	s_add_u32 s16, s76, s65
	s_addc_u32 s17, s77, 0
	s_add_u32 s67, s16, 0x100
	s_addc_u32 s80, s17, 0
	s_and_b64 s[6:7], s[78:79], exec
	s_cselect_b32 s83, s69, s80
	s_cselect_b32 s82, s68, s67
	s_add_u32 s6, s74, s65
	s_addc_u32 s7, s75, 0
	s_add_u32 s65, s6, 0x100
	s_addc_u32 s67, s7, 0
	s_and_b64 s[6:7], s[78:79], exec
	s_cselect_b32 s85, s71, s67
	s_cselect_b32 s84, s70, s65
	s_add_u32 s88, s16, 0x40080
	s_addc_u32 s89, s17, 0
	s_add_i32 s90, s94, s28
	s_waitcnt lgkmcnt(0)
	ds_read_b128 v[130:133], v169
	ds_read_b128 v[134:137], v169 offset:1024
	ds_read_b128 v[172:175], v169 offset:2048
	ds_read_b128 v[176:179], v169 offset:3072
	ds_read_b128 v[180:183], v170
	ds_read_b128 v[188:191], v170 offset:1024
	ds_read_b128 v[192:195], v170 offset:2048
	ds_read_b128 v[196:199], v170 offset:3072
	s_add_i32 m0, s13, 0xc000
	s_add_i32 s17, s13, 0xe000
	s_add_i32 s16, s90, 0x2000
	s_add_u32 s86, s84, 0x10000
	s_addc_u32 s87, s85, 0
	s_add_i32 s7, s95, s28
	s_add_i32 s6, s7, 0x2000
	s_add_i32 vcc_lo, 0, 0x18000
	s_add_i32 vcc_hi, 0, 0x1c000
	s_add_u32 s80, s82, 0x40000
	s_addc_u32 s81, s83, 0
	s_add_i32 s67, vcc_lo, s28
	s_add_i32 s91, s67, 0x2000
	s_add_u32 s78, s84, 0x10080
	s_addc_u32 s79, s85, 0
	s_add_i32 s97, vcc_hi, s28
	s_add_i32 s65, s97, 0x2000
	ds_read_b128 v[200:203], v171
	ds_read_b128 v[204:207], v171 offset:1024
	ds_read_b128 v[208:211], v171 offset:2048
	ds_read_b128 v[212:215], v171 offset:3072
	ds_read_b128 v[216:219], v171 offset:4096
	ds_read_b128 v[220:223], v171 offset:5120
	ds_read_b128 v[224:227], v171 offset:6144
	ds_read_b128 v[228:231], v171 offset:7168
	global_load_lds_dwordx4 v138, s[88:89]
	s_mov_b32 m0, s17
	s_nop 0
	global_load_lds_dwordx4 v142, s[88:89]
	s_waitcnt vmcnt(8)
	s_waitcnt lgkmcnt(0)
	s_setprio 1
	s_barrier
	v_mfma_f32_16x16x32_bf16 v[126:129], v[130:133], v[200:203], v[126:129]
	v_mfma_f32_16x16x32_bf16 v[122:125], v[172:175], v[200:203], v[122:125]
	v_mfma_f32_16x16x32_bf16 v[114:117], v[130:133], v[208:211], v[114:117]
	v_mfma_f32_16x16x32_bf16 v[106:109], v[172:175], v[208:211], v[106:109]
	v_mfma_f32_16x16x32_bf16 v[94:97], v[130:133], v[216:219], v[94:97]
	v_mfma_f32_16x16x32_bf16 v[90:93], v[172:175], v[216:219], v[90:93]
	v_mfma_f32_16x16x32_bf16 v[78:81], v[130:133], v[224:227], v[78:81]
	v_mfma_f32_16x16x32_bf16 v[74:77], v[172:175], v[224:227], v[74:77]
	v_mfma_f32_16x16x32_bf16 v[126:129], v[134:137], v[204:207], v[126:129]
	v_mfma_f32_16x16x32_bf16 v[122:125], v[176:179], v[204:207], v[122:125]
	v_mfma_f32_16x16x32_bf16 v[114:117], v[134:137], v[212:215], v[114:117]
	v_mfma_f32_16x16x32_bf16 v[106:109], v[176:179], v[212:215], v[106:109]
	v_mfma_f32_16x16x32_bf16 v[94:97], v[134:137], v[220:223], v[94:97]
	v_mfma_f32_16x16x32_bf16 v[90:93], v[176:179], v[220:223], v[90:93]
	v_mfma_f32_16x16x32_bf16 v[78:81], v[134:137], v[228:231], v[78:81]
	v_mfma_f32_16x16x32_bf16 v[74:77], v[176:179], v[228:231], v[74:77]
	v_mfma_f32_16x16x32_bf16 v[118:121], v[180:183], v[200:203], v[118:121]
	v_mfma_f32_16x16x32_bf16 v[110:113], v[192:195], v[200:203], v[110:113]
	v_mfma_f32_16x16x32_bf16 v[102:105], v[180:183], v[208:211], v[102:105]
	v_mfma_f32_16x16x32_bf16 v[98:101], v[192:195], v[208:211], v[98:101]
	v_mfma_f32_16x16x32_bf16 v[86:89], v[180:183], v[216:219], v[86:89]
	v_mfma_f32_16x16x32_bf16 v[82:85], v[192:195], v[216:219], v[82:85]
	v_mfma_f32_16x16x32_bf16 v[70:73], v[180:183], v[224:227], v[70:73]
	v_mfma_f32_16x16x32_bf16 v[66:69], v[192:195], v[224:227], v[66:69]
	v_mfma_f32_16x16x32_bf16 v[118:121], v[188:191], v[204:207], v[118:121]
	v_mfma_f32_16x16x32_bf16 v[110:113], v[196:199], v[204:207], v[110:113]
	v_mfma_f32_16x16x32_bf16 v[102:105], v[188:191], v[212:215], v[102:105]
	v_mfma_f32_16x16x32_bf16 v[98:101], v[196:199], v[212:215], v[98:101]
	v_mfma_f32_16x16x32_bf16 v[86:89], v[188:191], v[220:223], v[86:89]
	v_mfma_f32_16x16x32_bf16 v[82:85], v[196:199], v[220:223], v[82:85]
	v_mfma_f32_16x16x32_bf16 v[70:73], v[188:191], v[228:231], v[70:73]
	v_mfma_f32_16x16x32_bf16 v[66:69], v[196:199], v[228:231], v[66:69]
	s_barrier
	s_setprio 0
	s_mov_b32 m0, s90
	v_lshl_add_u64 v[150:151], s[84:85], 0, v[140:141]
	ds_read_b128 v[200:203], v171 offset:16384
	ds_read_b128 v[204:207], v171 offset:17408
	ds_read_b128 v[208:211], v171 offset:18432
	ds_read_b128 v[212:215], v171 offset:19456
	ds_read_b128 v[216:219], v171 offset:20480
	ds_read_b128 v[220:223], v171 offset:21504
	ds_read_b128 v[224:227], v171 offset:22528
	ds_read_b128 v[228:231], v171 offset:23552
	global_load_lds_dwordx4 v[150:151], off
	v_lshl_add_u64 v[184:185], s[84:85], 0, v[144:145]
	s_mov_b32 m0, s16
	s_nop 0
	global_load_lds_dwordx4 v[184:185], off
	s_mov_b32 m0, s7
	v_lshl_add_u64 v[234:235], s[82:83], 0, v[142:143]
	global_load_lds_dwordx4 v140, s[86:87]
	s_mov_b32 m0, s6
	s_nop 0
	global_load_lds_dwordx4 v144, s[86:87]
	v_lshl_add_u64 v[232:233], s[82:83], 0, v[138:139]
	s_mov_b32 m0, s13
	s_nop 0
	global_load_lds_dwordx4 v[232:233], off
	s_mov_b32 m0, s29
	s_nop 0
	global_load_lds_dwordx4 v[234:235], off
	s_waitcnt vmcnt(8)
	s_waitcnt lgkmcnt(0)
	s_setprio 1
	s_barrier
	v_mfma_f32_16x16x32_bf16 v[62:65], v[130:133], v[200:203], v[62:65]
	v_mfma_f32_16x16x32_bf16 v[58:61], v[172:175], v[200:203], v[58:61]
	v_mfma_f32_16x16x32_bf16 v[46:49], v[130:133], v[208:211], v[46:49]
	v_mfma_f32_16x16x32_bf16 v[42:45], v[172:175], v[208:211], v[42:45]
	v_mfma_f32_16x16x32_bf16 v[30:33], v[130:133], v[216:219], v[30:33]
	v_mfma_f32_16x16x32_bf16 v[26:29], v[172:175], v[216:219], v[26:29]
	v_mfma_f32_16x16x32_bf16 v[14:17], v[130:133], v[224:227], v[14:17]
	v_mfma_f32_16x16x32_bf16 v[10:13], v[172:175], v[224:227], v[10:13]
	v_mfma_f32_16x16x32_bf16 v[62:65], v[134:137], v[204:207], v[62:65]
	v_mfma_f32_16x16x32_bf16 v[58:61], v[176:179], v[204:207], v[58:61]
	v_mfma_f32_16x16x32_bf16 v[46:49], v[134:137], v[212:215], v[46:49]
	v_mfma_f32_16x16x32_bf16 v[42:45], v[176:179], v[212:215], v[42:45]
	v_mfma_f32_16x16x32_bf16 v[30:33], v[134:137], v[220:223], v[30:33]
	v_mfma_f32_16x16x32_bf16 v[26:29], v[176:179], v[220:223], v[26:29]
	v_mfma_f32_16x16x32_bf16 v[14:17], v[134:137], v[228:231], v[14:17]
	v_mfma_f32_16x16x32_bf16 v[10:13], v[176:179], v[228:231], v[10:13]
	v_mfma_f32_16x16x32_bf16 v[54:57], v[180:183], v[200:203], v[54:57]
	v_mfma_f32_16x16x32_bf16 v[50:53], v[192:195], v[200:203], v[50:53]
	v_mfma_f32_16x16x32_bf16 v[38:41], v[180:183], v[208:211], v[38:41]
	v_mfma_f32_16x16x32_bf16 v[34:37], v[192:195], v[208:211], v[34:37]
	v_mfma_f32_16x16x32_bf16 v[22:25], v[180:183], v[216:219], v[22:25]
	v_mfma_f32_16x16x32_bf16 v[18:21], v[192:195], v[216:219], v[18:21]
	v_mfma_f32_16x16x32_bf16 v[6:9], v[180:183], v[224:227], v[6:9]
	v_mfma_f32_16x16x32_bf16 v[2:5], v[192:195], v[224:227], v[2:5]
	v_mfma_f32_16x16x32_bf16 v[54:57], v[188:191], v[204:207], v[54:57]
	v_mfma_f32_16x16x32_bf16 v[50:53], v[196:199], v[204:207], v[50:53]
	v_mfma_f32_16x16x32_bf16 v[38:41], v[188:191], v[212:215], v[38:41]
	v_mfma_f32_16x16x32_bf16 v[34:37], v[196:199], v[212:215], v[34:37]
	v_mfma_f32_16x16x32_bf16 v[22:25], v[188:191], v[220:223], v[22:25]
	v_mfma_f32_16x16x32_bf16 v[18:21], v[196:199], v[220:223], v[18:21]
	v_mfma_f32_16x16x32_bf16 v[6:9], v[188:191], v[228:231], v[6:9]
	v_mfma_f32_16x16x32_bf16 v[2:5], v[196:199], v[228:231], v[2:5]
	s_barrier
	s_setprio 0
	v_add_u32_e32 v176, vcc_lo, v153
	v_add_u32_e32 v186, vcc_hi, v153
	ds_read_b128 v[130:133], v176
	ds_read_b128 v[134:137], v176 offset:1024
	ds_read_b128 v[172:175], v176 offset:2048
	ds_read_b128 v[176:179], v176 offset:3072
	ds_read_b128 v[180:183], v186
	ds_read_b128 v[188:191], v186 offset:1024
	ds_read_b128 v[192:195], v186 offset:2048
	ds_read_b128 v[196:199], v186 offset:3072
	s_mov_b32 m0, s39
	ds_read_b128 v[200:203], v171 offset:32768
	ds_read_b128 v[204:207], v171 offset:33792
	ds_read_b128 v[208:211], v171 offset:34816
	ds_read_b128 v[212:215], v171 offset:35840
	ds_read_b128 v[216:219], v171 offset:36864
	ds_read_b128 v[220:223], v171 offset:37888
	ds_read_b128 v[224:227], v171 offset:38912
	ds_read_b128 v[228:231], v171 offset:39936
	global_load_lds_dwordx4 v138, s[80:81]
	s_mov_b32 m0, s40
	s_nop 0
	global_load_lds_dwordx4 v142, s[80:81]
	s_waitcnt vmcnt(8)
	s_waitcnt lgkmcnt(0)
	s_setprio 1
	s_barrier
	v_mfma_f32_16x16x32_bf16 v[126:129], v[130:133], v[200:203], v[126:129]
	v_mfma_f32_16x16x32_bf16 v[122:125], v[172:175], v[200:203], v[122:125]
	v_mfma_f32_16x16x32_bf16 v[114:117], v[130:133], v[208:211], v[114:117]
	v_mfma_f32_16x16x32_bf16 v[106:109], v[172:175], v[208:211], v[106:109]
	v_mfma_f32_16x16x32_bf16 v[94:97], v[130:133], v[216:219], v[94:97]
	v_mfma_f32_16x16x32_bf16 v[90:93], v[172:175], v[216:219], v[90:93]
	v_mfma_f32_16x16x32_bf16 v[78:81], v[130:133], v[224:227], v[78:81]
	v_mfma_f32_16x16x32_bf16 v[74:77], v[172:175], v[224:227], v[74:77]
	v_mfma_f32_16x16x32_bf16 v[126:129], v[134:137], v[204:207], v[126:129]
	v_mfma_f32_16x16x32_bf16 v[122:125], v[176:179], v[204:207], v[122:125]
	v_mfma_f32_16x16x32_bf16 v[114:117], v[134:137], v[212:215], v[114:117]
	v_mfma_f32_16x16x32_bf16 v[106:109], v[176:179], v[212:215], v[106:109]
	v_mfma_f32_16x16x32_bf16 v[94:97], v[134:137], v[220:223], v[94:97]
	v_mfma_f32_16x16x32_bf16 v[90:93], v[176:179], v[220:223], v[90:93]
	v_mfma_f32_16x16x32_bf16 v[78:81], v[134:137], v[228:231], v[78:81]
	v_mfma_f32_16x16x32_bf16 v[74:77], v[176:179], v[228:231], v[74:77]
	v_mfma_f32_16x16x32_bf16 v[118:121], v[180:183], v[200:203], v[118:121]
	v_mfma_f32_16x16x32_bf16 v[110:113], v[192:195], v[200:203], v[110:113]
	v_mfma_f32_16x16x32_bf16 v[102:105], v[180:183], v[208:211], v[102:105]
	v_mfma_f32_16x16x32_bf16 v[98:101], v[192:195], v[208:211], v[98:101]
	v_mfma_f32_16x16x32_bf16 v[86:89], v[180:183], v[216:219], v[86:89]
	v_mfma_f32_16x16x32_bf16 v[82:85], v[192:195], v[216:219], v[82:85]
	v_mfma_f32_16x16x32_bf16 v[70:73], v[180:183], v[224:227], v[70:73]
	v_mfma_f32_16x16x32_bf16 v[66:69], v[192:195], v[224:227], v[66:69]
	v_mfma_f32_16x16x32_bf16 v[118:121], v[188:191], v[204:207], v[118:121]
	v_mfma_f32_16x16x32_bf16 v[110:113], v[196:199], v[204:207], v[110:113]
	v_mfma_f32_16x16x32_bf16 v[102:105], v[188:191], v[212:215], v[102:105]
	v_mfma_f32_16x16x32_bf16 v[98:101], v[196:199], v[212:215], v[98:101]
	v_mfma_f32_16x16x32_bf16 v[86:89], v[188:191], v[220:223], v[86:89]
	v_mfma_f32_16x16x32_bf16 v[82:85], v[196:199], v[220:223], v[82:85]
	v_mfma_f32_16x16x32_bf16 v[70:73], v[188:191], v[228:231], v[70:73]
	v_mfma_f32_16x16x32_bf16 v[66:69], v[196:199], v[228:231], v[66:69]
	s_barrier
	s_setprio 0
	s_mov_b32 m0, s67
	v_lshl_add_u64 v[150:151], v[150:151], 0, s[60:61]
	ds_read_b128 v[200:203], v171 offset:49152
	ds_read_b128 v[204:207], v171 offset:50176
	ds_read_b128 v[208:211], v171 offset:51200
	ds_read_b128 v[212:215], v171 offset:52224
	ds_read_b128 v[216:219], v171 offset:53248
	ds_read_b128 v[220:223], v171 offset:54272
	ds_read_b128 v[224:227], v171 offset:55296
	ds_read_b128 v[228:231], v171 offset:56320
	global_load_lds_dwordx4 v[150:151], off
	v_lshl_add_u64 v[150:151], v[184:185], 0, s[60:61]
	s_mov_b32 m0, s91
	s_nop 0
	global_load_lds_dwordx4 v[150:151], off
	s_mov_b32 m0, s97
	s_nop 0
	global_load_lds_dwordx4 v140, s[78:79]
	s_mov_b32 m0, s65
	s_nop 0
	global_load_lds_dwordx4 v144, s[78:79]
	v_lshl_add_u64 v[150:151], v[232:233], 0, s[60:61]
	s_mov_b32 m0, s56
	s_nop 0
	global_load_lds_dwordx4 v[150:151], off
	v_lshl_add_u64 v[150:151], v[234:235], 0, s[60:61]
	s_mov_b32 m0, s57
	s_nop 0
	global_load_lds_dwordx4 v[150:151], off
	s_waitcnt vmcnt(8)
	s_waitcnt lgkmcnt(0)
	s_setprio 1
	s_barrier
	v_mfma_f32_16x16x32_bf16 v[62:65], v[130:133], v[200:203], v[62:65]
	v_mfma_f32_16x16x32_bf16 v[58:61], v[172:175], v[200:203], v[58:61]
	v_mfma_f32_16x16x32_bf16 v[46:49], v[130:133], v[208:211], v[46:49]
	v_mfma_f32_16x16x32_bf16 v[42:45], v[172:175], v[208:211], v[42:45]
	v_mfma_f32_16x16x32_bf16 v[30:33], v[130:133], v[216:219], v[30:33]
	v_mfma_f32_16x16x32_bf16 v[26:29], v[172:175], v[216:219], v[26:29]
	v_mfma_f32_16x16x32_bf16 v[14:17], v[130:133], v[224:227], v[14:17]
	v_mfma_f32_16x16x32_bf16 v[10:13], v[172:175], v[224:227], v[10:13]
	v_mfma_f32_16x16x32_bf16 v[62:65], v[134:137], v[204:207], v[62:65]
	v_mfma_f32_16x16x32_bf16 v[58:61], v[176:179], v[204:207], v[58:61]
	v_mfma_f32_16x16x32_bf16 v[46:49], v[134:137], v[212:215], v[46:49]
	v_mfma_f32_16x16x32_bf16 v[42:45], v[176:179], v[212:215], v[42:45]
	v_mfma_f32_16x16x32_bf16 v[30:33], v[134:137], v[220:223], v[30:33]
	v_mfma_f32_16x16x32_bf16 v[26:29], v[176:179], v[220:223], v[26:29]
	v_mfma_f32_16x16x32_bf16 v[14:17], v[134:137], v[228:231], v[14:17]
	v_mfma_f32_16x16x32_bf16 v[10:13], v[176:179], v[228:231], v[10:13]
	v_mfma_f32_16x16x32_bf16 v[54:57], v[180:183], v[200:203], v[54:57]
	v_mfma_f32_16x16x32_bf16 v[50:53], v[192:195], v[200:203], v[50:53]
	v_mfma_f32_16x16x32_bf16 v[38:41], v[180:183], v[208:211], v[38:41]
	v_mfma_f32_16x16x32_bf16 v[34:37], v[192:195], v[208:211], v[34:37]
	v_mfma_f32_16x16x32_bf16 v[22:25], v[180:183], v[216:219], v[22:25]
	v_mfma_f32_16x16x32_bf16 v[18:21], v[192:195], v[216:219], v[18:21]
	v_mfma_f32_16x16x32_bf16 v[6:9], v[180:183], v[224:227], v[6:9]
	v_mfma_f32_16x16x32_bf16 v[2:5], v[192:195], v[224:227], v[2:5]
	v_mfma_f32_16x16x32_bf16 v[54:57], v[188:191], v[204:207], v[54:57]
	v_mfma_f32_16x16x32_bf16 v[50:53], v[196:199], v[204:207], v[50:53]
	v_mfma_f32_16x16x32_bf16 v[38:41], v[188:191], v[212:215], v[38:41]
	v_mfma_f32_16x16x32_bf16 v[34:37], v[196:199], v[212:215], v[34:37]
	v_mfma_f32_16x16x32_bf16 v[22:25], v[188:191], v[220:223], v[22:25]
	v_mfma_f32_16x16x32_bf16 v[18:21], v[196:199], v[220:223], v[18:21]
	v_mfma_f32_16x16x32_bf16 v[6:9], v[188:191], v[228:231], v[6:9]
	v_mfma_f32_16x16x32_bf16 v[2:5], v[196:199], v[228:231], v[2:5]
	s_barrier
	s_setprio 0
	s_movk_i32 s65, 0x100
	s_andn2_b64 vcc, exec, s[10:11]
	s_mov_b64 s[78:79], -1
	s_mov_b64 s[10:11], 0
	s_cbranch_vccz .LBB0_1923
	s_and_b64 vcc, exec, s[62:63]
	s_cbranch_vccz .LBB0_1926
	s_barrier

.LBB0_1984:
	ds_read_b128 v[142:145], v149
	ds_read_b128 v[154:157], v149 offset:1024
	ds_read_b128 v[158:161], v149 offset:2048
	ds_read_b128 v[166:169], v149 offset:3072
	ds_read_b128 v[170:173], v150
	ds_read_b128 v[174:177], v150 offset:1024
	ds_read_b128 v[178:181], v150 offset:2048
	ds_read_b128 v[182:185], v150 offset:3072
	s_add_u32 s6, s72, 0xfff00080
	s_addc_u32 s7, s73, -1
	s_cmp_eq_u32 s83, 60
	s_cselect_b32 s77, s63, s7
	s_cselect_b32 s76, s69, s6
	s_cselect_b32 s75, s61, s82
	s_cselect_b32 s74, s80, s81
	s_add_i32 m0, s27, 0xc000
	ds_read_b128 v[188:191], v151
	ds_read_b128 v[192:195], v151 offset:1024
	ds_read_b128 v[196:199], v151 offset:2048
	ds_read_b128 v[200:203], v151 offset:3072
	ds_read_b128 v[204:207], v151 offset:4096
	ds_read_b128 v[208:211], v151 offset:5120
	ds_read_b128 v[212:215], v151 offset:6144
	ds_read_b128 v[216:219], v151 offset:7168
	global_load_lds_dwordx4 v140, s[72:73]
	s_add_i32 m0, s27, 0xe000
	s_nop 0
	global_load_lds_dwordx4 v138, s[72:73]
	s_waitcnt vmcnt(8)
	s_waitcnt lgkmcnt(0)
	s_setprio 1
	s_barrier
	v_mfma_f32_16x16x32_bf16 v[126:129], v[142:145], v[188:191], v[126:129]
	v_mfma_f32_16x16x32_bf16 v[122:125], v[158:161], v[188:191], v[122:125]
	v_mfma_f32_16x16x32_bf16 v[110:113], v[142:145], v[196:199], v[110:113]
	v_mfma_f32_16x16x32_bf16 v[106:109], v[158:161], v[196:199], v[106:109]
	v_mfma_f32_16x16x32_bf16 v[94:97], v[142:145], v[204:207], v[94:97]
	v_mfma_f32_16x16x32_bf16 v[90:93], v[158:161], v[204:207], v[90:93]
	v_mfma_f32_16x16x32_bf16 v[78:81], v[142:145], v[212:215], v[78:81]
	v_mfma_f32_16x16x32_bf16 v[74:77], v[158:161], v[212:215], v[74:77]
	v_mfma_f32_16x16x32_bf16 v[126:129], v[154:157], v[192:195], v[126:129]
	v_mfma_f32_16x16x32_bf16 v[122:125], v[166:169], v[192:195], v[122:125]
	v_mfma_f32_16x16x32_bf16 v[110:113], v[154:157], v[200:203], v[110:113]
	v_mfma_f32_16x16x32_bf16 v[106:109], v[166:169], v[200:203], v[106:109]
	v_mfma_f32_16x16x32_bf16 v[94:97], v[154:157], v[208:211], v[94:97]
	v_mfma_f32_16x16x32_bf16 v[90:93], v[166:169], v[208:211], v[90:93]
	v_mfma_f32_16x16x32_bf16 v[78:81], v[154:157], v[216:219], v[78:81]
	v_mfma_f32_16x16x32_bf16 v[74:77], v[166:169], v[216:219], v[74:77]
	v_mfma_f32_16x16x32_bf16 v[118:121], v[170:173], v[188:191], v[118:121]
	v_mfma_f32_16x16x32_bf16 v[114:117], v[178:181], v[188:191], v[114:117]
	v_mfma_f32_16x16x32_bf16 v[102:105], v[170:173], v[196:199], v[102:105]
	v_mfma_f32_16x16x32_bf16 v[98:101], v[178:181], v[196:199], v[98:101]
	v_mfma_f32_16x16x32_bf16 v[86:89], v[170:173], v[204:207], v[86:89]
	v_mfma_f32_16x16x32_bf16 v[82:85], v[178:181], v[204:207], v[82:85]
	v_mfma_f32_16x16x32_bf16 v[70:73], v[170:173], v[212:215], v[70:73]
	v_mfma_f32_16x16x32_bf16 v[66:69], v[178:181], v[212:215], v[66:69]
	v_mfma_f32_16x16x32_bf16 v[118:121], v[174:177], v[192:195], v[118:121]
	v_mfma_f32_16x16x32_bf16 v[114:117], v[182:185], v[192:195], v[114:117]
	v_mfma_f32_16x16x32_bf16 v[102:105], v[174:177], v[200:203], v[102:105]
	v_mfma_f32_16x16x32_bf16 v[98:101], v[182:185], v[200:203], v[98:101]
	v_mfma_f32_16x16x32_bf16 v[86:89], v[174:177], v[208:211], v[86:89]
	v_mfma_f32_16x16x32_bf16 v[82:85], v[182:185], v[208:211], v[82:85]
	v_mfma_f32_16x16x32_bf16 v[70:73], v[174:177], v[216:219], v[70:73]
	v_mfma_f32_16x16x32_bf16 v[66:69], v[182:185], v[216:219], v[66:69]
	s_barrier
	s_setprio 0
	s_add_i32 s6, s78, s26
	v_lshl_add_u64 v[162:163], s[74:75], 0, v[132:133]
	s_mov_b32 m0, s6
	ds_read_b128 v[188:191], v151 offset:16384
	ds_read_b128 v[192:195], v151 offset:17408
	ds_read_b128 v[196:199], v151 offset:18432
	ds_read_b128 v[200:203], v151 offset:19456
	ds_read_b128 v[204:207], v151 offset:20480
	ds_read_b128 v[208:211], v151 offset:21504
	ds_read_b128 v[212:215], v151 offset:22528
	ds_read_b128 v[216:219], v151 offset:23552
	global_load_lds_dwordx4 v[162:163], off
	s_add_i32 m0, s6, 0x2000
	s_add_u32 s6, s74, 0x100000
	v_lshl_add_u64 v[220:221], s[74:75], 0, v[136:137]
	s_addc_u32 s7, s75, 0
	s_add_i32 s16, s79, s26
	global_load_lds_dwordx4 v[220:221], off
	s_mov_b32 m0, s16
	v_lshl_add_u64 v[224:225], s[76:77], 0, v[134:135]
	global_load_lds_dwordx4 v132, s[6:7]
	s_add_i32 m0, s16, 0x2000
	s_nop 0
	global_load_lds_dwordx4 v136, s[6:7]
	v_lshl_add_u64 v[222:223], s[76:77], 0, v[130:131]
	s_mov_b32 m0, s27
	s_nop 0
	global_load_lds_dwordx4 v[222:223], off
	s_mov_b32 m0, s28
	s_nop 0
	global_load_lds_dwordx4 v[224:225], off
	s_waitcnt vmcnt(8)
	s_waitcnt lgkmcnt(0)
	s_setprio 1
	s_barrier
	v_mfma_f32_16x16x32_bf16 v[62:65], v[142:145], v[188:191], v[62:65]
	v_mfma_f32_16x16x32_bf16 v[58:61], v[158:161], v[188:191], v[58:61]
	v_mfma_f32_16x16x32_bf16 v[46:49], v[142:145], v[196:199], v[46:49]
	v_mfma_f32_16x16x32_bf16 v[42:45], v[158:161], v[196:199], v[42:45]
	v_mfma_f32_16x16x32_bf16 v[30:33], v[142:145], v[204:207], v[30:33]
	v_mfma_f32_16x16x32_bf16 v[26:29], v[158:161], v[204:207], v[26:29]
	v_mfma_f32_16x16x32_bf16 v[14:17], v[142:145], v[212:215], v[14:17]
	v_mfma_f32_16x16x32_bf16 v[10:13], v[158:161], v[212:215], v[10:13]
	v_mfma_f32_16x16x32_bf16 v[62:65], v[154:157], v[192:195], v[62:65]
	v_mfma_f32_16x16x32_bf16 v[58:61], v[166:169], v[192:195], v[58:61]
	v_mfma_f32_16x16x32_bf16 v[46:49], v[154:157], v[200:203], v[46:49]
	v_mfma_f32_16x16x32_bf16 v[42:45], v[166:169], v[200:203], v[42:45]
	v_mfma_f32_16x16x32_bf16 v[30:33], v[154:157], v[208:211], v[30:33]
	v_mfma_f32_16x16x32_bf16 v[26:29], v[166:169], v[208:211], v[26:29]
	v_mfma_f32_16x16x32_bf16 v[14:17], v[154:157], v[216:219], v[14:17]
	v_mfma_f32_16x16x32_bf16 v[10:13], v[166:169], v[216:219], v[10:13]
	v_mfma_f32_16x16x32_bf16 v[54:57], v[170:173], v[188:191], v[54:57]
	v_mfma_f32_16x16x32_bf16 v[50:53], v[178:181], v[188:191], v[50:53]
	v_mfma_f32_16x16x32_bf16 v[38:41], v[170:173], v[196:199], v[38:41]
	v_mfma_f32_16x16x32_bf16 v[34:37], v[178:181], v[196:199], v[34:37]
	v_mfma_f32_16x16x32_bf16 v[22:25], v[170:173], v[204:207], v[22:25]
	v_mfma_f32_16x16x32_bf16 v[18:21], v[178:181], v[204:207], v[18:21]
	v_mfma_f32_16x16x32_bf16 v[6:9], v[170:173], v[212:215], v[6:9]
	v_mfma_f32_16x16x32_bf16 v[2:5], v[178:181], v[212:215], v[2:5]
	v_mfma_f32_16x16x32_bf16 v[54:57], v[174:177], v[192:195], v[54:57]
	v_mfma_f32_16x16x32_bf16 v[50:53], v[182:185], v[192:195], v[50:53]
	v_mfma_f32_16x16x32_bf16 v[38:41], v[174:177], v[200:203], v[38:41]
	v_mfma_f32_16x16x32_bf16 v[34:37], v[182:185], v[200:203], v[34:37]
	v_mfma_f32_16x16x32_bf16 v[22:25], v[174:177], v[208:211], v[22:25]
	v_mfma_f32_16x16x32_bf16 v[18:21], v[182:185], v[208:211], v[18:21]
	v_mfma_f32_16x16x32_bf16 v[6:9], v[174:177], v[216:219], v[6:9]
	v_mfma_f32_16x16x32_bf16 v[2:5], v[182:185], v[216:219], v[2:5]
	s_barrier
	s_setprio 0
	s_add_i32 s16, 0, 0x18000
	v_add_u32_e32 v153, s16, v147
	s_add_i32 s17, 0, 0x1c000
	ds_read_b128 v[142:145], v153
	ds_read_b128 v[154:157], v153 offset:1024
	ds_read_b128 v[158:161], v153 offset:2048
	ds_read_b128 v[166:169], v153 offset:3072
	v_add_u32_e32 v153, s17, v147
	ds_read_b128 v[170:173], v153
	ds_read_b128 v[174:177], v153 offset:1024
	ds_read_b128 v[178:181], v153 offset:2048
	ds_read_b128 v[182:185], v153 offset:3072
	s_add_u32 s6, s76, 0x100000
	s_addc_u32 s7, s77, 0
	s_mov_b32 m0, s29
	ds_read_b128 v[188:191], v151 offset:32768
	ds_read_b128 v[192:195], v151 offset:33792
	ds_read_b128 v[196:199], v151 offset:34816
	ds_read_b128 v[200:203], v151 offset:35840
	ds_read_b128 v[204:207], v151 offset:36864
	ds_read_b128 v[208:211], v151 offset:37888
	ds_read_b128 v[212:215], v151 offset:38912
	ds_read_b128 v[216:219], v151 offset:39936
	global_load_lds_dwordx4 v130, s[6:7]
	s_mov_b32 m0, s40
	s_nop 0
	global_load_lds_dwordx4 v134, s[6:7]
	s_waitcnt vmcnt(8)
	s_waitcnt lgkmcnt(0)
	s_setprio 1
	s_barrier
	v_mfma_f32_16x16x32_bf16 v[126:129], v[142:145], v[188:191], v[126:129]
	v_mfma_f32_16x16x32_bf16 v[122:125], v[158:161], v[188:191], v[122:125]
	v_mfma_f32_16x16x32_bf16 v[110:113], v[142:145], v[196:199], v[110:113]
	v_mfma_f32_16x16x32_bf16 v[106:109], v[158:161], v[196:199], v[106:109]
	v_mfma_f32_16x16x32_bf16 v[94:97], v[142:145], v[204:207], v[94:97]
	v_mfma_f32_16x16x32_bf16 v[90:93], v[158:161], v[204:207], v[90:93]
	v_mfma_f32_16x16x32_bf16 v[78:81], v[142:145], v[212:215], v[78:81]
	v_mfma_f32_16x16x32_bf16 v[74:77], v[158:161], v[212:215], v[74:77]
	v_mfma_f32_16x16x32_bf16 v[126:129], v[154:157], v[192:195], v[126:129]
	v_mfma_f32_16x16x32_bf16 v[122:125], v[166:169], v[192:195], v[122:125]
	v_mfma_f32_16x16x32_bf16 v[110:113], v[154:157], v[200:203], v[110:113]
	v_mfma_f32_16x16x32_bf16 v[106:109], v[166:169], v[200:203], v[106:109]
	v_mfma_f32_16x16x32_bf16 v[94:97], v[154:157], v[208:211], v[94:97]
	v_mfma_f32_16x16x32_bf16 v[90:93], v[166:169], v[208:211], v[90:93]
	v_mfma_f32_16x16x32_bf16 v[78:81], v[154:157], v[216:219], v[78:81]
	v_mfma_f32_16x16x32_bf16 v[74:77], v[166:169], v[216:219], v[74:77]
	v_mfma_f32_16x16x32_bf16 v[118:121], v[170:173], v[188:191], v[118:121]
	v_mfma_f32_16x16x32_bf16 v[114:117], v[178:181], v[188:191], v[114:117]
	v_mfma_f32_16x16x32_bf16 v[102:105], v[170:173], v[196:199], v[102:105]
	v_mfma_f32_16x16x32_bf16 v[98:101], v[178:181], v[196:199], v[98:101]
	v_mfma_f32_16x16x32_bf16 v[86:89], v[170:173], v[204:207], v[86:89]
	v_mfma_f32_16x16x32_bf16 v[82:85], v[178:181], v[204:207], v[82:85]
	v_mfma_f32_16x16x32_bf16 v[70:73], v[170:173], v[212:215], v[70:73]
	v_mfma_f32_16x16x32_bf16 v[66:69], v[178:181], v[212:215], v[66:69]
	v_mfma_f32_16x16x32_bf16 v[118:121], v[174:177], v[192:195], v[118:121]
	v_mfma_f32_16x16x32_bf16 v[114:117], v[182:185], v[192:195], v[114:117]
	v_mfma_f32_16x16x32_bf16 v[102:105], v[174:177], v[200:203], v[102:105]
	v_mfma_f32_16x16x32_bf16 v[98:101], v[182:185], v[200:203], v[98:101]
	v_mfma_f32_16x16x32_bf16 v[86:89], v[174:177], v[208:211], v[86:89]
	v_mfma_f32_16x16x32_bf16 v[82:85], v[182:185], v[208:211], v[82:85]
	v_mfma_f32_16x16x32_bf16 v[70:73], v[174:177], v[216:219], v[70:73]
	v_mfma_f32_16x16x32_bf16 v[66:69], v[182:185], v[216:219], v[66:69]
	s_barrier
	s_setprio 0
	s_add_i32 s6, s16, s26
	v_lshl_add_u64 v[162:163], v[162:163], 0, s[12:13]
	s_mov_b32 m0, s6
	ds_read_b128 v[188:191], v151 offset:49152
	ds_read_b128 v[192:195], v151 offset:50176
	ds_read_b128 v[196:199], v151 offset:51200
	ds_read_b128 v[200:203], v151 offset:52224
	ds_read_b128 v[204:207], v151 offset:53248
	ds_read_b128 v[208:211], v151 offset:54272
	ds_read_b128 v[212:215], v151 offset:55296
	ds_read_b128 v[216:219], v151 offset:56320
	global_load_lds_dwordx4 v[162:163], off
	s_add_i32 m0, s6, 0x2000
	s_add_u32 s6, s74, 0x100080
	v_lshl_add_u64 v[162:163], v[220:221], 0, s[12:13]
	s_addc_u32 s7, s75, 0
	s_add_i32 s16, s17, s26
	global_load_lds_dwordx4 v[162:163], off
	s_mov_b32 m0, s16
	s_nop 0
	global_load_lds_dwordx4 v132, s[6:7]
	s_add_i32 m0, s16, 0x2000
	s_nop 0
	global_load_lds_dwordx4 v136, s[6:7]
	v_lshl_add_u64 v[162:163], v[222:223], 0, s[12:13]
	s_mov_b32 m0, s56
	s_nop 0
	global_load_lds_dwordx4 v[162:163], off
	v_lshl_add_u64 v[162:163], v[224:225], 0, s[12:13]
	s_mov_b32 m0, s57
	s_nop 0
	global_load_lds_dwordx4 v[162:163], off
	s_waitcnt vmcnt(8)
	s_waitcnt lgkmcnt(0)
	s_setprio 1
	s_barrier
	v_mfma_f32_16x16x32_bf16 v[62:65], v[142:145], v[188:191], v[62:65]
	v_mfma_f32_16x16x32_bf16 v[58:61], v[158:161], v[188:191], v[58:61]
	v_mfma_f32_16x16x32_bf16 v[46:49], v[142:145], v[196:199], v[46:49]
	v_mfma_f32_16x16x32_bf16 v[42:45], v[158:161], v[196:199], v[42:45]
	v_mfma_f32_16x16x32_bf16 v[30:33], v[142:145], v[204:207], v[30:33]
	v_mfma_f32_16x16x32_bf16 v[26:29], v[158:161], v[204:207], v[26:29]
	v_mfma_f32_16x16x32_bf16 v[14:17], v[142:145], v[212:215], v[14:17]
	v_mfma_f32_16x16x32_bf16 v[10:13], v[158:161], v[212:215], v[10:13]
	v_mfma_f32_16x16x32_bf16 v[62:65], v[154:157], v[192:195], v[62:65]
	v_mfma_f32_16x16x32_bf16 v[58:61], v[166:169], v[192:195], v[58:61]
	v_mfma_f32_16x16x32_bf16 v[46:49], v[154:157], v[200:203], v[46:49]
	v_mfma_f32_16x16x32_bf16 v[42:45], v[166:169], v[200:203], v[42:45]
	v_mfma_f32_16x16x32_bf16 v[30:33], v[154:157], v[208:211], v[30:33]
	v_mfma_f32_16x16x32_bf16 v[26:29], v[166:169], v[208:211], v[26:29]
	v_mfma_f32_16x16x32_bf16 v[14:17], v[154:157], v[216:219], v[14:17]
	v_mfma_f32_16x16x32_bf16 v[10:13], v[166:169], v[216:219], v[10:13]
	v_mfma_f32_16x16x32_bf16 v[54:57], v[170:173], v[188:191], v[54:57]
	v_mfma_f32_16x16x32_bf16 v[50:53], v[178:181], v[188:191], v[50:53]
	v_mfma_f32_16x16x32_bf16 v[38:41], v[170:173], v[196:199], v[38:41]
	v_mfma_f32_16x16x32_bf16 v[34:37], v[178:181], v[196:199], v[34:37]
	v_mfma_f32_16x16x32_bf16 v[22:25], v[170:173], v[204:207], v[22:25]
	v_mfma_f32_16x16x32_bf16 v[18:21], v[178:181], v[204:207], v[18:21]
	v_mfma_f32_16x16x32_bf16 v[6:9], v[170:173], v[212:215], v[6:9]
	v_mfma_f32_16x16x32_bf16 v[2:5], v[178:181], v[212:215], v[2:5]
	v_mfma_f32_16x16x32_bf16 v[54:57], v[174:177], v[192:195], v[54:57]
	v_mfma_f32_16x16x32_bf16 v[50:53], v[182:185], v[192:195], v[50:53]
	v_mfma_f32_16x16x32_bf16 v[38:41], v[174:177], v[200:203], v[38:41]
	v_mfma_f32_16x16x32_bf16 v[34:37], v[182:185], v[200:203], v[34:37]
	v_mfma_f32_16x16x32_bf16 v[22:25], v[174:177], v[208:211], v[22:25]
	v_mfma_f32_16x16x32_bf16 v[18:21], v[182:185], v[208:211], v[18:21]
	v_mfma_f32_16x16x32_bf16 v[6:9], v[174:177], v[216:219], v[6:9]
	v_mfma_f32_16x16x32_bf16 v[2:5], v[182:185], v[216:219], v[2:5]
	s_barrier
	s_setprio 0
	s_add_i32 s83, s83, 2
	s_add_u32 s81, s81, 0x100
	s_addc_u32 s82, s82, 0
	s_add_u32 s72, s72, 0x100
	s_addc_u32 s73, s73, 0
	s_cmp_gt_u32 s83, 61
	s_cbranch_scc0 .LBB0_1984
	v_lshl_add_u32 v245, s70, 8, v146
	v_lshl_or_b32 v246, s68, 8, v148
	v_lshlrev_b32_e32 v245, 13, v245
	v_lshl_add_u32 v245, v246, 1, v245
	global_load_dwordx4 v[142:145], v245, s[24:25]
	global_load_dwordx4 v[154:157], v245, s[24:25] offset:256
	s_add_u32 s68, s24, 0x20000
	s_addc_u32 s69, s25, 0
	global_load_dwordx4 v[158:161], v245, s[68:69]
	global_load_dwordx4 v[166:169], v245, s[68:69] offset:256
	s_add_u32 s68, s24, 0x40000
	s_addc_u32 s69, s25, 0
	global_load_dwordx4 v[170:173], v245, s[68:69]
	global_load_dwordx4 v[174:177], v245, s[68:69] offset:256
	s_add_u32 s68, s24, 0x60000
	s_addc_u32 s69, s25, 0
	global_load_dwordx4 v[178:181], v245, s[68:69]
	global_load_dwordx4 v[182:185], v245, s[68:69] offset:256
	s_add_u32 s68, s24, 0x100000
	s_addc_u32 s69, s25, 0
	global_load_dwordx4 v[188:191], v245, s[68:69]
	global_load_dwordx4 v[192:195], v245, s[68:69] offset:256
	s_add_u32 s68, s24, 0x120000
	s_addc_u32 s69, s25, 0
	global_load_dwordx4 v[196:199], v245, s[68:69]
	global_load_dwordx4 v[200:203], v245, s[68:69] offset:256
	s_add_u32 s68, s24, 0x140000
	s_addc_u32 s69, s25, 0
	global_load_dwordx4 v[204:207], v245, s[68:69]
	global_load_dwordx4 v[208:211], v245, s[68:69] offset:256
	s_add_u32 s68, s24, 0x160000
	s_addc_u32 s69, s25, 0
	global_load_dwordx4 v[212:215], v245, s[68:69]
	global_load_dwordx4 v[216:219], v245, s[68:69] offset:256
	s_and_b64 vcc, exec, s[44:45]
	s_cbranch_vccz .LBB0_1987
	s_barrier

.LBB0_2067:
	ds_read_b128 v[2:5], v185
	ds_read_b128 v[6:9], v185 offset:1024
	ds_read_b128 v[138:141], v185 offset:2048
	ds_read_b128 v[142:145], v185 offset:3072
	ds_read_b128 v[146:149], v186
	ds_read_b128 v[150:153], v186 offset:1024
	ds_read_b128 v[170:173], v186 offset:2048
	ds_read_b128 v[174:177], v186 offset:3072
	s_add_u32 s6, s10, 0xfff80080
	s_addc_u32 s7, s11, -1
	s_cmp_eq_u32 s85, 28
	s_cselect_b32 s15, s28, s7
	s_cselect_b32 s14, s29, s6
	s_cselect_b32 s13, s65, s84
	s_cselect_b32 s12, s67, s83
	s_add_i32 m0, s39, 0xc000
	ds_read_b128 v[178:181], v187
	ds_read_b128 v[190:193], v187 offset:1024
	ds_read_b128 v[194:197], v187 offset:2048
	ds_read_b128 v[198:201], v187 offset:3072
	ds_read_b128 v[202:205], v187 offset:4096
	ds_read_b128 v[206:209], v187 offset:5120
	ds_read_b128 v[210:213], v187 offset:6144
	ds_read_b128 v[214:217], v187 offset:7168
	global_load_lds_dwordx4 v164, s[10:11]
	s_add_i32 m0, s39, 0xe000
	s_nop 0
	global_load_lds_dwordx4 v162, s[10:11]
	s_waitcnt vmcnt(8)
	s_waitcnt lgkmcnt(0)
	s_setprio 1
	s_barrier
	v_mfma_i32_16x16x64_i8 v[134:137], v[2:5], v[178:181], v[134:137]
	v_mfma_i32_16x16x64_i8 v[126:129], v[138:141], v[178:181], v[126:129]
	v_mfma_i32_16x16x64_i8 v[118:121], v[2:5], v[194:197], v[118:121]
	v_mfma_i32_16x16x64_i8 v[110:113], v[138:141], v[194:197], v[110:113]
	v_mfma_i32_16x16x64_i8 v[102:105], v[2:5], v[202:205], v[102:105]
	v_mfma_i32_16x16x64_i8 v[94:97], v[138:141], v[202:205], v[94:97]
	v_mfma_i32_16x16x64_i8 v[86:89], v[2:5], v[210:213], v[86:89]
	v_mfma_i32_16x16x64_i8 v[78:81], v[138:141], v[210:213], v[78:81]
	v_mfma_i32_16x16x64_i8 v[134:137], v[6:9], v[190:193], v[134:137]
	v_mfma_i32_16x16x64_i8 v[126:129], v[142:145], v[190:193], v[126:129]
	v_mfma_i32_16x16x64_i8 v[118:121], v[6:9], v[198:201], v[118:121]
	v_mfma_i32_16x16x64_i8 v[110:113], v[142:145], v[198:201], v[110:113]
	v_mfma_i32_16x16x64_i8 v[102:105], v[6:9], v[206:209], v[102:105]
	v_mfma_i32_16x16x64_i8 v[94:97], v[142:145], v[206:209], v[94:97]
	v_mfma_i32_16x16x64_i8 v[86:89], v[6:9], v[214:217], v[86:89]
	v_mfma_i32_16x16x64_i8 v[78:81], v[142:145], v[214:217], v[78:81]
	v_mfma_i32_16x16x64_i8 v[130:133], v[146:149], v[178:181], v[130:133]
	v_mfma_i32_16x16x64_i8 v[122:125], v[170:173], v[178:181], v[122:125]
	v_mfma_i32_16x16x64_i8 v[114:117], v[146:149], v[194:197], v[114:117]
	v_mfma_i32_16x16x64_i8 v[106:109], v[170:173], v[194:197], v[106:109]
	v_mfma_i32_16x16x64_i8 v[98:101], v[146:149], v[202:205], v[98:101]
	v_mfma_i32_16x16x64_i8 v[90:93], v[170:173], v[202:205], v[90:93]
	v_mfma_i32_16x16x64_i8 v[82:85], v[146:149], v[210:213], v[82:85]
	v_mfma_i32_16x16x64_i8 v[74:77], v[170:173], v[210:213], v[74:77]
	v_mfma_i32_16x16x64_i8 v[130:133], v[150:153], v[190:193], v[130:133]
	v_mfma_i32_16x16x64_i8 v[122:125], v[174:177], v[190:193], v[122:125]
	v_mfma_i32_16x16x64_i8 v[114:117], v[150:153], v[198:201], v[114:117]
	v_mfma_i32_16x16x64_i8 v[106:109], v[174:177], v[198:201], v[106:109]
	v_mfma_i32_16x16x64_i8 v[98:101], v[150:153], v[206:209], v[98:101]
	v_mfma_i32_16x16x64_i8 v[90:93], v[174:177], v[206:209], v[90:93]
	v_mfma_i32_16x16x64_i8 v[82:85], v[150:153], v[214:217], v[82:85]
	v_mfma_i32_16x16x64_i8 v[74:77], v[174:177], v[214:217], v[74:77]
	s_barrier
	s_setprio 0
	s_add_i32 s6, s79, s63
	v_lshl_add_u64 v[218:219], s[12:13], 0, v[156:157]
	s_mov_b32 m0, s6
	ds_read_b128 v[178:181], v187 offset:16384
	ds_read_b128 v[190:193], v187 offset:17408
	ds_read_b128 v[194:197], v187 offset:18432
	ds_read_b128 v[198:201], v187 offset:19456
	ds_read_b128 v[202:205], v187 offset:20480
	ds_read_b128 v[206:209], v187 offset:21504
	ds_read_b128 v[210:213], v187 offset:22528
	ds_read_b128 v[214:217], v187 offset:23552
	global_load_lds_dwordx4 v[218:219], off
	s_add_i32 m0, s6, 0x2000
	s_add_u32 s6, s12, 0x80000
	v_lshl_add_u64 v[220:221], s[12:13], 0, v[160:161]
	s_addc_u32 s7, s13, 0
	s_add_i32 s16, s80, s63
	global_load_lds_dwordx4 v[220:221], off
	s_mov_b32 m0, s16
	v_lshl_add_u64 v[224:225], s[14:15], 0, v[158:159]
	global_load_lds_dwordx4 v156, s[6:7]
	s_add_i32 m0, s16, 0x2000
	s_nop 0
	global_load_lds_dwordx4 v160, s[6:7]
	v_lshl_add_u64 v[222:223], s[14:15], 0, v[154:155]
	s_mov_b32 m0, s39
	s_nop 0
	global_load_lds_dwordx4 v[222:223], off
	s_mov_b32 m0, s72
	s_nop 0
	global_load_lds_dwordx4 v[224:225], off
	s_waitcnt vmcnt(8)
	s_waitcnt lgkmcnt(0)
	s_setprio 1
	s_barrier
	v_mfma_i32_16x16x64_i8 v[70:73], v[2:5], v[178:181], v[70:73]
	v_mfma_i32_16x16x64_i8 v[62:65], v[138:141], v[178:181], v[62:65]
	v_mfma_i32_16x16x64_i8 v[54:57], v[2:5], v[194:197], v[54:57]
	v_mfma_i32_16x16x64_i8 v[46:49], v[138:141], v[194:197], v[46:49]
	v_mfma_i32_16x16x64_i8 v[38:41], v[2:5], v[202:205], v[38:41]
	v_mfma_i32_16x16x64_i8 v[30:33], v[138:141], v[202:205], v[30:33]
	v_mfma_i32_16x16x64_i8 v[2:5], v[2:5], v[210:213], v[22:25]
	v_mfma_i32_16x16x64_i8 v[70:73], v[6:9], v[190:193], v[70:73]
	v_mfma_i32_16x16x64_i8 v[62:65], v[142:145], v[190:193], v[62:65]
	v_mfma_i32_16x16x64_i8 v[54:57], v[6:9], v[198:201], v[54:57]
	v_mfma_i32_16x16x64_i8 v[46:49], v[142:145], v[198:201], v[46:49]
	v_mfma_i32_16x16x64_i8 v[38:41], v[6:9], v[206:209], v[38:41]
	v_mfma_i32_16x16x64_i8 v[30:33], v[142:145], v[206:209], v[30:33]
	v_mfma_i32_16x16x64_i8 v[2:5], v[6:9], v[214:217], v[2:5]
	v_mfma_i32_16x16x64_i8 v[6:9], v[138:141], v[210:213], v[14:17]
	v_mfma_i32_16x16x64_i8 v[6:9], v[142:145], v[214:217], v[6:9]
	v_mfma_i32_16x16x64_i8 v[14:17], v[146:149], v[178:181], v[66:69]
	v_mfma_i32_16x16x64_i8 v[66:69], v[150:153], v[190:193], v[14:17]
	v_mfma_i32_16x16x64_i8 v[14:17], v[170:173], v[178:181], v[58:61]
	v_mfma_i32_16x16x64_i8 v[58:61], v[174:177], v[190:193], v[14:17]
	v_mfma_i32_16x16x64_i8 v[14:17], v[146:149], v[194:197], v[50:53]
	v_mfma_i32_16x16x64_i8 v[50:53], v[150:153], v[198:201], v[14:17]
	v_mfma_i32_16x16x64_i8 v[14:17], v[170:173], v[194:197], v[42:45]
	v_mfma_i32_16x16x64_i8 v[42:45], v[174:177], v[198:201], v[14:17]
	v_mfma_i32_16x16x64_i8 v[14:17], v[146:149], v[202:205], v[34:37]
	v_mfma_i32_16x16x64_i8 v[34:37], v[150:153], v[206:209], v[14:17]
	v_mfma_i32_16x16x64_i8 v[14:17], v[170:173], v[202:205], v[26:29]
	v_mfma_i32_16x16x64_i8 v[26:29], v[174:177], v[206:209], v[14:17]
	v_mfma_i32_16x16x64_i8 v[14:17], v[146:149], v[210:213], v[18:21]
	v_mfma_i32_16x16x64_i8 v[10:13], v[170:173], v[210:213], v[10:13]
	v_mfma_i32_16x16x64_i8 v[18:21], v[150:153], v[214:217], v[14:17]
	v_mfma_i32_16x16x64_i8 v[10:13], v[174:177], v[214:217], v[10:13]
	s_barrier
	s_setprio 0
	s_add_i32 s16, 0, 0x18000
	s_add_i32 s17, 0, 0x1c000
	v_add_u32_e32 v142, s16, v183
	v_add_u32_e32 v174, s17, v183
	ds_read_b128 v[14:17], v142
	ds_read_b128 v[22:25], v142 offset:1024
	ds_read_b128 v[138:141], v142 offset:2048
	ds_read_b128 v[142:145], v142 offset:3072
	ds_read_b128 v[146:149], v174
	ds_read_b128 v[150:153], v174 offset:1024
	ds_read_b128 v[170:173], v174 offset:2048
	ds_read_b128 v[174:177], v174 offset:3072
	s_add_u32 s6, s14, 0x80000
	s_addc_u32 s7, s15, 0
	s_mov_b32 m0, s73
	ds_read_b128 v[178:181], v187 offset:32768
	ds_read_b128 v[190:193], v187 offset:33792
	ds_read_b128 v[194:197], v187 offset:34816
	ds_read_b128 v[198:201], v187 offset:35840
	ds_read_b128 v[202:205], v187 offset:36864
	ds_read_b128 v[206:209], v187 offset:37888
	ds_read_b128 v[210:213], v187 offset:38912
	ds_read_b128 v[214:217], v187 offset:39936
	global_load_lds_dwordx4 v154, s[6:7]
	s_mov_b32 m0, s74
	s_nop 0
	global_load_lds_dwordx4 v158, s[6:7]
	s_waitcnt vmcnt(8)
	s_waitcnt lgkmcnt(0)
	s_setprio 1
	s_barrier
	v_mfma_i32_16x16x64_i8 v[134:137], v[14:17], v[178:181], v[134:137]
	v_mfma_i32_16x16x64_i8 v[126:129], v[138:141], v[178:181], v[126:129]
	v_mfma_i32_16x16x64_i8 v[118:121], v[14:17], v[194:197], v[118:121]
	v_mfma_i32_16x16x64_i8 v[110:113], v[138:141], v[194:197], v[110:113]
	v_mfma_i32_16x16x64_i8 v[102:105], v[14:17], v[202:205], v[102:105]
	v_mfma_i32_16x16x64_i8 v[94:97], v[138:141], v[202:205], v[94:97]
	v_mfma_i32_16x16x64_i8 v[86:89], v[14:17], v[210:213], v[86:89]
	v_mfma_i32_16x16x64_i8 v[78:81], v[138:141], v[210:213], v[78:81]
	v_mfma_i32_16x16x64_i8 v[134:137], v[22:25], v[190:193], v[134:137]
	v_mfma_i32_16x16x64_i8 v[126:129], v[142:145], v[190:193], v[126:129]
	v_mfma_i32_16x16x64_i8 v[118:121], v[22:25], v[198:201], v[118:121]
	v_mfma_i32_16x16x64_i8 v[110:113], v[142:145], v[198:201], v[110:113]
	v_mfma_i32_16x16x64_i8 v[102:105], v[22:25], v[206:209], v[102:105]
	v_mfma_i32_16x16x64_i8 v[94:97], v[142:145], v[206:209], v[94:97]
	v_mfma_i32_16x16x64_i8 v[86:89], v[22:25], v[214:217], v[86:89]
	v_mfma_i32_16x16x64_i8 v[78:81], v[142:145], v[214:217], v[78:81]
	v_mfma_i32_16x16x64_i8 v[130:133], v[146:149], v[178:181], v[130:133]
	v_mfma_i32_16x16x64_i8 v[122:125], v[170:173], v[178:181], v[122:125]
	v_mfma_i32_16x16x64_i8 v[114:117], v[146:149], v[194:197], v[114:117]
	v_mfma_i32_16x16x64_i8 v[106:109], v[170:173], v[194:197], v[106:109]
	v_mfma_i32_16x16x64_i8 v[98:101], v[146:149], v[202:205], v[98:101]
	v_mfma_i32_16x16x64_i8 v[90:93], v[170:173], v[202:205], v[90:93]
	v_mfma_i32_16x16x64_i8 v[82:85], v[146:149], v[210:213], v[82:85]
	v_mfma_i32_16x16x64_i8 v[74:77], v[170:173], v[210:213], v[74:77]
	v_mfma_i32_16x16x64_i8 v[130:133], v[150:153], v[190:193], v[130:133]
	v_mfma_i32_16x16x64_i8 v[122:125], v[174:177], v[190:193], v[122:125]
	v_mfma_i32_16x16x64_i8 v[114:117], v[150:153], v[198:201], v[114:117]
	v_mfma_i32_16x16x64_i8 v[106:109], v[174:177], v[198:201], v[106:109]
	v_mfma_i32_16x16x64_i8 v[98:101], v[150:153], v[206:209], v[98:101]
	v_mfma_i32_16x16x64_i8 v[90:93], v[174:177], v[206:209], v[90:93]
	v_mfma_i32_16x16x64_i8 v[82:85], v[150:153], v[214:217], v[82:85]
	v_mfma_i32_16x16x64_i8 v[74:77], v[174:177], v[214:217], v[74:77]
	s_barrier
	s_setprio 0
	s_add_i32 s6, s16, s63
	v_lshl_add_u64 v[218:219], v[218:219], 0, s[46:47]
	s_mov_b32 m0, s6
	ds_read_b128 v[178:181], v187 offset:49152
	ds_read_b128 v[190:193], v187 offset:50176
	ds_read_b128 v[194:197], v187 offset:51200
	ds_read_b128 v[198:201], v187 offset:52224
	ds_read_b128 v[202:205], v187 offset:53248
	ds_read_b128 v[206:209], v187 offset:54272
	ds_read_b128 v[210:213], v187 offset:55296
	ds_read_b128 v[214:217], v187 offset:56320
	global_load_lds_dwordx4 v[218:219], off
	s_add_i32 m0, s6, 0x2000
	s_add_u32 s6, s12, 0x80080
	v_lshl_add_u64 v[218:219], v[220:221], 0, s[46:47]
	s_addc_u32 s7, s13, 0
	s_add_i32 s12, s17, s63
	global_load_lds_dwordx4 v[218:219], off
	s_mov_b32 m0, s12
	s_nop 0
	global_load_lds_dwordx4 v156, s[6:7]
	s_add_i32 m0, s12, 0x2000
	s_nop 0
	global_load_lds_dwordx4 v160, s[6:7]
	v_lshl_add_u64 v[218:219], v[222:223], 0, s[46:47]
	s_mov_b32 m0, s76
	s_nop 0
	global_load_lds_dwordx4 v[218:219], off
	v_lshl_add_u64 v[218:219], v[224:225], 0, s[46:47]
	s_mov_b32 m0, s77
	s_nop 0
	global_load_lds_dwordx4 v[218:219], off
	s_waitcnt vmcnt(8)
	s_waitcnt lgkmcnt(0)
	s_setprio 1
	s_barrier
	v_mfma_i32_16x16x64_i8 v[70:73], v[14:17], v[178:181], v[70:73]
	v_mfma_i32_16x16x64_i8 v[54:57], v[14:17], v[194:197], v[54:57]
	v_mfma_i32_16x16x64_i8 v[38:41], v[14:17], v[202:205], v[38:41]
	v_mfma_i32_16x16x64_i8 v[2:5], v[14:17], v[210:213], v[2:5]
	v_mfma_i32_16x16x64_i8 v[70:73], v[22:25], v[190:193], v[70:73]
	v_mfma_i32_16x16x64_i8 v[62:65], v[138:141], v[178:181], v[62:65]
	v_mfma_i32_16x16x64_i8 v[54:57], v[22:25], v[198:201], v[54:57]
	v_mfma_i32_16x16x64_i8 v[46:49], v[138:141], v[194:197], v[46:49]
	v_mfma_i32_16x16x64_i8 v[38:41], v[22:25], v[206:209], v[38:41]
	v_mfma_i32_16x16x64_i8 v[30:33], v[138:141], v[202:205], v[30:33]
	v_mfma_i32_16x16x64_i8 v[22:25], v[22:25], v[214:217], v[2:5]
	v_mfma_i32_16x16x64_i8 v[2:5], v[138:141], v[210:213], v[6:9]
	v_mfma_i32_16x16x64_i8 v[62:65], v[142:145], v[190:193], v[62:65]
	v_mfma_i32_16x16x64_i8 v[46:49], v[142:145], v[198:201], v[46:49]
	v_mfma_i32_16x16x64_i8 v[30:33], v[142:145], v[206:209], v[30:33]
	v_mfma_i32_16x16x64_i8 v[14:17], v[142:145], v[214:217], v[2:5]
	v_mfma_i32_16x16x64_i8 v[2:5], v[146:149], v[178:181], v[66:69]
	v_mfma_i32_16x16x64_i8 v[66:69], v[150:153], v[190:193], v[2:5]
	v_mfma_i32_16x16x64_i8 v[2:5], v[170:173], v[178:181], v[58:61]
	v_mfma_i32_16x16x64_i8 v[58:61], v[174:177], v[190:193], v[2:5]
	v_mfma_i32_16x16x64_i8 v[2:5], v[146:149], v[194:197], v[50:53]
	v_mfma_i32_16x16x64_i8 v[50:53], v[150:153], v[198:201], v[2:5]
	v_mfma_i32_16x16x64_i8 v[2:5], v[170:173], v[194:197], v[42:45]
	v_mfma_i32_16x16x64_i8 v[42:45], v[174:177], v[198:201], v[2:5]
	v_mfma_i32_16x16x64_i8 v[2:5], v[146:149], v[202:205], v[34:37]
	v_mfma_i32_16x16x64_i8 v[34:37], v[150:153], v[206:209], v[2:5]
	v_mfma_i32_16x16x64_i8 v[2:5], v[170:173], v[202:205], v[26:29]
	v_mfma_i32_16x16x64_i8 v[26:29], v[174:177], v[206:209], v[2:5]
	v_mfma_i32_16x16x64_i8 v[2:5], v[146:149], v[210:213], v[18:21]
	v_mfma_i32_16x16x64_i8 v[18:21], v[150:153], v[214:217], v[2:5]
	v_mfma_i32_16x16x64_i8 v[2:5], v[170:173], v[210:213], v[10:13]
	v_mfma_i32_16x16x64_i8 v[10:13], v[174:177], v[214:217], v[2:5]
	s_barrier
	s_setprio 0
	s_add_i32 s85, s85, 2
	s_add_u32 s83, s83, 0x100
	s_addc_u32 s84, s84, 0
	s_add_u32 s10, s10, 0x100
	s_addc_u32 s11, s11, 0
	s_cmp_gt_u32 s85, 29
	s_cbranch_scc0 .LBB0_2067
	s_and_b64 vcc, exec, s[60:61]
	s_cbranch_vccz .LBB0_2070
	s_barrier

.LBB0_2118:
	ds_read_b128 v[142:145], v149
	ds_read_b128 v[154:157], v149 offset:1024
	ds_read_b128 v[158:161], v149 offset:2048
	ds_read_b128 v[162:165], v149 offset:3072
	ds_read_b128 v[166:169], v150
	ds_read_b128 v[170:173], v150 offset:1024
	ds_read_b128 v[174:177], v150 offset:2048
	ds_read_b128 v[178:181], v150 offset:3072
	s_add_u32 s16, s40, 0xffd50080
	s_addc_u32 s17, s41, -1
	s_cmpk_eq_i32 s71, 0xa8
	s_cselect_b32 s45, s37, s17
	s_cselect_b32 s44, s36, s16
	s_cselect_b32 s43, s39, s70
	s_cselect_b32 s42, s38, s69
	s_add_i32 m0, s27, 0xc000
	ds_read_b128 v[182:185], v151
	ds_read_b128 v[186:189], v151 offset:1024
	ds_read_b128 v[190:193], v151 offset:2048
	ds_read_b128 v[194:197], v151 offset:3072
	ds_read_b128 v[198:201], v151 offset:4096
	ds_read_b128 v[202:205], v151 offset:5120
	ds_read_b128 v[206:209], v151 offset:6144
	ds_read_b128 v[210:213], v151 offset:7168
	global_load_lds_dwordx4 v140, s[40:41]
	s_add_i32 m0, s27, 0xe000
	s_nop 0
	global_load_lds_dwordx4 v138, s[40:41]
	s_waitcnt vmcnt(8)
	s_waitcnt lgkmcnt(0)
	s_setprio 1
	s_barrier
	v_mfma_f32_16x16x32_bf16 v[126:129], v[142:145], v[182:185], v[126:129]
	v_mfma_f32_16x16x32_bf16 v[122:125], v[158:161], v[182:185], v[122:125]
	v_mfma_f32_16x16x32_bf16 v[110:113], v[142:145], v[190:193], v[110:113]
	v_mfma_f32_16x16x32_bf16 v[106:109], v[158:161], v[190:193], v[106:109]
	v_mfma_f32_16x16x32_bf16 v[94:97], v[142:145], v[198:201], v[94:97]
	v_mfma_f32_16x16x32_bf16 v[90:93], v[158:161], v[198:201], v[90:93]
	v_mfma_f32_16x16x32_bf16 v[78:81], v[142:145], v[206:209], v[78:81]
	v_mfma_f32_16x16x32_bf16 v[74:77], v[158:161], v[206:209], v[74:77]
	v_mfma_f32_16x16x32_bf16 v[126:129], v[154:157], v[186:189], v[126:129]
	v_mfma_f32_16x16x32_bf16 v[122:125], v[162:165], v[186:189], v[122:125]
	v_mfma_f32_16x16x32_bf16 v[110:113], v[154:157], v[194:197], v[110:113]
	v_mfma_f32_16x16x32_bf16 v[106:109], v[162:165], v[194:197], v[106:109]
	v_mfma_f32_16x16x32_bf16 v[94:97], v[154:157], v[202:205], v[94:97]
	v_mfma_f32_16x16x32_bf16 v[90:93], v[162:165], v[202:205], v[90:93]
	v_mfma_f32_16x16x32_bf16 v[78:81], v[154:157], v[210:213], v[78:81]
	v_mfma_f32_16x16x32_bf16 v[74:77], v[162:165], v[210:213], v[74:77]
	v_mfma_f32_16x16x32_bf16 v[118:121], v[166:169], v[182:185], v[118:121]
	v_mfma_f32_16x16x32_bf16 v[114:117], v[174:177], v[182:185], v[114:117]
	v_mfma_f32_16x16x32_bf16 v[102:105], v[166:169], v[190:193], v[102:105]
	v_mfma_f32_16x16x32_bf16 v[98:101], v[174:177], v[190:193], v[98:101]
	v_mfma_f32_16x16x32_bf16 v[86:89], v[166:169], v[198:201], v[86:89]
	v_mfma_f32_16x16x32_bf16 v[82:85], v[174:177], v[198:201], v[82:85]
	v_mfma_f32_16x16x32_bf16 v[70:73], v[166:169], v[206:209], v[70:73]
	v_mfma_f32_16x16x32_bf16 v[66:69], v[174:177], v[206:209], v[66:69]
	v_mfma_f32_16x16x32_bf16 v[118:121], v[170:173], v[186:189], v[118:121]
	v_mfma_f32_16x16x32_bf16 v[114:117], v[178:181], v[186:189], v[114:117]
	v_mfma_f32_16x16x32_bf16 v[102:105], v[170:173], v[194:197], v[102:105]
	v_mfma_f32_16x16x32_bf16 v[98:101], v[178:181], v[194:197], v[98:101]
	v_mfma_f32_16x16x32_bf16 v[86:89], v[170:173], v[202:205], v[86:89]
	v_mfma_f32_16x16x32_bf16 v[82:85], v[178:181], v[202:205], v[82:85]
	v_mfma_f32_16x16x32_bf16 v[70:73], v[170:173], v[210:213], v[70:73]
	v_mfma_f32_16x16x32_bf16 v[66:69], v[178:181], v[210:213], v[66:69]
	s_barrier
	s_setprio 0
	s_add_i32 s16, s63, s26
	v_lshl_add_u64 v[214:215], s[42:43], 0, v[132:133]
	s_mov_b32 m0, s16
	ds_read_b128 v[182:185], v151 offset:16384
	ds_read_b128 v[186:189], v151 offset:17408
	ds_read_b128 v[190:193], v151 offset:18432
	ds_read_b128 v[194:197], v151 offset:19456
	ds_read_b128 v[198:201], v151 offset:20480
	ds_read_b128 v[202:205], v151 offset:21504
	ds_read_b128 v[206:209], v151 offset:22528
	ds_read_b128 v[210:213], v151 offset:23552
	global_load_lds_dwordx4 v[214:215], off
	s_add_i32 m0, s16, 0x2000
	s_add_u32 s16, s42, 0x2b0000
	v_lshl_add_u64 v[216:217], s[42:43], 0, v[136:137]
	s_addc_u32 s17, s43, 0
	s_add_i32 s72, s64, s26
	global_load_lds_dwordx4 v[216:217], off
	s_mov_b32 m0, s72
	v_lshl_add_u64 v[220:221], s[44:45], 0, v[134:135]
	global_load_lds_dwordx4 v132, s[16:17]
	s_add_i32 m0, s72, 0x2000
	s_nop 0
	global_load_lds_dwordx4 v136, s[16:17]
	v_lshl_add_u64 v[218:219], s[44:45], 0, v[130:131]
	s_mov_b32 m0, s27
	s_nop 0
	global_load_lds_dwordx4 v[218:219], off
	s_mov_b32 m0, s28
	s_nop 0
	global_load_lds_dwordx4 v[220:221], off
	s_waitcnt vmcnt(8)
	s_waitcnt lgkmcnt(0)
	s_setprio 1
	s_barrier
	v_mfma_f32_16x16x32_bf16 v[62:65], v[142:145], v[182:185], v[62:65]
	v_mfma_f32_16x16x32_bf16 v[58:61], v[158:161], v[182:185], v[58:61]
	v_mfma_f32_16x16x32_bf16 v[46:49], v[142:145], v[190:193], v[46:49]
	v_mfma_f32_16x16x32_bf16 v[42:45], v[158:161], v[190:193], v[42:45]
	v_mfma_f32_16x16x32_bf16 v[30:33], v[142:145], v[198:201], v[30:33]
	v_mfma_f32_16x16x32_bf16 v[26:29], v[158:161], v[198:201], v[26:29]
	v_mfma_f32_16x16x32_bf16 v[14:17], v[142:145], v[206:209], v[14:17]
	v_mfma_f32_16x16x32_bf16 v[10:13], v[158:161], v[206:209], v[10:13]
	v_mfma_f32_16x16x32_bf16 v[62:65], v[154:157], v[186:189], v[62:65]
	v_mfma_f32_16x16x32_bf16 v[58:61], v[162:165], v[186:189], v[58:61]
	v_mfma_f32_16x16x32_bf16 v[46:49], v[154:157], v[194:197], v[46:49]
	v_mfma_f32_16x16x32_bf16 v[42:45], v[162:165], v[194:197], v[42:45]
	v_mfma_f32_16x16x32_bf16 v[30:33], v[154:157], v[202:205], v[30:33]
	v_mfma_f32_16x16x32_bf16 v[26:29], v[162:165], v[202:205], v[26:29]
	v_mfma_f32_16x16x32_bf16 v[14:17], v[154:157], v[210:213], v[14:17]
	v_mfma_f32_16x16x32_bf16 v[10:13], v[162:165], v[210:213], v[10:13]
	v_mfma_f32_16x16x32_bf16 v[54:57], v[166:169], v[182:185], v[54:57]
	v_mfma_f32_16x16x32_bf16 v[50:53], v[174:177], v[182:185], v[50:53]
	v_mfma_f32_16x16x32_bf16 v[38:41], v[166:169], v[190:193], v[38:41]
	v_mfma_f32_16x16x32_bf16 v[34:37], v[174:177], v[190:193], v[34:37]
	v_mfma_f32_16x16x32_bf16 v[22:25], v[166:169], v[198:201], v[22:25]
	v_mfma_f32_16x16x32_bf16 v[18:21], v[174:177], v[198:201], v[18:21]
	v_mfma_f32_16x16x32_bf16 v[6:9], v[166:169], v[206:209], v[6:9]
	v_mfma_f32_16x16x32_bf16 v[2:5], v[174:177], v[206:209], v[2:5]
	v_mfma_f32_16x16x32_bf16 v[54:57], v[170:173], v[186:189], v[54:57]
	v_mfma_f32_16x16x32_bf16 v[50:53], v[178:181], v[186:189], v[50:53]
	v_mfma_f32_16x16x32_bf16 v[38:41], v[170:173], v[194:197], v[38:41]
	v_mfma_f32_16x16x32_bf16 v[34:37], v[178:181], v[194:197], v[34:37]
	v_mfma_f32_16x16x32_bf16 v[22:25], v[170:173], v[202:205], v[22:25]
	v_mfma_f32_16x16x32_bf16 v[18:21], v[178:181], v[202:205], v[18:21]
	v_mfma_f32_16x16x32_bf16 v[6:9], v[170:173], v[210:213], v[6:9]
	v_mfma_f32_16x16x32_bf16 v[2:5], v[178:181], v[210:213], v[2:5]
	s_barrier
	s_setprio 0
	s_add_i32 s72, 0, 0x18000
	v_add_u32_e32 v153, s72, v147
	s_add_i32 s73, 0, 0x1c000
	ds_read_b128 v[142:145], v153
	ds_read_b128 v[154:157], v153 offset:1024
	ds_read_b128 v[158:161], v153 offset:2048
	ds_read_b128 v[162:165], v153 offset:3072
	v_add_u32_e32 v153, s73, v147
	ds_read_b128 v[166:169], v153
	ds_read_b128 v[170:173], v153 offset:1024
	ds_read_b128 v[174:177], v153 offset:2048
	ds_read_b128 v[178:181], v153 offset:3072
	s_add_u32 s16, s44, 0x2b0000
	s_addc_u32 s17, s45, 0
	s_mov_b32 m0, s29
	ds_read_b128 v[182:185], v151 offset:32768
	ds_read_b128 v[186:189], v151 offset:33792
	ds_read_b128 v[190:193], v151 offset:34816
	ds_read_b128 v[194:197], v151 offset:35840
	ds_read_b128 v[198:201], v151 offset:36864
	ds_read_b128 v[202:205], v151 offset:37888
	ds_read_b128 v[206:209], v151 offset:38912
	ds_read_b128 v[210:213], v151 offset:39936
	global_load_lds_dwordx4 v130, s[16:17]
	s_mov_b32 m0, s56
	s_nop 0
	global_load_lds_dwordx4 v134, s[16:17]
	s_waitcnt vmcnt(8)
	s_waitcnt lgkmcnt(0)
	s_setprio 1
	s_barrier
	v_mfma_f32_16x16x32_bf16 v[126:129], v[142:145], v[182:185], v[126:129]
	v_mfma_f32_16x16x32_bf16 v[122:125], v[158:161], v[182:185], v[122:125]
	v_mfma_f32_16x16x32_bf16 v[110:113], v[142:145], v[190:193], v[110:113]
	v_mfma_f32_16x16x32_bf16 v[106:109], v[158:161], v[190:193], v[106:109]
	v_mfma_f32_16x16x32_bf16 v[94:97], v[142:145], v[198:201], v[94:97]
	v_mfma_f32_16x16x32_bf16 v[90:93], v[158:161], v[198:201], v[90:93]
	v_mfma_f32_16x16x32_bf16 v[78:81], v[142:145], v[206:209], v[78:81]
	v_mfma_f32_16x16x32_bf16 v[74:77], v[158:161], v[206:209], v[74:77]
	v_mfma_f32_16x16x32_bf16 v[126:129], v[154:157], v[186:189], v[126:129]
	v_mfma_f32_16x16x32_bf16 v[122:125], v[162:165], v[186:189], v[122:125]
	v_mfma_f32_16x16x32_bf16 v[110:113], v[154:157], v[194:197], v[110:113]
	v_mfma_f32_16x16x32_bf16 v[106:109], v[162:165], v[194:197], v[106:109]
	v_mfma_f32_16x16x32_bf16 v[94:97], v[154:157], v[202:205], v[94:97]
	v_mfma_f32_16x16x32_bf16 v[90:93], v[162:165], v[202:205], v[90:93]
	v_mfma_f32_16x16x32_bf16 v[78:81], v[154:157], v[210:213], v[78:81]
	v_mfma_f32_16x16x32_bf16 v[74:77], v[162:165], v[210:213], v[74:77]
	v_mfma_f32_16x16x32_bf16 v[118:121], v[166:169], v[182:185], v[118:121]
	v_mfma_f32_16x16x32_bf16 v[114:117], v[174:177], v[182:185], v[114:117]
	v_mfma_f32_16x16x32_bf16 v[102:105], v[166:169], v[190:193], v[102:105]
	v_mfma_f32_16x16x32_bf16 v[98:101], v[174:177], v[190:193], v[98:101]
	v_mfma_f32_16x16x32_bf16 v[86:89], v[166:169], v[198:201], v[86:89]
	v_mfma_f32_16x16x32_bf16 v[82:85], v[174:177], v[198:201], v[82:85]
	v_mfma_f32_16x16x32_bf16 v[70:73], v[166:169], v[206:209], v[70:73]
	v_mfma_f32_16x16x32_bf16 v[66:69], v[174:177], v[206:209], v[66:69]
	v_mfma_f32_16x16x32_bf16 v[118:121], v[170:173], v[186:189], v[118:121]
	v_mfma_f32_16x16x32_bf16 v[114:117], v[178:181], v[186:189], v[114:117]
	v_mfma_f32_16x16x32_bf16 v[102:105], v[170:173], v[194:197], v[102:105]
	v_mfma_f32_16x16x32_bf16 v[98:101], v[178:181], v[194:197], v[98:101]
	v_mfma_f32_16x16x32_bf16 v[86:89], v[170:173], v[202:205], v[86:89]
	v_mfma_f32_16x16x32_bf16 v[82:85], v[178:181], v[202:205], v[82:85]
	v_mfma_f32_16x16x32_bf16 v[70:73], v[170:173], v[210:213], v[70:73]
	v_mfma_f32_16x16x32_bf16 v[66:69], v[178:181], v[210:213], v[66:69]
	s_barrier
	s_setprio 0
	s_add_i32 s16, s72, s26
	v_lshl_add_u64 v[214:215], v[214:215], 0, s[14:15]
	s_mov_b32 m0, s16
	ds_read_b128 v[182:185], v151 offset:49152
	ds_read_b128 v[186:189], v151 offset:50176
	ds_read_b128 v[190:193], v151 offset:51200
	ds_read_b128 v[194:197], v151 offset:52224
	ds_read_b128 v[198:201], v151 offset:53248
	ds_read_b128 v[202:205], v151 offset:54272
	ds_read_b128 v[206:209], v151 offset:55296
	ds_read_b128 v[210:213], v151 offset:56320
	global_load_lds_dwordx4 v[214:215], off
	s_add_i32 m0, s16, 0x2000
	s_add_u32 s16, s42, 0x2b0080
	v_lshl_add_u64 v[214:215], v[216:217], 0, s[14:15]
	s_addc_u32 s17, s43, 0
	s_add_i32 s42, s73, s26
	global_load_lds_dwordx4 v[214:215], off
	s_mov_b32 m0, s42
	s_nop 0
	global_load_lds_dwordx4 v132, s[16:17]
	s_add_i32 m0, s42, 0x2000
	s_nop 0
	global_load_lds_dwordx4 v136, s[16:17]
	v_lshl_add_u64 v[214:215], v[218:219], 0, s[14:15]
	s_mov_b32 m0, s60
	s_nop 0
	global_load_lds_dwordx4 v[214:215], off
	v_lshl_add_u64 v[214:215], v[220:221], 0, s[14:15]
	s_mov_b32 m0, s61
	s_nop 0
	global_load_lds_dwordx4 v[214:215], off
	s_waitcnt vmcnt(8)
	s_waitcnt lgkmcnt(0)
	s_setprio 1
	s_barrier
	v_mfma_f32_16x16x32_bf16 v[62:65], v[142:145], v[182:185], v[62:65]
	v_mfma_f32_16x16x32_bf16 v[58:61], v[158:161], v[182:185], v[58:61]
	v_mfma_f32_16x16x32_bf16 v[46:49], v[142:145], v[190:193], v[46:49]
	v_mfma_f32_16x16x32_bf16 v[42:45], v[158:161], v[190:193], v[42:45]
	v_mfma_f32_16x16x32_bf16 v[30:33], v[142:145], v[198:201], v[30:33]
	v_mfma_f32_16x16x32_bf16 v[26:29], v[158:161], v[198:201], v[26:29]
	v_mfma_f32_16x16x32_bf16 v[14:17], v[142:145], v[206:209], v[14:17]
	v_mfma_f32_16x16x32_bf16 v[10:13], v[158:161], v[206:209], v[10:13]
	v_mfma_f32_16x16x32_bf16 v[62:65], v[154:157], v[186:189], v[62:65]
	v_mfma_f32_16x16x32_bf16 v[58:61], v[162:165], v[186:189], v[58:61]
	v_mfma_f32_16x16x32_bf16 v[46:49], v[154:157], v[194:197], v[46:49]
	v_mfma_f32_16x16x32_bf16 v[42:45], v[162:165], v[194:197], v[42:45]
	v_mfma_f32_16x16x32_bf16 v[30:33], v[154:157], v[202:205], v[30:33]
	v_mfma_f32_16x16x32_bf16 v[26:29], v[162:165], v[202:205], v[26:29]
	v_mfma_f32_16x16x32_bf16 v[14:17], v[154:157], v[210:213], v[14:17]
	v_mfma_f32_16x16x32_bf16 v[10:13], v[162:165], v[210:213], v[10:13]
	v_mfma_f32_16x16x32_bf16 v[54:57], v[166:169], v[182:185], v[54:57]
	v_mfma_f32_16x16x32_bf16 v[50:53], v[174:177], v[182:185], v[50:53]
	v_mfma_f32_16x16x32_bf16 v[38:41], v[166:169], v[190:193], v[38:41]
	v_mfma_f32_16x16x32_bf16 v[34:37], v[174:177], v[190:193], v[34:37]
	v_mfma_f32_16x16x32_bf16 v[22:25], v[166:169], v[198:201], v[22:25]
	v_mfma_f32_16x16x32_bf16 v[18:21], v[174:177], v[198:201], v[18:21]
	v_mfma_f32_16x16x32_bf16 v[6:9], v[166:169], v[206:209], v[6:9]
	v_mfma_f32_16x16x32_bf16 v[2:5], v[174:177], v[206:209], v[2:5]
	v_mfma_f32_16x16x32_bf16 v[54:57], v[170:173], v[186:189], v[54:57]
	v_mfma_f32_16x16x32_bf16 v[50:53], v[178:181], v[186:189], v[50:53]
	v_mfma_f32_16x16x32_bf16 v[38:41], v[170:173], v[194:197], v[38:41]
	v_mfma_f32_16x16x32_bf16 v[34:37], v[178:181], v[194:197], v[34:37]
	v_mfma_f32_16x16x32_bf16 v[22:25], v[170:173], v[202:205], v[22:25]
	v_mfma_f32_16x16x32_bf16 v[18:21], v[178:181], v[202:205], v[18:21]
	v_mfma_f32_16x16x32_bf16 v[6:9], v[170:173], v[210:213], v[6:9]
	v_mfma_f32_16x16x32_bf16 v[2:5], v[178:181], v[210:213], v[2:5]
	s_barrier
	s_setprio 0
	s_add_i32 s71, s71, 2
	s_add_u32 s69, s69, 0x100
	s_addc_u32 s70, s70, 0
	s_add_u32 s40, s40, 0x100
	s_addc_u32 s41, s41, 0
	s_cmpk_gt_u32 s71, 0xa9
	s_cbranch_scc0 .LBB0_2118
	v_lshl_add_u32 v245, s68, 8, v146
	v_lshl_or_b32 v246, s67, 8, v148
	v_lshlrev_b32_e32 v245, 13, v245
	v_lshl_add_u32 v245, v246, 1, v245
	global_load_dwordx4 v[142:145], v245, s[24:25]
	global_load_dwordx4 v[154:157], v245, s[24:25] offset:256
	s_add_u32 s40, s24, 0x20000
	s_addc_u32 s41, s25, 0
	global_load_dwordx4 v[158:161], v245, s[40:41]
	global_load_dwordx4 v[162:165], v245, s[40:41] offset:256
	s_add_u32 s40, s24, 0x40000
	s_addc_u32 s41, s25, 0
	global_load_dwordx4 v[166:169], v245, s[40:41]
	global_load_dwordx4 v[170:173], v245, s[40:41] offset:256
	s_add_u32 s40, s24, 0x60000
	s_addc_u32 s41, s25, 0
	global_load_dwordx4 v[174:177], v245, s[40:41]
	global_load_dwordx4 v[178:181], v245, s[40:41] offset:256
	s_add_u32 s40, s24, 0x100000
	s_addc_u32 s41, s25, 0
	global_load_dwordx4 v[182:185], v245, s[40:41]
	global_load_dwordx4 v[186:189], v245, s[40:41] offset:256
	s_add_u32 s40, s24, 0x120000
	s_addc_u32 s41, s25, 0
	global_load_dwordx4 v[190:193], v245, s[40:41]
	global_load_dwordx4 v[194:197], v245, s[40:41] offset:256
	s_add_u32 s40, s24, 0x140000
	s_addc_u32 s41, s25, 0
	global_load_dwordx4 v[198:201], v245, s[40:41]
	global_load_dwordx4 v[202:205], v245, s[40:41] offset:256
	s_add_u32 s40, s24, 0x160000
	s_addc_u32 s41, s25, 0
	global_load_dwordx4 v[206:209], v245, s[40:41]
	global_load_dwordx4 v[210:213], v245, s[40:41] offset:256
	s_and_b64 vcc, exec, s[34:35]
	s_cbranch_vccz .LBB0_2121
	s_barrier

.LBB0_2159:
	ds_read_b128 v[2:5], v183
	ds_read_b128 v[6:9], v183 offset:1024
	ds_read_b128 v[138:141], v183 offset:2048
	ds_read_b128 v[142:145], v183 offset:3072
	ds_read_b128 v[146:149], v184
	ds_read_b128 v[150:153], v184 offset:1024
	ds_read_b128 v[168:171], v184 offset:2048
	ds_read_b128 v[172:175], v184 offset:3072
	s_add_u32 s10, s8, 0xfff80080
	s_addc_u32 s11, s9, -1
	s_cmp_eq_u32 s79, 28
	s_cselect_b32 s13, s41, s11
	s_cselect_b32 s12, s75, s10
	s_cselect_b32 s11, s39, s78
	s_cselect_b32 s10, s76, s77
	s_add_i32 m0, s15, 0xc000
	ds_read_b128 v[176:179], v185
	ds_read_b128 v[188:191], v185 offset:1024
	ds_read_b128 v[192:195], v185 offset:2048
	ds_read_b128 v[196:199], v185 offset:3072
	ds_read_b128 v[200:203], v185 offset:4096
	ds_read_b128 v[204:207], v185 offset:5120
	ds_read_b128 v[208:211], v185 offset:6144
	ds_read_b128 v[212:215], v185 offset:7168
	global_load_lds_dwordx4 v164, s[8:9]
	s_add_i32 m0, s15, 0xe000
	s_nop 0
	global_load_lds_dwordx4 v162, s[8:9]
	s_waitcnt vmcnt(8)
	s_waitcnt lgkmcnt(0)
	s_setprio 1
	s_barrier
	v_mfma_i32_16x16x64_i8 v[134:137], v[2:5], v[176:179], v[134:137]
	v_mfma_i32_16x16x64_i8 v[126:129], v[138:141], v[176:179], v[126:129]
	v_mfma_i32_16x16x64_i8 v[118:121], v[2:5], v[192:195], v[118:121]
	v_mfma_i32_16x16x64_i8 v[110:113], v[138:141], v[192:195], v[110:113]
	v_mfma_i32_16x16x64_i8 v[102:105], v[2:5], v[200:203], v[102:105]
	v_mfma_i32_16x16x64_i8 v[94:97], v[138:141], v[200:203], v[94:97]
	v_mfma_i32_16x16x64_i8 v[86:89], v[2:5], v[208:211], v[86:89]
	v_mfma_i32_16x16x64_i8 v[78:81], v[138:141], v[208:211], v[78:81]
	v_mfma_i32_16x16x64_i8 v[134:137], v[6:9], v[188:191], v[134:137]
	v_mfma_i32_16x16x64_i8 v[126:129], v[142:145], v[188:191], v[126:129]
	v_mfma_i32_16x16x64_i8 v[118:121], v[6:9], v[196:199], v[118:121]
	v_mfma_i32_16x16x64_i8 v[110:113], v[142:145], v[196:199], v[110:113]
	v_mfma_i32_16x16x64_i8 v[102:105], v[6:9], v[204:207], v[102:105]
	v_mfma_i32_16x16x64_i8 v[94:97], v[142:145], v[204:207], v[94:97]
	v_mfma_i32_16x16x64_i8 v[86:89], v[6:9], v[212:215], v[86:89]
	v_mfma_i32_16x16x64_i8 v[78:81], v[142:145], v[212:215], v[78:81]
	v_mfma_i32_16x16x64_i8 v[130:133], v[146:149], v[176:179], v[130:133]
	v_mfma_i32_16x16x64_i8 v[122:125], v[168:171], v[176:179], v[122:125]
	v_mfma_i32_16x16x64_i8 v[114:117], v[146:149], v[192:195], v[114:117]
	v_mfma_i32_16x16x64_i8 v[106:109], v[168:171], v[192:195], v[106:109]
	v_mfma_i32_16x16x64_i8 v[98:101], v[146:149], v[200:203], v[98:101]
	v_mfma_i32_16x16x64_i8 v[90:93], v[168:171], v[200:203], v[90:93]
	v_mfma_i32_16x16x64_i8 v[82:85], v[146:149], v[208:211], v[82:85]
	v_mfma_i32_16x16x64_i8 v[74:77], v[168:171], v[208:211], v[74:77]
	v_mfma_i32_16x16x64_i8 v[130:133], v[150:153], v[188:191], v[130:133]
	v_mfma_i32_16x16x64_i8 v[122:125], v[172:175], v[188:191], v[122:125]
	v_mfma_i32_16x16x64_i8 v[114:117], v[150:153], v[196:199], v[114:117]
	v_mfma_i32_16x16x64_i8 v[106:109], v[172:175], v[196:199], v[106:109]
	v_mfma_i32_16x16x64_i8 v[98:101], v[150:153], v[204:207], v[98:101]
	v_mfma_i32_16x16x64_i8 v[90:93], v[172:175], v[204:207], v[90:93]
	v_mfma_i32_16x16x64_i8 v[82:85], v[150:153], v[212:215], v[82:85]
	v_mfma_i32_16x16x64_i8 v[74:77], v[172:175], v[212:215], v[74:77]
	s_barrier
	s_setprio 0
	s_add_i32 s16, s69, s56
	v_lshl_add_u64 v[216:217], s[10:11], 0, v[156:157]
	s_mov_b32 m0, s16
	ds_read_b128 v[176:179], v185 offset:16384
	ds_read_b128 v[188:191], v185 offset:17408
	ds_read_b128 v[192:195], v185 offset:18432
	ds_read_b128 v[196:199], v185 offset:19456
	ds_read_b128 v[200:203], v185 offset:20480
	ds_read_b128 v[204:207], v185 offset:21504
	ds_read_b128 v[208:211], v185 offset:22528
	ds_read_b128 v[212:215], v185 offset:23552
	global_load_lds_dwordx4 v[216:217], off
	s_add_i32 m0, s16, 0x2000
	s_add_u32 s16, s10, 0x80000
	v_lshl_add_u64 v[218:219], s[10:11], 0, v[160:161]
	s_addc_u32 s17, s11, 0
	s_add_i32 s80, s70, s56
	global_load_lds_dwordx4 v[218:219], off
	s_mov_b32 m0, s80
	v_lshl_add_u64 v[222:223], s[12:13], 0, v[158:159]
	global_load_lds_dwordx4 v156, s[16:17]
	s_add_i32 m0, s80, 0x2000
	s_nop 0
	global_load_lds_dwordx4 v160, s[16:17]
	v_lshl_add_u64 v[220:221], s[12:13], 0, v[154:155]
	s_mov_b32 m0, s15
	s_nop 0
	global_load_lds_dwordx4 v[220:221], off
	s_mov_b32 m0, s60
	s_nop 0
	global_load_lds_dwordx4 v[222:223], off
	s_waitcnt vmcnt(8)
	s_waitcnt lgkmcnt(0)
	s_setprio 1
	s_barrier
	v_mfma_i32_16x16x64_i8 v[70:73], v[2:5], v[176:179], v[70:73]
	v_mfma_i32_16x16x64_i8 v[62:65], v[138:141], v[176:179], v[62:65]
	v_mfma_i32_16x16x64_i8 v[54:57], v[2:5], v[192:195], v[54:57]
	v_mfma_i32_16x16x64_i8 v[46:49], v[138:141], v[192:195], v[46:49]
	v_mfma_i32_16x16x64_i8 v[38:41], v[2:5], v[200:203], v[38:41]
	v_mfma_i32_16x16x64_i8 v[30:33], v[138:141], v[200:203], v[30:33]
	v_mfma_i32_16x16x64_i8 v[2:5], v[2:5], v[208:211], v[22:25]
	v_mfma_i32_16x16x64_i8 v[70:73], v[6:9], v[188:191], v[70:73]
	v_mfma_i32_16x16x64_i8 v[62:65], v[142:145], v[188:191], v[62:65]
	v_mfma_i32_16x16x64_i8 v[54:57], v[6:9], v[196:199], v[54:57]
	v_mfma_i32_16x16x64_i8 v[46:49], v[142:145], v[196:199], v[46:49]
	v_mfma_i32_16x16x64_i8 v[38:41], v[6:9], v[204:207], v[38:41]
	v_mfma_i32_16x16x64_i8 v[30:33], v[142:145], v[204:207], v[30:33]
	v_mfma_i32_16x16x64_i8 v[2:5], v[6:9], v[212:215], v[2:5]
	v_mfma_i32_16x16x64_i8 v[6:9], v[138:141], v[208:211], v[14:17]
	v_mfma_i32_16x16x64_i8 v[6:9], v[142:145], v[212:215], v[6:9]
	v_mfma_i32_16x16x64_i8 v[14:17], v[146:149], v[176:179], v[66:69]
	v_mfma_i32_16x16x64_i8 v[66:69], v[150:153], v[188:191], v[14:17]
	v_mfma_i32_16x16x64_i8 v[14:17], v[168:171], v[176:179], v[58:61]
	v_mfma_i32_16x16x64_i8 v[58:61], v[172:175], v[188:191], v[14:17]
	v_mfma_i32_16x16x64_i8 v[14:17], v[146:149], v[192:195], v[50:53]
	v_mfma_i32_16x16x64_i8 v[50:53], v[150:153], v[196:199], v[14:17]
	v_mfma_i32_16x16x64_i8 v[14:17], v[168:171], v[192:195], v[42:45]
	v_mfma_i32_16x16x64_i8 v[42:45], v[172:175], v[196:199], v[14:17]
	v_mfma_i32_16x16x64_i8 v[14:17], v[146:149], v[200:203], v[34:37]
	v_mfma_i32_16x16x64_i8 v[34:37], v[150:153], v[204:207], v[14:17]
	v_mfma_i32_16x16x64_i8 v[14:17], v[168:171], v[200:203], v[26:29]
	v_mfma_i32_16x16x64_i8 v[26:29], v[172:175], v[204:207], v[14:17]
	v_mfma_i32_16x16x64_i8 v[14:17], v[146:149], v[208:211], v[18:21]
	v_mfma_i32_16x16x64_i8 v[10:13], v[168:171], v[208:211], v[10:13]
	v_mfma_i32_16x16x64_i8 v[18:21], v[150:153], v[212:215], v[14:17]
	v_mfma_i32_16x16x64_i8 v[10:13], v[172:175], v[212:215], v[10:13]
	s_barrier
	s_setprio 0
	s_add_i32 s16, 0, 0x18000
	s_add_i32 s17, 0, 0x1c000
	v_add_u32_e32 v142, s16, v181
	v_add_u32_e32 v172, s17, v181
	ds_read_b128 v[14:17], v142
	ds_read_b128 v[22:25], v142 offset:1024
	ds_read_b128 v[138:141], v142 offset:2048
	ds_read_b128 v[142:145], v142 offset:3072
	ds_read_b128 v[146:149], v172
	ds_read_b128 v[150:153], v172 offset:1024
	ds_read_b128 v[168:171], v172 offset:2048
	ds_read_b128 v[172:175], v172 offset:3072
	s_add_u32 s12, s12, 0x80000
	s_addc_u32 s13, s13, 0
	s_mov_b32 m0, s61
	ds_read_b128 v[176:179], v185 offset:32768
	ds_read_b128 v[188:191], v185 offset:33792
	ds_read_b128 v[192:195], v185 offset:34816
	ds_read_b128 v[196:199], v185 offset:35840
	ds_read_b128 v[200:203], v185 offset:36864
	ds_read_b128 v[204:207], v185 offset:37888
	ds_read_b128 v[208:211], v185 offset:38912
	ds_read_b128 v[212:215], v185 offset:39936
	global_load_lds_dwordx4 v154, s[12:13]
	s_mov_b32 m0, s62
	s_nop 0
	global_load_lds_dwordx4 v158, s[12:13]
	s_waitcnt vmcnt(8)
	s_waitcnt lgkmcnt(0)
	s_setprio 1
	s_barrier
	v_mfma_i32_16x16x64_i8 v[134:137], v[14:17], v[176:179], v[134:137]
	v_mfma_i32_16x16x64_i8 v[126:129], v[138:141], v[176:179], v[126:129]
	v_mfma_i32_16x16x64_i8 v[118:121], v[14:17], v[192:195], v[118:121]
	v_mfma_i32_16x16x64_i8 v[110:113], v[138:141], v[192:195], v[110:113]
	v_mfma_i32_16x16x64_i8 v[102:105], v[14:17], v[200:203], v[102:105]
	v_mfma_i32_16x16x64_i8 v[94:97], v[138:141], v[200:203], v[94:97]
	v_mfma_i32_16x16x64_i8 v[86:89], v[14:17], v[208:211], v[86:89]
	v_mfma_i32_16x16x64_i8 v[78:81], v[138:141], v[208:211], v[78:81]
	v_mfma_i32_16x16x64_i8 v[134:137], v[22:25], v[188:191], v[134:137]
	v_mfma_i32_16x16x64_i8 v[126:129], v[142:145], v[188:191], v[126:129]
	v_mfma_i32_16x16x64_i8 v[118:121], v[22:25], v[196:199], v[118:121]
	v_mfma_i32_16x16x64_i8 v[110:113], v[142:145], v[196:199], v[110:113]
	v_mfma_i32_16x16x64_i8 v[102:105], v[22:25], v[204:207], v[102:105]
	v_mfma_i32_16x16x64_i8 v[94:97], v[142:145], v[204:207], v[94:97]
	v_mfma_i32_16x16x64_i8 v[86:89], v[22:25], v[212:215], v[86:89]
	v_mfma_i32_16x16x64_i8 v[78:81], v[142:145], v[212:215], v[78:81]
	v_mfma_i32_16x16x64_i8 v[130:133], v[146:149], v[176:179], v[130:133]
	v_mfma_i32_16x16x64_i8 v[122:125], v[168:171], v[176:179], v[122:125]
	v_mfma_i32_16x16x64_i8 v[114:117], v[146:149], v[192:195], v[114:117]
	v_mfma_i32_16x16x64_i8 v[106:109], v[168:171], v[192:195], v[106:109]
	v_mfma_i32_16x16x64_i8 v[98:101], v[146:149], v[200:203], v[98:101]
	v_mfma_i32_16x16x64_i8 v[90:93], v[168:171], v[200:203], v[90:93]
	v_mfma_i32_16x16x64_i8 v[82:85], v[146:149], v[208:211], v[82:85]
	v_mfma_i32_16x16x64_i8 v[74:77], v[168:171], v[208:211], v[74:77]
	v_mfma_i32_16x16x64_i8 v[130:133], v[150:153], v[188:191], v[130:133]
	v_mfma_i32_16x16x64_i8 v[122:125], v[172:175], v[188:191], v[122:125]
	v_mfma_i32_16x16x64_i8 v[114:117], v[150:153], v[196:199], v[114:117]
	v_mfma_i32_16x16x64_i8 v[106:109], v[172:175], v[196:199], v[106:109]
	v_mfma_i32_16x16x64_i8 v[98:101], v[150:153], v[204:207], v[98:101]
	v_mfma_i32_16x16x64_i8 v[90:93], v[172:175], v[204:207], v[90:93]
	v_mfma_i32_16x16x64_i8 v[82:85], v[150:153], v[212:215], v[82:85]
	v_mfma_i32_16x16x64_i8 v[74:77], v[172:175], v[212:215], v[74:77]
	s_barrier
	s_setprio 0
	s_add_i32 s12, s16, s56
	v_lshl_add_u64 v[216:217], v[216:217], 0, s[34:35]
	s_mov_b32 m0, s12
	ds_read_b128 v[176:179], v185 offset:49152
	ds_read_b128 v[188:191], v185 offset:50176
	ds_read_b128 v[192:195], v185 offset:51200
	ds_read_b128 v[196:199], v185 offset:52224
	ds_read_b128 v[200:203], v185 offset:53248
	ds_read_b128 v[204:207], v185 offset:54272
	ds_read_b128 v[208:211], v185 offset:55296
	ds_read_b128 v[212:215], v185 offset:56320
	global_load_lds_dwordx4 v[216:217], off
	s_add_i32 m0, s12, 0x2000
	s_add_u32 s10, s10, 0x80080
	v_lshl_add_u64 v[216:217], v[218:219], 0, s[34:35]
	s_addc_u32 s11, s11, 0
	s_add_i32 s12, s17, s56
	global_load_lds_dwordx4 v[216:217], off
	s_mov_b32 m0, s12
	s_nop 0
	global_load_lds_dwordx4 v156, s[10:11]
	s_add_i32 m0, s12, 0x2000
	s_nop 0
	global_load_lds_dwordx4 v160, s[10:11]
	v_lshl_add_u64 v[216:217], v[220:221], 0, s[34:35]
	s_mov_b32 m0, s64
	s_nop 0
	global_load_lds_dwordx4 v[216:217], off
	v_lshl_add_u64 v[216:217], v[222:223], 0, s[34:35]
	s_mov_b32 m0, s65
	s_nop 0
	global_load_lds_dwordx4 v[216:217], off
	s_waitcnt vmcnt(8)
	s_waitcnt lgkmcnt(0)
	s_setprio 1
	s_barrier
	v_mfma_i32_16x16x64_i8 v[70:73], v[14:17], v[176:179], v[70:73]
	v_mfma_i32_16x16x64_i8 v[54:57], v[14:17], v[192:195], v[54:57]
	v_mfma_i32_16x16x64_i8 v[38:41], v[14:17], v[200:203], v[38:41]
	v_mfma_i32_16x16x64_i8 v[2:5], v[14:17], v[208:211], v[2:5]
	v_mfma_i32_16x16x64_i8 v[70:73], v[22:25], v[188:191], v[70:73]
	v_mfma_i32_16x16x64_i8 v[62:65], v[138:141], v[176:179], v[62:65]
	v_mfma_i32_16x16x64_i8 v[54:57], v[22:25], v[196:199], v[54:57]
	v_mfma_i32_16x16x64_i8 v[46:49], v[138:141], v[192:195], v[46:49]
	v_mfma_i32_16x16x64_i8 v[38:41], v[22:25], v[204:207], v[38:41]
	v_mfma_i32_16x16x64_i8 v[30:33], v[138:141], v[200:203], v[30:33]
	v_mfma_i32_16x16x64_i8 v[22:25], v[22:25], v[212:215], v[2:5]
	v_mfma_i32_16x16x64_i8 v[2:5], v[138:141], v[208:211], v[6:9]
	v_mfma_i32_16x16x64_i8 v[62:65], v[142:145], v[188:191], v[62:65]
	v_mfma_i32_16x16x64_i8 v[46:49], v[142:145], v[196:199], v[46:49]
	v_mfma_i32_16x16x64_i8 v[30:33], v[142:145], v[204:207], v[30:33]
	v_mfma_i32_16x16x64_i8 v[14:17], v[142:145], v[212:215], v[2:5]
	v_mfma_i32_16x16x64_i8 v[2:5], v[146:149], v[176:179], v[66:69]
	v_mfma_i32_16x16x64_i8 v[66:69], v[150:153], v[188:191], v[2:5]
	v_mfma_i32_16x16x64_i8 v[2:5], v[168:171], v[176:179], v[58:61]
	v_mfma_i32_16x16x64_i8 v[58:61], v[172:175], v[188:191], v[2:5]
	v_mfma_i32_16x16x64_i8 v[2:5], v[146:149], v[192:195], v[50:53]
	v_mfma_i32_16x16x64_i8 v[50:53], v[150:153], v[196:199], v[2:5]
	v_mfma_i32_16x16x64_i8 v[2:5], v[168:171], v[192:195], v[42:45]
	v_mfma_i32_16x16x64_i8 v[42:45], v[172:175], v[196:199], v[2:5]
	v_mfma_i32_16x16x64_i8 v[2:5], v[146:149], v[200:203], v[34:37]
	v_mfma_i32_16x16x64_i8 v[34:37], v[150:153], v[204:207], v[2:5]
	v_mfma_i32_16x16x64_i8 v[2:5], v[168:171], v[200:203], v[26:29]
	v_mfma_i32_16x16x64_i8 v[26:29], v[172:175], v[204:207], v[2:5]
	v_mfma_i32_16x16x64_i8 v[2:5], v[146:149], v[208:211], v[18:21]
	v_mfma_i32_16x16x64_i8 v[18:21], v[150:153], v[212:215], v[2:5]
	v_mfma_i32_16x16x64_i8 v[2:5], v[168:171], v[208:211], v[10:13]
	v_mfma_i32_16x16x64_i8 v[10:13], v[172:175], v[212:215], v[2:5]
	s_barrier
	s_setprio 0
	s_add_i32 s79, s79, 2
	s_add_u32 s77, s77, 0x100
	s_addc_u32 s78, s78, 0
	s_add_u32 s8, s8, 0x100
	s_addc_u32 s9, s9, 0
	s_cmp_gt_u32 s79, 29
	s_cbranch_scc0 .LBB0_2159
	s_and_b64 vcc, exec, s[36:37]
	s_cbranch_vccz .LBB0_2162
	s_barrier

.LBB0_2248:
	ds_read_b128 v[146:149], v152
	ds_read_b128 v[156:159], v152 offset:1024
	ds_read_b128 v[160:163], v152 offset:2048
	ds_read_b128 v[164:167], v152 offset:3072
	ds_read_b128 v[168:171], v153
	ds_read_b128 v[172:175], v153 offset:1024
	ds_read_b128 v[176:179], v153 offset:2048
	ds_read_b128 v[180:183], v153 offset:3072
	s_add_u32 s28, s26, 0xffd50080
	s_addc_u32 s29, s27, -1
	s_cmpk_eq_i32 s64, 0xa8
	s_cselect_b32 s31, s11, s29
	s_cselect_b32 s30, s10, s28
	s_cselect_b32 s29, s25, s63
	s_cselect_b32 s28, s24, s62
	s_add_i32 m0, s38, 0xc000
	ds_read_b128 v[184:187], v154
	ds_read_b128 v[188:191], v154 offset:1024
	ds_read_b128 v[192:195], v154 offset:2048
	ds_read_b128 v[196:199], v154 offset:3072
	ds_read_b128 v[200:203], v154 offset:4096
	ds_read_b128 v[204:207], v154 offset:5120
	ds_read_b128 v[208:211], v154 offset:6144
	ds_read_b128 v[212:215], v154 offset:7168
	global_load_lds_dwordx4 v140, s[26:27]
	s_add_i32 m0, s38, 0xe000
	s_nop 0
	global_load_lds_dwordx4 v138, s[26:27]
	s_waitcnt vmcnt(8)
	s_waitcnt lgkmcnt(0)
	s_setprio 1
	s_barrier
	v_mfma_f32_16x16x32_bf16 v[126:129], v[146:149], v[184:187], v[126:129]
	v_mfma_f32_16x16x32_bf16 v[122:125], v[160:163], v[184:187], v[122:125]
	v_mfma_f32_16x16x32_bf16 v[110:113], v[146:149], v[192:195], v[110:113]
	v_mfma_f32_16x16x32_bf16 v[106:109], v[160:163], v[192:195], v[106:109]
	v_mfma_f32_16x16x32_bf16 v[94:97], v[146:149], v[200:203], v[94:97]
	v_mfma_f32_16x16x32_bf16 v[90:93], v[160:163], v[200:203], v[90:93]
	v_mfma_f32_16x16x32_bf16 v[78:81], v[146:149], v[208:211], v[78:81]
	v_mfma_f32_16x16x32_bf16 v[74:77], v[160:163], v[208:211], v[74:77]
	v_mfma_f32_16x16x32_bf16 v[126:129], v[156:159], v[188:191], v[126:129]
	v_mfma_f32_16x16x32_bf16 v[122:125], v[164:167], v[188:191], v[122:125]
	v_mfma_f32_16x16x32_bf16 v[110:113], v[156:159], v[196:199], v[110:113]
	v_mfma_f32_16x16x32_bf16 v[106:109], v[164:167], v[196:199], v[106:109]
	v_mfma_f32_16x16x32_bf16 v[94:97], v[156:159], v[204:207], v[94:97]
	v_mfma_f32_16x16x32_bf16 v[90:93], v[164:167], v[204:207], v[90:93]
	v_mfma_f32_16x16x32_bf16 v[78:81], v[156:159], v[212:215], v[78:81]
	v_mfma_f32_16x16x32_bf16 v[74:77], v[164:167], v[212:215], v[74:77]
	v_mfma_f32_16x16x32_bf16 v[118:121], v[168:171], v[184:187], v[118:121]
	v_mfma_f32_16x16x32_bf16 v[114:117], v[176:179], v[184:187], v[114:117]
	v_mfma_f32_16x16x32_bf16 v[102:105], v[168:171], v[192:195], v[102:105]
	v_mfma_f32_16x16x32_bf16 v[98:101], v[176:179], v[192:195], v[98:101]
	v_mfma_f32_16x16x32_bf16 v[86:89], v[168:171], v[200:203], v[86:89]
	v_mfma_f32_16x16x32_bf16 v[82:85], v[176:179], v[200:203], v[82:85]
	v_mfma_f32_16x16x32_bf16 v[70:73], v[168:171], v[208:211], v[70:73]
	v_mfma_f32_16x16x32_bf16 v[66:69], v[176:179], v[208:211], v[66:69]
	v_mfma_f32_16x16x32_bf16 v[118:121], v[172:175], v[188:191], v[118:121]
	v_mfma_f32_16x16x32_bf16 v[114:117], v[180:183], v[188:191], v[114:117]
	v_mfma_f32_16x16x32_bf16 v[102:105], v[172:175], v[196:199], v[102:105]
	v_mfma_f32_16x16x32_bf16 v[98:101], v[180:183], v[196:199], v[98:101]
	v_mfma_f32_16x16x32_bf16 v[86:89], v[172:175], v[204:207], v[86:89]
	v_mfma_f32_16x16x32_bf16 v[82:85], v[180:183], v[204:207], v[82:85]
	v_mfma_f32_16x16x32_bf16 v[70:73], v[172:175], v[212:215], v[70:73]
	v_mfma_f32_16x16x32_bf16 v[66:69], v[180:183], v[212:215], v[66:69]
	s_barrier
	s_setprio 0
	s_add_i32 s65, s47, s37
	v_lshl_add_u64 v[216:217], s[28:29], 0, v[132:133]
	s_mov_b32 m0, s65
	ds_read_b128 v[184:187], v154 offset:16384
	ds_read_b128 v[188:191], v154 offset:17408
	ds_read_b128 v[192:195], v154 offset:18432
	ds_read_b128 v[196:199], v154 offset:19456
	ds_read_b128 v[200:203], v154 offset:20480
	ds_read_b128 v[204:207], v154 offset:21504
	ds_read_b128 v[208:211], v154 offset:22528
	ds_read_b128 v[212:215], v154 offset:23552
	global_load_lds_dwordx4 v[216:217], off
	s_add_i32 m0, s65, 0x2000
	s_add_u32 s66, s28, 0x2b0000
	v_lshl_add_u64 v[218:219], s[28:29], 0, v[136:137]
	s_addc_u32 s67, s29, 0
	s_add_i32 s65, s49, s37
	global_load_lds_dwordx4 v[218:219], off
	s_mov_b32 m0, s65
	v_lshl_add_u64 v[222:223], s[30:31], 0, v[134:135]
	global_load_lds_dwordx4 v132, s[66:67]
	s_add_i32 m0, s65, 0x2000
	s_nop 0
	global_load_lds_dwordx4 v136, s[66:67]
	v_lshl_add_u64 v[220:221], s[30:31], 0, v[130:131]
	s_mov_b32 m0, s38
	s_nop 0
	global_load_lds_dwordx4 v[220:221], off
	s_mov_b32 m0, s39
	s_nop 0
	global_load_lds_dwordx4 v[222:223], off
	s_waitcnt vmcnt(8)
	s_waitcnt lgkmcnt(0)
	s_setprio 1
	s_barrier
	v_mfma_f32_16x16x32_bf16 v[62:65], v[146:149], v[184:187], v[62:65]
	v_mfma_f32_16x16x32_bf16 v[58:61], v[160:163], v[184:187], v[58:61]
	v_mfma_f32_16x16x32_bf16 v[46:49], v[146:149], v[192:195], v[46:49]
	v_mfma_f32_16x16x32_bf16 v[42:45], v[160:163], v[192:195], v[42:45]
	v_mfma_f32_16x16x32_bf16 v[30:33], v[146:149], v[200:203], v[30:33]
	v_mfma_f32_16x16x32_bf16 v[26:29], v[160:163], v[200:203], v[26:29]
	v_mfma_f32_16x16x32_bf16 v[14:17], v[146:149], v[208:211], v[14:17]
	v_mfma_f32_16x16x32_bf16 v[10:13], v[160:163], v[208:211], v[10:13]
	v_mfma_f32_16x16x32_bf16 v[62:65], v[156:159], v[188:191], v[62:65]
	v_mfma_f32_16x16x32_bf16 v[58:61], v[164:167], v[188:191], v[58:61]
	v_mfma_f32_16x16x32_bf16 v[46:49], v[156:159], v[196:199], v[46:49]
	v_mfma_f32_16x16x32_bf16 v[42:45], v[164:167], v[196:199], v[42:45]
	v_mfma_f32_16x16x32_bf16 v[30:33], v[156:159], v[204:207], v[30:33]
	v_mfma_f32_16x16x32_bf16 v[26:29], v[164:167], v[204:207], v[26:29]
	v_mfma_f32_16x16x32_bf16 v[14:17], v[156:159], v[212:215], v[14:17]
	v_mfma_f32_16x16x32_bf16 v[10:13], v[164:167], v[212:215], v[10:13]
	v_mfma_f32_16x16x32_bf16 v[54:57], v[168:171], v[184:187], v[54:57]
	v_mfma_f32_16x16x32_bf16 v[50:53], v[176:179], v[184:187], v[50:53]
	v_mfma_f32_16x16x32_bf16 v[38:41], v[168:171], v[192:195], v[38:41]
	v_mfma_f32_16x16x32_bf16 v[34:37], v[176:179], v[192:195], v[34:37]
	v_mfma_f32_16x16x32_bf16 v[22:25], v[168:171], v[200:203], v[22:25]
	v_mfma_f32_16x16x32_bf16 v[18:21], v[176:179], v[200:203], v[18:21]
	v_mfma_f32_16x16x32_bf16 v[6:9], v[168:171], v[208:211], v[6:9]
	v_mfma_f32_16x16x32_bf16 v[2:5], v[176:179], v[208:211], v[2:5]
	v_mfma_f32_16x16x32_bf16 v[54:57], v[172:175], v[188:191], v[54:57]
	v_mfma_f32_16x16x32_bf16 v[50:53], v[180:183], v[188:191], v[50:53]
	v_mfma_f32_16x16x32_bf16 v[38:41], v[172:175], v[196:199], v[38:41]
	v_mfma_f32_16x16x32_bf16 v[34:37], v[180:183], v[196:199], v[34:37]
	v_mfma_f32_16x16x32_bf16 v[22:25], v[172:175], v[204:207], v[22:25]
	v_mfma_f32_16x16x32_bf16 v[18:21], v[180:183], v[204:207], v[18:21]
	v_mfma_f32_16x16x32_bf16 v[6:9], v[172:175], v[212:215], v[6:9]
	v_mfma_f32_16x16x32_bf16 v[2:5], v[180:183], v[212:215], v[2:5]
	s_barrier
	s_setprio 0
	s_add_i32 s65, 0, 0x18000
	s_add_i32 s66, 0, 0x1c000
	v_add_u32_e32 v164, s65, v150
	v_add_u32_e32 v180, s66, v150
	ds_read_b128 v[146:149], v164
	ds_read_b128 v[156:159], v164 offset:1024
	ds_read_b128 v[160:163], v164 offset:2048
	ds_read_b128 v[164:167], v164 offset:3072
	ds_read_b128 v[168:171], v180
	ds_read_b128 v[172:175], v180 offset:1024
	ds_read_b128 v[176:179], v180 offset:2048
	ds_read_b128 v[180:183], v180 offset:3072
	s_add_u32 s30, s30, 0x2b0000
	s_addc_u32 s31, s31, 0
	s_mov_b32 m0, s40
	ds_read_b128 v[184:187], v154 offset:32768
	ds_read_b128 v[188:191], v154 offset:33792
	ds_read_b128 v[192:195], v154 offset:34816
	ds_read_b128 v[196:199], v154 offset:35840
	ds_read_b128 v[200:203], v154 offset:36864
	ds_read_b128 v[204:207], v154 offset:37888
	ds_read_b128 v[208:211], v154 offset:38912
	ds_read_b128 v[212:215], v154 offset:39936
	global_load_lds_dwordx4 v130, s[30:31]
	s_mov_b32 m0, s41
	s_nop 0
	global_load_lds_dwordx4 v134, s[30:31]
	s_waitcnt vmcnt(8)
	s_waitcnt lgkmcnt(0)
	s_setprio 1
	s_barrier
	v_mfma_f32_16x16x32_bf16 v[126:129], v[146:149], v[184:187], v[126:129]
	v_mfma_f32_16x16x32_bf16 v[122:125], v[160:163], v[184:187], v[122:125]
	v_mfma_f32_16x16x32_bf16 v[110:113], v[146:149], v[192:195], v[110:113]
	v_mfma_f32_16x16x32_bf16 v[106:109], v[160:163], v[192:195], v[106:109]
	v_mfma_f32_16x16x32_bf16 v[94:97], v[146:149], v[200:203], v[94:97]
	v_mfma_f32_16x16x32_bf16 v[90:93], v[160:163], v[200:203], v[90:93]
	v_mfma_f32_16x16x32_bf16 v[78:81], v[146:149], v[208:211], v[78:81]
	v_mfma_f32_16x16x32_bf16 v[74:77], v[160:163], v[208:211], v[74:77]
	v_mfma_f32_16x16x32_bf16 v[126:129], v[156:159], v[188:191], v[126:129]
	v_mfma_f32_16x16x32_bf16 v[122:125], v[164:167], v[188:191], v[122:125]
	v_mfma_f32_16x16x32_bf16 v[110:113], v[156:159], v[196:199], v[110:113]
	v_mfma_f32_16x16x32_bf16 v[106:109], v[164:167], v[196:199], v[106:109]
	v_mfma_f32_16x16x32_bf16 v[94:97], v[156:159], v[204:207], v[94:97]
	v_mfma_f32_16x16x32_bf16 v[90:93], v[164:167], v[204:207], v[90:93]
	v_mfma_f32_16x16x32_bf16 v[78:81], v[156:159], v[212:215], v[78:81]
	v_mfma_f32_16x16x32_bf16 v[74:77], v[164:167], v[212:215], v[74:77]
	v_mfma_f32_16x16x32_bf16 v[118:121], v[168:171], v[184:187], v[118:121]
	v_mfma_f32_16x16x32_bf16 v[114:117], v[176:179], v[184:187], v[114:117]
	v_mfma_f32_16x16x32_bf16 v[102:105], v[168:171], v[192:195], v[102:105]
	v_mfma_f32_16x16x32_bf16 v[98:101], v[176:179], v[192:195], v[98:101]
	v_mfma_f32_16x16x32_bf16 v[86:89], v[168:171], v[200:203], v[86:89]
	v_mfma_f32_16x16x32_bf16 v[82:85], v[176:179], v[200:203], v[82:85]
	v_mfma_f32_16x16x32_bf16 v[70:73], v[168:171], v[208:211], v[70:73]
	v_mfma_f32_16x16x32_bf16 v[66:69], v[176:179], v[208:211], v[66:69]
	v_mfma_f32_16x16x32_bf16 v[118:121], v[172:175], v[188:191], v[118:121]
	v_mfma_f32_16x16x32_bf16 v[114:117], v[180:183], v[188:191], v[114:117]
	v_mfma_f32_16x16x32_bf16 v[102:105], v[172:175], v[196:199], v[102:105]
	v_mfma_f32_16x16x32_bf16 v[98:101], v[180:183], v[196:199], v[98:101]
	v_mfma_f32_16x16x32_bf16 v[86:89], v[172:175], v[204:207], v[86:89]
	v_mfma_f32_16x16x32_bf16 v[82:85], v[180:183], v[204:207], v[82:85]
	v_mfma_f32_16x16x32_bf16 v[70:73], v[172:175], v[212:215], v[70:73]
	v_mfma_f32_16x16x32_bf16 v[66:69], v[180:183], v[212:215], v[66:69]
	s_barrier
	s_setprio 0
	s_add_i32 s30, s65, s37
	v_lshl_add_u64 v[216:217], v[216:217], 0, s[20:21]
	s_mov_b32 m0, s30
	ds_read_b128 v[184:187], v154 offset:49152
	ds_read_b128 v[188:191], v154 offset:50176
	ds_read_b128 v[192:195], v154 offset:51200
	ds_read_b128 v[196:199], v154 offset:52224
	ds_read_b128 v[200:203], v154 offset:53248
	ds_read_b128 v[204:207], v154 offset:54272
	ds_read_b128 v[208:211], v154 offset:55296
	ds_read_b128 v[212:215], v154 offset:56320
	global_load_lds_dwordx4 v[216:217], off
	s_add_i32 m0, s30, 0x2000
	s_add_u32 s28, s28, 0x2b0080
	v_lshl_add_u64 v[216:217], v[218:219], 0, s[20:21]
	s_addc_u32 s29, s29, 0
	s_add_i32 s30, s66, s37
	global_load_lds_dwordx4 v[216:217], off
	s_mov_b32 m0, s30
	s_nop 0
	global_load_lds_dwordx4 v132, s[28:29]
	s_add_i32 m0, s30, 0x2000
	s_nop 0
	global_load_lds_dwordx4 v136, s[28:29]
	v_lshl_add_u64 v[216:217], v[220:221], 0, s[20:21]
	s_mov_b32 m0, s44
	s_nop 0
	global_load_lds_dwordx4 v[216:217], off
	v_lshl_add_u64 v[216:217], v[222:223], 0, s[20:21]
	s_mov_b32 m0, s45
	s_nop 0
	global_load_lds_dwordx4 v[216:217], off
	s_waitcnt vmcnt(8)
	s_waitcnt lgkmcnt(0)
	s_setprio 1
	s_barrier
	v_mfma_f32_16x16x32_bf16 v[62:65], v[146:149], v[184:187], v[62:65]
	v_mfma_f32_16x16x32_bf16 v[58:61], v[160:163], v[184:187], v[58:61]
	v_mfma_f32_16x16x32_bf16 v[46:49], v[146:149], v[192:195], v[46:49]
	v_mfma_f32_16x16x32_bf16 v[42:45], v[160:163], v[192:195], v[42:45]
	v_mfma_f32_16x16x32_bf16 v[30:33], v[146:149], v[200:203], v[30:33]
	v_mfma_f32_16x16x32_bf16 v[26:29], v[160:163], v[200:203], v[26:29]
	v_mfma_f32_16x16x32_bf16 v[14:17], v[146:149], v[208:211], v[14:17]
	v_mfma_f32_16x16x32_bf16 v[10:13], v[160:163], v[208:211], v[10:13]
	v_mfma_f32_16x16x32_bf16 v[62:65], v[156:159], v[188:191], v[62:65]
	v_mfma_f32_16x16x32_bf16 v[58:61], v[164:167], v[188:191], v[58:61]
	v_mfma_f32_16x16x32_bf16 v[46:49], v[156:159], v[196:199], v[46:49]
	v_mfma_f32_16x16x32_bf16 v[42:45], v[164:167], v[196:199], v[42:45]
	v_mfma_f32_16x16x32_bf16 v[30:33], v[156:159], v[204:207], v[30:33]
	v_mfma_f32_16x16x32_bf16 v[26:29], v[164:167], v[204:207], v[26:29]
	v_mfma_f32_16x16x32_bf16 v[14:17], v[156:159], v[212:215], v[14:17]
	v_mfma_f32_16x16x32_bf16 v[10:13], v[164:167], v[212:215], v[10:13]
	v_mfma_f32_16x16x32_bf16 v[54:57], v[168:171], v[184:187], v[54:57]
	v_mfma_f32_16x16x32_bf16 v[50:53], v[176:179], v[184:187], v[50:53]
	v_mfma_f32_16x16x32_bf16 v[38:41], v[168:171], v[192:195], v[38:41]
	v_mfma_f32_16x16x32_bf16 v[34:37], v[176:179], v[192:195], v[34:37]
	v_mfma_f32_16x16x32_bf16 v[22:25], v[168:171], v[200:203], v[22:25]
	v_mfma_f32_16x16x32_bf16 v[18:21], v[176:179], v[200:203], v[18:21]
	v_mfma_f32_16x16x32_bf16 v[6:9], v[168:171], v[208:211], v[6:9]
	v_mfma_f32_16x16x32_bf16 v[2:5], v[176:179], v[208:211], v[2:5]
	v_mfma_f32_16x16x32_bf16 v[54:57], v[172:175], v[188:191], v[54:57]
	v_mfma_f32_16x16x32_bf16 v[50:53], v[180:183], v[188:191], v[50:53]
	v_mfma_f32_16x16x32_bf16 v[38:41], v[172:175], v[196:199], v[38:41]
	v_mfma_f32_16x16x32_bf16 v[34:37], v[180:183], v[196:199], v[34:37]
	v_mfma_f32_16x16x32_bf16 v[22:25], v[172:175], v[204:207], v[22:25]
	v_mfma_f32_16x16x32_bf16 v[18:21], v[180:183], v[204:207], v[18:21]
	v_mfma_f32_16x16x32_bf16 v[6:9], v[172:175], v[212:215], v[6:9]
	v_mfma_f32_16x16x32_bf16 v[2:5], v[180:183], v[212:215], v[2:5]
	s_barrier
	s_setprio 0
	s_add_i32 s64, s64, 2
	s_add_u32 s62, s62, 0x100
	s_addc_u32 s63, s63, 0
	s_add_u32 s26, s26, 0x100
	s_addc_u32 s27, s27, 0
	s_cmpk_gt_u32 s64, 0xa9
	s_cbranch_scc0 .LBB0_2248
	v_lshl_add_u32 v245, s60, 8, v1
	v_lshl_or_b32 v246, s61, 8, v151
	v_lshlrev_b32_e32 v245, 13, v245
	v_lshl_add_u32 v245, v246, 1, v245
	global_load_dwordx4 v[146:149], v245, s[16:17]
	global_load_dwordx4 v[156:159], v245, s[16:17] offset:256
	s_add_u32 s26, s16, 0x20000
	s_addc_u32 s27, s17, 0
	global_load_dwordx4 v[160:163], v245, s[26:27]
	global_load_dwordx4 v[164:167], v245, s[26:27] offset:256
	s_add_u32 s26, s16, 0x40000
	s_addc_u32 s27, s17, 0
	global_load_dwordx4 v[168:171], v245, s[26:27]
	global_load_dwordx4 v[172:175], v245, s[26:27] offset:256
	s_add_u32 s26, s16, 0x60000
	s_addc_u32 s27, s17, 0
	global_load_dwordx4 v[176:179], v245, s[26:27]
	global_load_dwordx4 v[180:183], v245, s[26:27] offset:256
	s_add_u32 s26, s16, 0x100000
	s_addc_u32 s27, s17, 0
	global_load_dwordx4 v[184:187], v245, s[26:27]
	global_load_dwordx4 v[188:191], v245, s[26:27] offset:256
	s_add_u32 s26, s16, 0x120000
	s_addc_u32 s27, s17, 0
	global_load_dwordx4 v[192:195], v245, s[26:27]
	global_load_dwordx4 v[196:199], v245, s[26:27] offset:256
	s_add_u32 s26, s16, 0x140000
	s_addc_u32 s27, s17, 0
	global_load_dwordx4 v[200:203], v245, s[26:27]
	global_load_dwordx4 v[204:207], v245, s[26:27] offset:256
	s_add_u32 s26, s16, 0x160000
	s_addc_u32 s27, s17, 0
	global_load_dwordx4 v[208:211], v245, s[26:27]
	global_load_dwordx4 v[212:215], v245, s[26:27] offset:256
	s_and_b64 vcc, exec, s[22:23]
	s_cbranch_vccz .LBB0_2251
	s_barrier
